# hand-written up_ffn 256-tile epilogue: g tile staged in LDS by swizzled LDS-DMA, w_conv loaded once per tile, v_rcp_f32 silu, pipelined ds_reads
# speedup vs baseline: 1.1269x; 1.0610x over previous
.LBB0_28:
	v_readlane_b32 s0, v253, 57
	v_readlane_b32 s1, v253, 58
	s_andn2_b64 vcc, exec, s[0:1]
	s_cbranch_vccnz .LBB0_69
	v_readlane_b32 s0, v254, 53
	v_readlane_b32 s1, v254, 54
	s_and_b64 s[0:1], s[0:1], exec
	v_readlane_b32 s36, v252, 49
	s_cselect_b32 s0, 0x10800, 0
	v_readlane_b32 s48, v252, 61
	v_readlane_b32 s49, v252, 62
	s_add_u32 s8, s48, s0
	s_addc_u32 s9, s49, 0
	v_readlane_b32 s76, v252, 0
	v_readlane_b32 s37, v252, 50
	v_readlane_b32 s38, v252, 51
	v_readlane_b32 s39, v252, 52
	v_readlane_b32 s40, v252, 53
	v_readlane_b32 s41, v252, 54
	v_readlane_b32 s42, v252, 55
	v_readlane_b32 s43, v252, 56
	v_readlane_b32 s44, v252, 57
	v_readlane_b32 s45, v252, 58
	v_readlane_b32 s46, v252, 59
	v_readlane_b32 s47, v252, 60
	v_readlane_b32 s50, v252, 63
	v_readlane_b32 s51, v253, 0
	s_branch .LBB0_31
.LBB0_31:
	s_ashr_i32 s0, s76, 31
	s_lshr_b32 s0, s0, 29
	s_add_i32 s0, s76, s0
	s_ashr_i32 s1, s0, 3
	s_and_b32 s0, s0, -8
	s_sub_i32 s0, s76, s0
	s_lshr_b32 s4, s0, 31
	s_or_b32 s4, s4, 0x84
	s_mul_i32 s56, s4, s0
	s_add_i32 s56, s56, s1
	s_mul_hi_i32 s0, s56, 0x2aaaaaab
	s_lshr_b32 s1, s0, 31
	s_ashr_i32 s57, s0, 5
	s_add_i32 s57, s57, s1
	s_lshl_b32 s4, s57, 2
	s_sub_i32 s0, 22, s4
	s_min_u32 s5, s0, 4
	s_mul_i32 s62, s57, 0xc0
	s_sub_i32 s10, s56, s62
	v_cvt_f32_ubyte0_e32 v2, s5
	v_cvt_f32_i32_e32 v0, s10
	v_rcp_iflag_f32_e32 v3, v2
	s_ashr_i32 s0, s10, 30
	v_mov_b32_e32 v142, v206
	v_mul_f32_e32 v3, v0, v3
	v_trunc_f32_e32 v3, v3
	v_fma_f32 v0, -v3, v2, v0
	s_barrier
	s_or_b32 s11, s0, 1
	v_cmp_ge_f32_e64 s[0:1], |v0|, v2
	v_cvt_i32_f32_e32 v3, v3
	v_ashrrev_i32_e32 v0, 31, v142
	v_lshrrev_b32_e32 v0, 26, v0
	v_add_u32_e32 v0, v142, v0
	v_ashrrev_i32_e32 v4, 6, v0
	v_bfe_i32 v0, v142, 27, 1
	v_lshlrev_b32_e32 v147, 4, v142
	v_lshrrev_b32_e32 v0, 22, v0
	v_add_u32_e32 v0, v147, v0
	v_and_b32_e32 v0, 0xfffffc00, v0
	v_sub_u32_e32 v0, v147, v0
	v_lshrrev_b32_e32 v2, 4, v0
	v_bitop3_b32 v2, v2, v0, 32 bitop3:0x6c
	v_ashrrev_i32_e32 v0, 31, v0
	v_lshrrev_b32_e32 v0, 26, v0
	v_add_u32_e32 v0, v2, v0
	v_ashrrev_i32_e32 v5, 6, v0
	v_mul_i32_i24_e32 v6, 64, v5
	s_and_b64 s[0:1], s[0:1], exec
	v_sub_u32_e32 v2, v2, v6
	v_readfirstlane_b32 s1, v3
	v_lshlrev_b32_e32 v3, 3, v4
	v_lshlrev_b32_e32 v0, 5, v4
	v_ashrrev_i16_sdwa v2, v207, sext(v2) dst_sel:DWORD dst_unused:UNUSED_PAD src0_sel:DWORD src1_sel:BYTE_0
	v_and_b32_e32 v3, 0xffff0, v3
	v_and_b32_e32 v0, 32, v0
	v_bfe_i32 v7, v2, 0, 16
	v_add_u32_e32 v0, v0, v7
	v_add_lshl_u32 v2, v5, v3, 12
	v_add_u32_e32 v148, 0x2000, v147
	s_cselect_b32 s0, s11, 0
	v_lshl_add_u32 v0, v0, 1, v2
	v_ashrrev_i32_e32 v2, 31, v148
	s_add_i32 s63, s1, s0
	v_lshrrev_b32_e32 v2, 22, v2
	s_sext_i32_i16 s0, s63
	s_mul_i32 s63, s63, s5
	v_add_u32_e32 v2, v148, v2
	s_sub_i32 s1, s10, s63
	v_ashrrev_i32_e32 v6, 10, v2
	s_sext_i32_i16 s1, s1
	v_mul_i32_i24_e32 v2, 0x400, v6
	s_add_i32 s4, s4, s1
	v_sub_u32_e32 v2, v148, v2
	s_lshl_b32 s4, s4, 8
	v_lshrrev_b32_e32 v3, 4, v2
	v_bitop3_b32 v2, v3, v2, 32 bitop3:0x6c
	s_ashr_i32 s5, s4, 31
	s_lshl_b32 s10, s0, 8
	v_ashrrev_i32_e32 v8, 31, v2
	s_lshl_b64 s[0:1], s[4:5], 12
	v_lshrrev_b32_e32 v8, 26, v8
	s_add_u32 s0, s6, s0
	v_add_u32_e32 v9, v2, v8
	s_addc_u32 s1, s7, s1
	s_ashr_i32 s11, s10, 31
	v_ashrrev_i32_e32 v8, 6, v9
	v_and_b32_e32 v9, 0xc0, v9
	s_lshl_b64 s[12:13], s[10:11], 12
	v_sub_u32_e32 v2, v2, v9
	s_add_u32 s14, s88, s12
	v_lshlrev_b32_e32 v3, 3, v6
	v_lshlrev_b32_e32 v10, 5, v6
	v_ashrrev_i16_sdwa v2, v207, sext(v2) dst_sel:DWORD dst_unused:UNUSED_PAD src0_sel:DWORD src1_sel:BYTE_0
	v_add_u32_e32 v149, 0x10000, v147
	s_addc_u32 s15, s89, s13
	s_or_b32 s16, s4, 0x80
	v_and_b32_e32 v3, 0xffff0, v3
	v_and_b32_e32 v10, 32, v10
	v_bfe_i32 v9, v2, 0, 16
	v_readfirstlane_b32 s5, v149
	v_add_u32_e32 v150, 0x12000, v147
	s_ashr_i32 s17, s16, 31
	v_add_u32_e32 v2, v10, v9
	v_add_lshl_u32 v3, v8, v3, 12
	s_mov_b32 m0, s5
	v_readfirstlane_b32 s5, v150
	s_lshl_b64 s[16:17], s[16:17], 12
	v_lshl_add_u32 v2, v2, 1, v3
	global_load_lds_dwordx4 v0, s[0:1]
	s_mov_b32 m0, s5
	v_readfirstlane_b32 s5, v147
	s_add_u32 s16, s6, s16
	global_load_lds_dwordx4 v2, s[0:1]
	s_mov_b32 m0, s5
	v_readfirstlane_b32 s5, v148
	s_addc_u32 s17, s7, s17
	v_add_u32_e32 v152, 0x14000, v147
	s_or_b32 s52, s10, 0x80
	global_load_lds_dwordx4 v0, s[14:15]
	s_mov_b32 m0, s5
	v_readfirstlane_b32 s5, v152
	v_add_u32_e32 v153, 0x16000, v147
	s_ashr_i32 s53, s52, 31
	global_load_lds_dwordx4 v2, s[14:15]
	s_mov_b32 m0, s5
	v_readfirstlane_b32 s5, v153
	s_lshl_b64 s[52:53], s[52:53], 12
	v_add_u32_e32 v154, 0x4000, v147
	global_load_lds_dwordx4 v0, s[16:17]
	s_mov_b32 m0, s5
	s_add_u32 s72, s88, s52
	v_readfirstlane_b32 s5, v154
	v_add_u32_e32 v155, 0x6000, v147
	global_load_lds_dwordx4 v2, s[16:17]
	s_addc_u32 s73, s89, s53
	s_mov_b32 m0, s5
	v_readfirstlane_b32 s5, v155
	global_load_lds_dwordx4 v0, s[72:73]
	s_mov_b32 m0, s5
	v_ashrrev_i32_e32 v143, 8, v142
	global_load_lds_dwordx4 v2, s[72:73]
	v_cmp_eq_u32_e32 vcc, 1, v143
	s_and_saveexec_b64 s[52:53], vcc
	s_cbranch_execz .LBB0_33
	s_barrier
.LBB0_33:
	s_or_b64 exec, exec, s[52:53]
	v_mov_b32_e32 v3, v1
	v_lshl_add_u64 v[12:13], s[0:1], 0, v[2:3]
	s_waitcnt vmcnt(8)
	v_lshl_add_u64 v[16:17], s[14:15], 0, v[2:3]
	v_lshl_add_u64 v[20:21], s[16:17], 0, v[2:3]
	v_lshl_add_u64 v[130:131], s[72:73], 0, v[2:3]
	v_and_b32_e32 v146, 15, v142
	v_bfe_u32 v145, v142, 4, 2
	v_lshlrev_b32_e32 v3, 2, v142
	v_add_u32_e32 v156, 0x18000, v147
	v_lshl_add_u64 v[10:11], s[0:1], 0, v[0:1]
	v_lshl_add_u64 v[14:15], s[14:15], 0, v[0:1]
	v_lshl_add_u64 v[18:19], s[16:17], 0, v[0:1]
	v_lshl_add_u64 v[132:133], s[72:73], 0, v[0:1]
	v_lshlrev_b32_e32 v0, 6, v146
	v_lshlrev_b32_e32 v2, 4, v145
	v_and_b32_e32 v3, 32, v3
	s_mov_b64 s[14:15], 0x80
	v_readfirstlane_b32 s0, v156
	v_add_u32_e32 v157, 0x1a000, v147
	v_bitop3_b32 v22, v2, v3, v0 bitop3:0x36
	v_lshl_add_u64 v[2:3], v[10:11], 0, s[14:15]
	s_mov_b32 m0, s0
	v_readfirstlane_b32 s0, v157
	v_add_u32_e32 v158, 0x8000, v147
	s_waitcnt vmcnt(4)
	s_barrier
	global_load_lds_dwordx4 v[2:3], off
	v_lshl_add_u64 v[2:3], v[12:13], 0, s[14:15]
	s_mov_b32 m0, s0
	v_readfirstlane_b32 s0, v158
	v_add_u32_e32 v159, 0xa000, v147
	global_load_lds_dwordx4 v[2:3], off
	v_lshl_add_u64 v[2:3], v[14:15], 0, s[14:15]
	s_mov_b32 m0, s0
	v_readfirstlane_b32 s0, v159
	v_add_u32_e32 v160, 0x1c000, v147
	global_load_lds_dwordx4 v[2:3], off
	v_lshl_add_u64 v[2:3], v[16:17], 0, s[14:15]
	s_mov_b32 m0, s0
	v_readfirstlane_b32 s0, v160
	v_add_u32_e32 v161, 0x1e000, v147
	global_load_lds_dwordx4 v[2:3], off
	v_lshl_add_u64 v[2:3], v[18:19], 0, s[14:15]
	s_mov_b32 m0, s0
	v_readfirstlane_b32 s0, v161
	global_load_lds_dwordx4 v[2:3], off
	v_lshl_add_u64 v[2:3], v[20:21], 0, s[14:15]
	s_mov_b32 m0, s0
	s_sub_i32 s1, s56, s63
	global_load_lds_dwordx4 v[2:3], off
	s_sub_i32 s1, s1, s62
	v_lshlrev_b32_e32 v0, 15, v4
	s_sext_i32_i16 s1, s1
	v_and_b32_e32 v0, 0xffff0000, v0
	s_lshl_b32 s0, s57, 10
	s_lshl_b32 s1, s1, 8
	v_lshl_add_u32 v0, v5, 12, v0
	v_and_b32_e32 v2, 1, v4
	s_add_i32 s0, s0, s1
	v_lshl_or_b32 v0, v2, 6, v0
	v_lshlrev_b32_e32 v2, 15, v6
	s_ashr_i32 s1, s0, 31
	v_and_b32_e32 v2, 0xffff0000, v2
	s_lshl_b64 s[0:1], s[0:1], 12
	v_lshl_add_u32 v2, v8, 12, v2
	v_and_b32_e32 v3, 1, v6
	s_add_u32 s0, s6, s0
	v_lshl_or_b32 v2, v3, 6, v2
	v_lshl_add_u32 v0, v7, 1, v0
	s_addc_u32 s1, s7, s1
	v_lshl_add_u32 v2, v9, 1, v2
	v_mov_b32_e32 v3, v1
	v_lshl_add_u64 v[134:135], s[0:1], 0, v[0:1]
	v_lshl_add_u64 v[136:137], s[0:1], 0, v[2:3]
	s_add_u32 s0, s88, s12
	v_bfe_u32 v144, v142, 6, 2
	s_waitcnt vmcnt(6)
	s_addc_u32 s1, s89, s13
	v_lshlrev_b32_e32 v23, 13, v143
	v_lshl_or_b32 v24, v144, 12, v212
	v_lshl_add_u64 v[140:141], s[0:1], 0, v[2:3]
	v_mov_b32_e32 v2, 0
	v_lshl_add_u64 v[138:139], s[0:1], 0, v[0:1]
	s_mov_b32 s0, -2
	s_mov_b64 s[12:13], 0
	v_add_u32_e32 v151, v24, v22
	v_add_u32_e32 v0, v23, v22
	v_mov_b32_e32 v3, v2
	v_mov_b32_e32 v4, v2
	v_mov_b32_e32 v5, v2
	v_mov_b32_e32 v6, v2
	v_mov_b32_e32 v7, v2
	v_mov_b32_e32 v8, v2
	v_mov_b32_e32 v9, v2
	v_mov_b32_e32 v10, v2
	v_mov_b32_e32 v11, v2
	v_mov_b32_e32 v12, v2
	v_mov_b32_e32 v13, v2
	v_mov_b32_e32 v14, v2
	v_mov_b32_e32 v15, v2
	v_mov_b32_e32 v16, v2
	v_mov_b32_e32 v17, v2
	v_mov_b32_e32 v18, v2
	v_mov_b32_e32 v19, v2
	v_mov_b32_e32 v20, v2
	v_mov_b32_e32 v21, v2
	v_mov_b32_e32 v22, v2
	v_mov_b32_e32 v23, v2
	v_mov_b32_e32 v24, v2
	v_mov_b32_e32 v25, v2
	v_mov_b32_e32 v26, v2
	v_mov_b32_e32 v27, v2
	v_mov_b32_e32 v28, v2
	v_mov_b32_e32 v29, v2
	v_mov_b32_e32 v30, v2
	v_mov_b32_e32 v31, v2
	v_mov_b32_e32 v32, v2
	v_mov_b32_e32 v33, v2
	v_mov_b32_e32 v34, v2
	v_mov_b32_e32 v35, v2
	v_mov_b32_e32 v36, v2
	v_mov_b32_e32 v37, v2
	v_mov_b32_e32 v38, v2
	v_mov_b32_e32 v39, v2
	v_mov_b32_e32 v40, v2
	v_mov_b32_e32 v41, v2
	v_mov_b32_e32 v42, v2
	v_mov_b32_e32 v43, v2
	v_mov_b32_e32 v44, v2
	v_mov_b32_e32 v45, v2
	v_mov_b32_e32 v46, v2
	v_mov_b32_e32 v47, v2
	v_mov_b32_e32 v48, v2
	v_mov_b32_e32 v49, v2
	v_mov_b32_e32 v50, v2
	v_mov_b32_e32 v51, v2
	v_mov_b32_e32 v52, v2
	v_mov_b32_e32 v53, v2
	v_mov_b32_e32 v54, v2
	v_mov_b32_e32 v55, v2
	v_mov_b32_e32 v56, v2
	v_mov_b32_e32 v57, v2
	v_mov_b32_e32 v58, v2
	v_mov_b32_e32 v59, v2
	v_mov_b32_e32 v60, v2
	v_mov_b32_e32 v61, v2
	v_mov_b32_e32 v62, v2
	v_mov_b32_e32 v63, v2
	v_mov_b32_e32 v64, v2
	v_mov_b32_e32 v65, v2
	v_mov_b32_e32 v70, v2
	v_mov_b32_e32 v71, v2
	v_mov_b32_e32 v72, v2
	v_mov_b32_e32 v73, v2
	v_mov_b32_e32 v86, v2
	v_mov_b32_e32 v87, v2
	v_mov_b32_e32 v88, v2
	v_mov_b32_e32 v89, v2
	v_mov_b32_e32 v90, v2
	v_mov_b32_e32 v91, v2
	v_mov_b32_e32 v92, v2
	v_mov_b32_e32 v93, v2
	v_mov_b32_e32 v94, v2
	v_mov_b32_e32 v95, v2
	v_mov_b32_e32 v96, v2
	v_mov_b32_e32 v97, v2
	v_mov_b32_e32 v98, v2
	v_mov_b32_e32 v99, v2
	v_mov_b32_e32 v100, v2
	v_mov_b32_e32 v101, v2
	v_mov_b32_e32 v102, v2
	v_mov_b32_e32 v103, v2
	v_mov_b32_e32 v104, v2
	v_mov_b32_e32 v105, v2
	v_mov_b32_e32 v106, v2
	v_mov_b32_e32 v107, v2
	v_mov_b32_e32 v108, v2
	v_mov_b32_e32 v109, v2
	v_mov_b32_e32 v110, v2
	v_mov_b32_e32 v111, v2
	v_mov_b32_e32 v112, v2
	v_mov_b32_e32 v113, v2
	v_mov_b32_e32 v114, v2
	v_mov_b32_e32 v115, v2
	v_mov_b32_e32 v116, v2
	v_mov_b32_e32 v117, v2
	v_mov_b32_e32 v118, v2
	v_mov_b32_e32 v119, v2
	v_mov_b32_e32 v120, v2
	v_mov_b32_e32 v121, v2
	v_mov_b32_e32 v122, v2
	v_mov_b32_e32 v123, v2
	v_mov_b32_e32 v124, v2
	v_mov_b32_e32 v125, v2
	v_mov_b32_e32 v126, v2
	v_mov_b32_e32 v127, v2
	v_mov_b32_e32 v128, v2
	v_mov_b32_e32 v129, v2
	v_mov_b32_e32 v66, v2
	v_mov_b32_e32 v67, v2
	v_mov_b32_e32 v68, v2
	v_mov_b32_e32 v69, v2
	v_mov_b32_e32 v74, v2
	v_mov_b32_e32 v75, v2
	v_mov_b32_e32 v76, v2
	v_mov_b32_e32 v77, v2
	v_mov_b32_e32 v78, v2
	v_mov_b32_e32 v79, v2
	v_mov_b32_e32 v80, v2
	v_mov_b32_e32 v81, v2
	v_mov_b32_e32 v82, v2
	v_mov_b32_e32 v83, v2
	v_mov_b32_e32 v84, v2
	v_mov_b32_e32 v85, v2
	s_barrier
.LBB0_34:
	ds_read_b128 v[164:167], v151
	ds_read_b128 v[168:171], v151 offset:1024
	ds_read_b128 v[172:175], v151 offset:2048
	ds_read_b128 v[176:179], v151 offset:3072
	v_add_u32_e32 v162, 0xc000, v147
	v_lshl_add_u64 v[204:205], v[138:139], 0, s[12:13]
	v_readfirstlane_b32 s1, v162
	v_lshl_add_u64 v[210:211], v[204:205], 0, s[60:61]
	s_mov_b32 m0, s1
	v_add_u32_e32 v163, 0xe000, v147
	ds_read_b128 v[180:183], v0
	ds_read_b128 v[184:187], v0 offset:1024
	ds_read_b128 v[188:191], v0 offset:2048
	ds_read_b128 v[192:195], v0 offset:3072
	ds_read_b128 v[196:199], v0 offset:4096
	ds_read_b128 v[200:203], v0 offset:5120
	ds_read_b128 v[222:225], v0 offset:6144
	ds_read_b128 v[232:235], v0 offset:7168
	global_load_lds_dwordx4 v[210:211], off
	v_lshl_add_u64 v[210:211], v[140:141], 0, s[12:13]
	v_readfirstlane_b32 s1, v163
	v_lshl_add_u64 v[216:217], v[210:211], 0, s[60:61]
	s_mov_b32 m0, s1
	s_nop 0
	global_load_lds_dwordx4 v[216:217], off
	s_waitcnt lgkmcnt(8)
	s_barrier
	s_waitcnt lgkmcnt(0)
	s_setprio 1
	s_waitcnt lgkmcnt(0)
	v_mfma_f32_16x16x32_bf16 v[126:129], v[164:167], v[180:183], v[126:129]
	v_mfma_f32_16x16x32_bf16 v[122:125], v[172:175], v[180:183], v[122:125]
	v_mfma_f32_16x16x32_bf16 v[118:121], v[164:167], v[188:191], v[118:121]
	v_mfma_f32_16x16x32_bf16 v[114:117], v[172:175], v[188:191], v[114:117]
	v_mfma_f32_16x16x32_bf16 v[110:113], v[164:167], v[196:199], v[110:113]
	v_mfma_f32_16x16x32_bf16 v[106:109], v[172:175], v[196:199], v[106:109]
	v_mfma_f32_16x16x32_bf16 v[102:105], v[164:167], v[222:225], v[102:105]
	v_mfma_f32_16x16x32_bf16 v[98:101], v[172:175], v[222:225], v[98:101]
	v_mfma_f32_16x16x32_bf16 v[126:129], v[168:171], v[184:187], v[126:129]
	v_mfma_f32_16x16x32_bf16 v[122:125], v[176:179], v[184:187], v[122:125]
	v_mfma_f32_16x16x32_bf16 v[118:121], v[168:171], v[192:195], v[118:121]
	v_mfma_f32_16x16x32_bf16 v[114:117], v[176:179], v[192:195], v[114:117]
	v_mfma_f32_16x16x32_bf16 v[110:113], v[168:171], v[200:203], v[110:113]
	v_mfma_f32_16x16x32_bf16 v[106:109], v[176:179], v[200:203], v[106:109]
	v_mfma_f32_16x16x32_bf16 v[102:105], v[168:171], v[232:235], v[102:105]
	v_mfma_f32_16x16x32_bf16 v[98:101], v[176:179], v[232:235], v[98:101]
	s_setprio 0
	s_barrier
	v_lshl_add_u64 v[216:217], v[134:135], 0, s[12:13]
	v_readfirstlane_b32 s1, v149
	v_lshl_add_u64 v[218:219], v[216:217], 0, s[74:75]
	s_mov_b32 m0, s1
	ds_read_b128 v[236:239], v151 offset:16384
	ds_read_b128 v[240:243], v151 offset:17408
	ds_read_b128 v[244:247], v151 offset:18432
	ds_read_b128 v[248:251], v151 offset:19456
	global_load_lds_dwordx4 v[218:219], off
	v_lshl_add_u64 v[218:219], v[136:137], 0, s[12:13]
	v_readfirstlane_b32 s1, v150
	v_lshl_add_u64 v[228:229], v[218:219], 0, s[74:75]
	s_mov_b32 m0, s1
	s_nop 0
	global_load_lds_dwordx4 v[228:229], off
	s_barrier
	s_waitcnt lgkmcnt(0)
	s_setprio 1
	s_waitcnt lgkmcnt(0)
	v_mfma_f32_16x16x32_bf16 v[94:97], v[236:239], v[180:183], v[94:97]
	v_mfma_f32_16x16x32_bf16 v[90:93], v[244:247], v[180:183], v[90:93]
	v_mfma_f32_16x16x32_bf16 v[86:89], v[236:239], v[188:191], v[86:89]
	v_mfma_f32_16x16x32_bf16 v[70:73], v[244:247], v[188:191], v[70:73]
	v_mfma_f32_16x16x32_bf16 v[62:65], v[236:239], v[196:199], v[62:65]
	v_mfma_f32_16x16x32_bf16 v[58:61], v[244:247], v[196:199], v[58:61]
	v_mfma_f32_16x16x32_bf16 v[54:57], v[236:239], v[222:225], v[54:57]
	v_mfma_f32_16x16x32_bf16 v[50:53], v[244:247], v[222:225], v[50:53]
	v_mfma_f32_16x16x32_bf16 v[94:97], v[240:243], v[184:187], v[94:97]
	v_mfma_f32_16x16x32_bf16 v[90:93], v[248:251], v[184:187], v[90:93]
	v_mfma_f32_16x16x32_bf16 v[86:89], v[240:243], v[192:195], v[86:89]
	v_mfma_f32_16x16x32_bf16 v[70:73], v[248:251], v[192:195], v[70:73]
	v_mfma_f32_16x16x32_bf16 v[62:65], v[240:243], v[200:203], v[62:65]
	v_mfma_f32_16x16x32_bf16 v[58:61], v[248:251], v[200:203], v[58:61]
	v_mfma_f32_16x16x32_bf16 v[54:57], v[240:243], v[232:235], v[54:57]
	v_mfma_f32_16x16x32_bf16 v[50:53], v[248:251], v[232:235], v[50:53]
	s_setprio 0
	v_readfirstlane_b32 s1, v147
	v_lshl_add_u64 v[228:229], v[204:205], 0, s[74:75]
	s_mov_b32 m0, s1
	v_readfirstlane_b32 s1, v148
	s_barrier
	ds_read_b128 v[180:183], v0 offset:16384
	ds_read_b128 v[184:187], v0 offset:17408
	ds_read_b128 v[188:191], v0 offset:18432
	ds_read_b128 v[192:195], v0 offset:19456
	ds_read_b128 v[196:199], v0 offset:20480
	ds_read_b128 v[200:203], v0 offset:21504
	ds_read_b128 v[222:225], v0 offset:22528
	ds_read_b128 v[232:235], v0 offset:23552
	global_load_lds_dwordx4 v[228:229], off
	v_lshl_add_u64 v[228:229], v[210:211], 0, s[74:75]
	s_mov_b32 m0, s1
	s_nop 0
	global_load_lds_dwordx4 v[228:229], off
	s_barrier
	s_waitcnt lgkmcnt(0)
	s_setprio 1
	s_waitcnt lgkmcnt(0)
	v_mfma_f32_16x16x32_bf16 v[46:49], v[164:167], v[180:183], v[46:49]
	v_mfma_f32_16x16x32_bf16 v[42:45], v[172:175], v[180:183], v[42:45]
	v_mfma_f32_16x16x32_bf16 v[38:41], v[164:167], v[188:191], v[38:41]
	v_mfma_f32_16x16x32_bf16 v[34:37], v[172:175], v[188:191], v[34:37]
	v_mfma_f32_16x16x32_bf16 v[30:33], v[164:167], v[196:199], v[30:33]
	v_mfma_f32_16x16x32_bf16 v[26:29], v[172:175], v[196:199], v[26:29]
	v_mfma_f32_16x16x32_bf16 v[22:25], v[164:167], v[222:225], v[22:25]
	v_mfma_f32_16x16x32_bf16 v[18:21], v[172:175], v[222:225], v[18:21]
	v_mfma_f32_16x16x32_bf16 v[46:49], v[168:171], v[184:187], v[46:49]
	v_mfma_f32_16x16x32_bf16 v[42:45], v[176:179], v[184:187], v[42:45]
	v_mfma_f32_16x16x32_bf16 v[38:41], v[168:171], v[192:195], v[38:41]
	v_mfma_f32_16x16x32_bf16 v[34:37], v[176:179], v[192:195], v[34:37]
	v_mfma_f32_16x16x32_bf16 v[30:33], v[168:171], v[200:203], v[30:33]
	v_mfma_f32_16x16x32_bf16 v[26:29], v[176:179], v[200:203], v[26:29]
	v_mfma_f32_16x16x32_bf16 v[22:25], v[168:171], v[232:235], v[22:25]
	v_mfma_f32_16x16x32_bf16 v[18:21], v[176:179], v[232:235], v[18:21]
	s_setprio 0
	s_barrier
	v_readfirstlane_b32 s1, v152
	v_lshl_add_u64 v[164:165], v[216:217], 0, s[18:19]
	s_mov_b32 m0, s1
	v_readfirstlane_b32 s1, v153
	global_load_lds_dwordx4 v[164:165], off
	v_lshl_add_u64 v[164:165], v[218:219], 0, s[18:19]
	s_mov_b32 m0, s1
	s_nop 0
	global_load_lds_dwordx4 v[164:165], off
	s_waitcnt vmcnt(6)
	s_barrier
	s_setprio 1
	v_mfma_f32_16x16x32_bf16 v[14:17], v[236:239], v[180:183], v[14:17]
	v_mfma_f32_16x16x32_bf16 v[10:13], v[244:247], v[180:183], v[10:13]
	v_mfma_f32_16x16x32_bf16 v[6:9], v[236:239], v[188:191], v[6:9]
	v_mfma_f32_16x16x32_bf16 v[2:5], v[244:247], v[188:191], v[2:5]
	v_mfma_f32_16x16x32_bf16 v[66:69], v[236:239], v[196:199], v[66:69]
	v_mfma_f32_16x16x32_bf16 v[74:77], v[244:247], v[196:199], v[74:77]
	v_mfma_f32_16x16x32_bf16 v[78:81], v[236:239], v[222:225], v[78:81]
	v_mfma_f32_16x16x32_bf16 v[82:85], v[244:247], v[222:225], v[82:85]
	v_mfma_f32_16x16x32_bf16 v[14:17], v[240:243], v[184:187], v[14:17]
	v_mfma_f32_16x16x32_bf16 v[10:13], v[248:251], v[184:187], v[10:13]
	v_mfma_f32_16x16x32_bf16 v[6:9], v[240:243], v[192:195], v[6:9]
	v_mfma_f32_16x16x32_bf16 v[2:5], v[248:251], v[192:195], v[2:5]
	v_mfma_f32_16x16x32_bf16 v[66:69], v[240:243], v[200:203], v[66:69]
	v_mfma_f32_16x16x32_bf16 v[74:77], v[248:251], v[200:203], v[74:77]
	v_mfma_f32_16x16x32_bf16 v[78:81], v[240:243], v[232:235], v[78:81]
	v_mfma_f32_16x16x32_bf16 v[82:85], v[248:251], v[232:235], v[82:85]
	s_setprio 0
	s_barrier
	ds_read_b128 v[164:167], v151 offset:32768
	ds_read_b128 v[168:171], v151 offset:33792
	ds_read_b128 v[172:175], v151 offset:34816
	ds_read_b128 v[176:179], v151 offset:35840
	v_readfirstlane_b32 s1, v154
	v_lshl_add_u64 v[228:229], v[204:205], 0, s[18:19]
	s_mov_b32 m0, s1
	v_readfirstlane_b32 s1, v155
	ds_read_b128 v[180:183], v0 offset:32768
	ds_read_b128 v[184:187], v0 offset:33792
	ds_read_b128 v[188:191], v0 offset:34816
	ds_read_b128 v[192:195], v0 offset:35840
	ds_read_b128 v[196:199], v0 offset:36864
	ds_read_b128 v[200:203], v0 offset:37888
	ds_read_b128 v[222:225], v0 offset:38912
	ds_read_b128 v[232:235], v0 offset:39936
	global_load_lds_dwordx4 v[228:229], off
	v_lshl_add_u64 v[228:229], v[210:211], 0, s[18:19]
	s_mov_b32 m0, s1
	s_nop 0
	global_load_lds_dwordx4 v[228:229], off
	s_waitcnt lgkmcnt(8)
	s_barrier
	s_waitcnt lgkmcnt(0)
	s_setprio 1
	s_waitcnt lgkmcnt(0)
	v_mfma_f32_16x16x32_bf16 v[126:129], v[164:167], v[180:183], v[126:129]
	v_mfma_f32_16x16x32_bf16 v[122:125], v[172:175], v[180:183], v[122:125]
	v_mfma_f32_16x16x32_bf16 v[118:121], v[164:167], v[188:191], v[118:121]
	v_mfma_f32_16x16x32_bf16 v[114:117], v[172:175], v[188:191], v[114:117]
	v_mfma_f32_16x16x32_bf16 v[110:113], v[164:167], v[196:199], v[110:113]
	v_mfma_f32_16x16x32_bf16 v[106:109], v[172:175], v[196:199], v[106:109]
	v_mfma_f32_16x16x32_bf16 v[102:105], v[164:167], v[222:225], v[102:105]
	v_mfma_f32_16x16x32_bf16 v[98:101], v[172:175], v[222:225], v[98:101]
	v_mfma_f32_16x16x32_bf16 v[126:129], v[168:171], v[184:187], v[126:129]
	v_mfma_f32_16x16x32_bf16 v[122:125], v[176:179], v[184:187], v[122:125]
	v_mfma_f32_16x16x32_bf16 v[118:121], v[168:171], v[192:195], v[118:121]
	v_mfma_f32_16x16x32_bf16 v[114:117], v[176:179], v[192:195], v[114:117]
	v_mfma_f32_16x16x32_bf16 v[110:113], v[168:171], v[200:203], v[110:113]
	v_mfma_f32_16x16x32_bf16 v[106:109], v[176:179], v[200:203], v[106:109]
	v_mfma_f32_16x16x32_bf16 v[102:105], v[168:171], v[232:235], v[102:105]
	v_mfma_f32_16x16x32_bf16 v[98:101], v[176:179], v[232:235], v[98:101]
	s_setprio 0
	s_barrier
	v_readfirstlane_b32 s1, v156
	v_lshl_add_u64 v[228:229], v[216:217], 0, s[28:29]
	s_mov_b32 m0, s1
	v_readfirstlane_b32 s1, v157
	ds_read_b128 v[236:239], v151 offset:49152
	ds_read_b128 v[240:243], v151 offset:50176
	ds_read_b128 v[244:247], v151 offset:51200
	ds_read_b128 v[248:251], v151 offset:52224
	global_load_lds_dwordx4 v[228:229], off
	v_lshl_add_u64 v[228:229], v[218:219], 0, s[28:29]
	s_mov_b32 m0, s1
	s_nop 0
	global_load_lds_dwordx4 v[228:229], off
	s_barrier
	s_waitcnt lgkmcnt(0)
	s_setprio 1
	s_waitcnt lgkmcnt(0)
	v_mfma_f32_16x16x32_bf16 v[94:97], v[236:239], v[180:183], v[94:97]
	v_mfma_f32_16x16x32_bf16 v[90:93], v[244:247], v[180:183], v[90:93]
	v_mfma_f32_16x16x32_bf16 v[86:89], v[236:239], v[188:191], v[86:89]
	v_mfma_f32_16x16x32_bf16 v[70:73], v[244:247], v[188:191], v[70:73]
	v_mfma_f32_16x16x32_bf16 v[62:65], v[236:239], v[196:199], v[62:65]
	v_mfma_f32_16x16x32_bf16 v[58:61], v[244:247], v[196:199], v[58:61]
	v_mfma_f32_16x16x32_bf16 v[54:57], v[236:239], v[222:225], v[54:57]
	v_mfma_f32_16x16x32_bf16 v[50:53], v[244:247], v[222:225], v[50:53]
	v_mfma_f32_16x16x32_bf16 v[94:97], v[240:243], v[184:187], v[94:97]
	v_mfma_f32_16x16x32_bf16 v[90:93], v[248:251], v[184:187], v[90:93]
	v_mfma_f32_16x16x32_bf16 v[86:89], v[240:243], v[192:195], v[86:89]
	v_mfma_f32_16x16x32_bf16 v[70:73], v[248:251], v[192:195], v[70:73]
	v_mfma_f32_16x16x32_bf16 v[62:65], v[240:243], v[200:203], v[62:65]
	v_mfma_f32_16x16x32_bf16 v[58:61], v[248:251], v[200:203], v[58:61]
	v_mfma_f32_16x16x32_bf16 v[54:57], v[240:243], v[232:235], v[54:57]
	v_mfma_f32_16x16x32_bf16 v[50:53], v[248:251], v[232:235], v[50:53]
	s_setprio 0
	v_readfirstlane_b32 s1, v158
	v_lshl_add_u64 v[204:205], v[204:205], 0, s[28:29]
	s_mov_b32 m0, s1
	v_readfirstlane_b32 s1, v159
	s_barrier
	ds_read_b128 v[180:183], v0 offset:49152
	ds_read_b128 v[184:187], v0 offset:50176
	ds_read_b128 v[188:191], v0 offset:51200
	ds_read_b128 v[192:195], v0 offset:52224
	ds_read_b128 v[196:199], v0 offset:53248
	ds_read_b128 v[200:203], v0 offset:54272
	ds_read_b128 v[222:225], v0 offset:55296
	ds_read_b128 v[232:235], v0 offset:56320
	global_load_lds_dwordx4 v[204:205], off
	v_lshl_add_u64 v[204:205], v[210:211], 0, s[28:29]
	s_mov_b32 m0, s1
	s_nop 0
	global_load_lds_dwordx4 v[204:205], off
	s_barrier
	s_waitcnt lgkmcnt(0)
	s_setprio 1
	s_waitcnt lgkmcnt(0)
	v_mfma_f32_16x16x32_bf16 v[46:49], v[164:167], v[180:183], v[46:49]
	v_mfma_f32_16x16x32_bf16 v[42:45], v[172:175], v[180:183], v[42:45]
	v_mfma_f32_16x16x32_bf16 v[38:41], v[164:167], v[188:191], v[38:41]
	v_mfma_f32_16x16x32_bf16 v[34:37], v[172:175], v[188:191], v[34:37]
	v_mfma_f32_16x16x32_bf16 v[30:33], v[164:167], v[196:199], v[30:33]
	v_mfma_f32_16x16x32_bf16 v[26:29], v[172:175], v[196:199], v[26:29]
	v_mfma_f32_16x16x32_bf16 v[22:25], v[164:167], v[222:225], v[22:25]
	v_mfma_f32_16x16x32_bf16 v[18:21], v[172:175], v[222:225], v[18:21]
	v_mfma_f32_16x16x32_bf16 v[46:49], v[168:171], v[184:187], v[46:49]
	v_mfma_f32_16x16x32_bf16 v[42:45], v[176:179], v[184:187], v[42:45]
	v_mfma_f32_16x16x32_bf16 v[38:41], v[168:171], v[192:195], v[38:41]
	v_mfma_f32_16x16x32_bf16 v[34:37], v[176:179], v[192:195], v[34:37]
	v_mfma_f32_16x16x32_bf16 v[30:33], v[168:171], v[200:203], v[30:33]
	v_mfma_f32_16x16x32_bf16 v[26:29], v[176:179], v[200:203], v[26:29]
	v_mfma_f32_16x16x32_bf16 v[22:25], v[168:171], v[232:235], v[22:25]
	v_mfma_f32_16x16x32_bf16 v[18:21], v[176:179], v[232:235], v[18:21]
	s_setprio 0
	s_barrier
	v_readfirstlane_b32 s1, v160
	v_lshl_add_u64 v[164:165], v[216:217], 0, s[30:31]
	s_mov_b32 m0, s1
	v_readfirstlane_b32 s1, v161
	global_load_lds_dwordx4 v[164:165], off
	v_lshl_add_u64 v[164:165], v[218:219], 0, s[30:31]
	s_mov_b32 m0, s1
	s_nop 0
	global_load_lds_dwordx4 v[164:165], off
	s_waitcnt vmcnt(6)
	s_barrier
	s_setprio 1
	v_mfma_f32_16x16x32_bf16 v[14:17], v[236:239], v[180:183], v[14:17]
	v_mfma_f32_16x16x32_bf16 v[10:13], v[244:247], v[180:183], v[10:13]
	v_mfma_f32_16x16x32_bf16 v[6:9], v[236:239], v[188:191], v[6:9]
	v_mfma_f32_16x16x32_bf16 v[2:5], v[244:247], v[188:191], v[2:5]
	v_mfma_f32_16x16x32_bf16 v[66:69], v[236:239], v[196:199], v[66:69]
	v_mfma_f32_16x16x32_bf16 v[74:77], v[244:247], v[196:199], v[74:77]
	v_mfma_f32_16x16x32_bf16 v[78:81], v[236:239], v[222:225], v[78:81]
	v_mfma_f32_16x16x32_bf16 v[82:85], v[244:247], v[222:225], v[82:85]
	v_mfma_f32_16x16x32_bf16 v[14:17], v[240:243], v[184:187], v[14:17]
	v_mfma_f32_16x16x32_bf16 v[10:13], v[248:251], v[184:187], v[10:13]
	v_mfma_f32_16x16x32_bf16 v[6:9], v[240:243], v[192:195], v[6:9]
	v_mfma_f32_16x16x32_bf16 v[2:5], v[248:251], v[192:195], v[2:5]
	v_mfma_f32_16x16x32_bf16 v[66:69], v[240:243], v[200:203], v[66:69]
	v_mfma_f32_16x16x32_bf16 v[74:77], v[248:251], v[200:203], v[74:77]
	v_mfma_f32_16x16x32_bf16 v[78:81], v[240:243], v[232:235], v[78:81]
	v_mfma_f32_16x16x32_bf16 v[82:85], v[248:251], v[232:235], v[82:85]
	s_setprio 0
	s_add_i32 s0, s0, 2
	s_add_u32 s12, s12, 0x100
	s_addc_u32 s13, s13, 0
	s_cmp_lt_u32 s0, 28
	s_barrier
	s_cbranch_scc1 .LBB0_34
	s_mov_b64 s[12:13], 0xf80
	v_readfirstlane_b32 s0, v162
	v_lshl_add_u64 v[132:133], v[132:133], 0, s[12:13]
	s_mov_b32 m0, s0
	v_readfirstlane_b32 s0, v163
	ds_read_b128 v[134:137], v151
	ds_read_b128 v[138:141], v151 offset:1024
	ds_read_b128 v[152:155], v151 offset:2048
	ds_read_b128 v[156:159], v151 offset:3072
	ds_read_b128 v[164:167], v0
	ds_read_b128 v[168:171], v0 offset:1024
	ds_read_b128 v[172:175], v0 offset:2048
	ds_read_b128 v[176:179], v0 offset:3072
	ds_read_b128 v[180:183], v0 offset:4096
	ds_read_b128 v[184:187], v0 offset:5120
	ds_read_b128 v[188:191], v0 offset:6144
	ds_read_b128 v[192:195], v0 offset:7168
	global_load_lds_dwordx4 v[132:133], off
	v_lshl_add_u64 v[130:131], v[130:131], 0, s[12:13]
	s_mov_b32 m0, s0
	s_nop 0
	global_load_lds_dwordx4 v[130:131], off
	s_barrier
	s_waitcnt lgkmcnt(0)
	s_setprio 1
	s_waitcnt lgkmcnt(0)
	v_mfma_f32_16x16x32_bf16 v[122:125], v[152:155], v[164:167], v[122:125]
	v_mfma_f32_16x16x32_bf16 v[118:121], v[134:137], v[172:175], v[118:121]
	v_mfma_f32_16x16x32_bf16 v[114:117], v[152:155], v[172:175], v[114:117]
	v_mfma_f32_16x16x32_bf16 v[102:105], v[134:137], v[188:191], v[102:105]
	v_mfma_f32_16x16x32_bf16 v[98:101], v[152:155], v[188:191], v[98:101]
	v_mfma_f32_16x16x32_bf16 v[126:129], v[134:137], v[164:167], v[126:129]
	v_mfma_f32_16x16x32_bf16 v[122:125], v[156:159], v[168:171], v[122:125]
	v_mfma_f32_16x16x32_bf16 v[118:121], v[138:141], v[176:179], v[118:121]
	v_mfma_f32_16x16x32_bf16 v[114:117], v[156:159], v[176:179], v[114:117]
	v_mfma_f32_16x16x32_bf16 v[110:113], v[134:137], v[180:183], v[110:113]
	v_mfma_f32_16x16x32_bf16 v[106:109], v[152:155], v[180:183], v[106:109]
	v_mfma_f32_16x16x32_bf16 v[102:105], v[138:141], v[192:195], v[102:105]
	v_mfma_f32_16x16x32_bf16 v[98:101], v[156:159], v[192:195], v[98:101]
	v_mfma_f32_16x16x32_bf16 v[126:129], v[138:141], v[168:171], v[126:129]
	v_mfma_f32_16x16x32_bf16 v[130:133], v[138:141], v[184:187], v[110:113]
	v_mfma_f32_16x16x32_bf16 v[160:163], v[156:159], v[184:187], v[106:109]
	s_setprio 0
	s_barrier
	ds_read_b128 v[106:109], v151 offset:16384
	ds_read_b128 v[110:113], v151 offset:17408
	ds_read_b128 v[196:199], v151 offset:18432
	ds_read_b128 v[200:203], v151 offset:19456
	s_barrier
	s_waitcnt lgkmcnt(0)
	s_setprio 1
	s_waitcnt lgkmcnt(3)
	v_mfma_f32_16x16x32_bf16 v[86:89], v[106:109], v[172:175], v[86:89]
	s_waitcnt lgkmcnt(1)
	v_mfma_f32_16x16x32_bf16 v[70:73], v[196:199], v[172:175], v[70:73]
	v_mfma_f32_16x16x32_bf16 v[62:65], v[106:109], v[180:183], v[62:65]
	v_mfma_f32_16x16x32_bf16 v[58:61], v[196:199], v[180:183], v[58:61]
	v_mfma_f32_16x16x32_bf16 v[54:57], v[106:109], v[188:191], v[54:57]
	v_mfma_f32_16x16x32_bf16 v[50:53], v[196:199], v[188:191], v[50:53]
	v_mfma_f32_16x16x32_bf16 v[94:97], v[106:109], v[164:167], v[94:97]
	v_mfma_f32_16x16x32_bf16 v[90:93], v[196:199], v[164:167], v[90:93]
	v_mfma_f32_16x16x32_bf16 v[86:89], v[110:113], v[176:179], v[86:89]
	s_waitcnt lgkmcnt(0)
	v_mfma_f32_16x16x32_bf16 v[70:73], v[200:203], v[176:179], v[70:73]
	v_mfma_f32_16x16x32_bf16 v[62:65], v[110:113], v[184:187], v[62:65]
	v_mfma_f32_16x16x32_bf16 v[58:61], v[200:203], v[184:187], v[58:61]
	v_mfma_f32_16x16x32_bf16 v[54:57], v[110:113], v[192:195], v[54:57]
	v_mfma_f32_16x16x32_bf16 v[50:53], v[200:203], v[192:195], v[50:53]
	v_mfma_f32_16x16x32_bf16 v[222:225], v[110:113], v[168:171], v[94:97]
	v_mfma_f32_16x16x32_bf16 v[164:167], v[200:203], v[168:171], v[90:93]
	s_setprio 0
	s_barrier
	s_nop 0
	ds_read_b128 v[90:93], v0 offset:16384
	ds_read_b128 v[94:97], v0 offset:17408
	ds_read_b128 v[168:171], v0 offset:18432
	ds_read_b128 v[172:175], v0 offset:19456
	ds_read_b128 v[176:179], v0 offset:20480
	ds_read_b128 v[180:183], v0 offset:21504
	ds_read_b128 v[184:187], v0 offset:22528
	ds_read_b128 v[188:191], v0 offset:23552
	s_waitcnt vmcnt(4)
	s_barrier
	s_waitcnt lgkmcnt(0)
	s_setprio 1
	s_waitcnt lgkmcnt(7)
	v_mfma_f32_16x16x32_bf16 v[46:49], v[134:137], v[90:93], v[46:49]
	v_mfma_f32_16x16x32_bf16 v[42:45], v[152:155], v[90:93], v[42:45]
	s_waitcnt lgkmcnt(5)
	v_mfma_f32_16x16x32_bf16 v[38:41], v[134:137], v[168:171], v[38:41]
	v_mfma_f32_16x16x32_bf16 v[34:37], v[152:155], v[168:171], v[34:37]
	s_waitcnt lgkmcnt(3)
	v_mfma_f32_16x16x32_bf16 v[30:33], v[134:137], v[176:179], v[30:33]
	v_mfma_f32_16x16x32_bf16 v[26:29], v[152:155], v[176:179], v[26:29]
	s_waitcnt lgkmcnt(1)
	v_mfma_f32_16x16x32_bf16 v[22:25], v[134:137], v[184:187], v[22:25]
	v_mfma_f32_16x16x32_bf16 v[18:21], v[152:155], v[184:187], v[18:21]
	v_mfma_f32_16x16x32_bf16 v[46:49], v[138:141], v[94:97], v[46:49]
	v_mfma_f32_16x16x32_bf16 v[42:45], v[156:159], v[94:97], v[42:45]
	v_mfma_f32_16x16x32_bf16 v[38:41], v[138:141], v[172:175], v[38:41]
	v_mfma_f32_16x16x32_bf16 v[34:37], v[156:159], v[172:175], v[34:37]
	v_mfma_f32_16x16x32_bf16 v[30:33], v[138:141], v[180:183], v[30:33]
	v_mfma_f32_16x16x32_bf16 v[26:29], v[156:159], v[180:183], v[26:29]
	s_waitcnt lgkmcnt(0)
	v_mfma_f32_16x16x32_bf16 v[22:25], v[138:141], v[188:191], v[22:25]
	v_mfma_f32_16x16x32_bf16 v[18:21], v[156:159], v[188:191], v[18:21]
	s_setprio 0
	s_setprio 1
	v_mfma_f32_16x16x32_bf16 v[10:13], v[196:199], v[90:93], v[10:13]
	v_mfma_f32_16x16x32_bf16 v[152:155], v[200:203], v[94:97], v[10:13]
	v_mfma_f32_16x16x32_bf16 v[10:13], v[106:109], v[176:179], v[66:69]
	v_mfma_f32_16x16x32_bf16 v[156:159], v[110:113], v[180:183], v[10:13]
	v_mfma_f32_16x16x32_bf16 v[10:13], v[196:199], v[176:179], v[74:77]
	v_mfma_f32_16x16x32_bf16 v[6:9], v[106:109], v[168:171], v[6:9]
	v_mfma_f32_16x16x32_bf16 v[2:5], v[196:199], v[168:171], v[2:5]
	v_mfma_f32_16x16x32_bf16 v[168:171], v[200:203], v[180:183], v[10:13]
	v_mfma_f32_16x16x32_bf16 v[10:13], v[106:109], v[184:187], v[78:81]
	v_mfma_f32_16x16x32_bf16 v[14:17], v[106:109], v[90:93], v[14:17]
	v_mfma_f32_16x16x32_bf16 v[6:9], v[110:113], v[172:175], v[6:9]
	v_mfma_f32_16x16x32_bf16 v[2:5], v[200:203], v[172:175], v[2:5]
	v_mfma_f32_16x16x32_bf16 v[172:175], v[110:113], v[188:191], v[10:13]
	v_mfma_f32_16x16x32_bf16 v[10:13], v[196:199], v[184:187], v[82:85]
	v_mfma_f32_16x16x32_bf16 v[134:137], v[110:113], v[94:97], v[14:17]
	v_mfma_f32_16x16x32_bf16 v[176:179], v[200:203], v[188:191], v[10:13]
	s_setprio 0
	s_barrier
	s_nop 3
	ds_read_b128 v[10:13], v151 offset:32768
	ds_read_b128 v[14:17], v151 offset:33792
	ds_read_b128 v[180:183], v151 offset:34816
	ds_read_b128 v[184:187], v151 offset:35840
	ds_read_b128 v[66:69], v0 offset:32768
	ds_read_b128 v[82:85], v0 offset:33792
	ds_read_b128 v[188:191], v0 offset:34816
	ds_read_b128 v[192:195], v0 offset:35840
	ds_read_b128 v[196:199], v0 offset:36864
	ds_read_b128 v[200:203], v0 offset:37888
	ds_read_b128 v[232:235], v0 offset:38912
	ds_read_b128 v[236:239], v0 offset:39936
	s_waitcnt vmcnt(2)
	s_barrier
	s_waitcnt lgkmcnt(0)
	s_setprio 1
	s_waitcnt lgkmcnt(7)
	v_mfma_f32_16x16x32_bf16 v[74:77], v[10:13], v[66:69], v[126:129]
	s_waitcnt lgkmcnt(6)
	v_mfma_f32_16x16x32_bf16 v[138:141], v[14:17], v[82:85], v[74:77]
	v_mfma_f32_16x16x32_bf16 v[74:77], v[180:183], v[66:69], v[122:125]
	v_mfma_f32_16x16x32_bf16 v[122:125], v[184:187], v[82:85], v[74:77]
	s_waitcnt lgkmcnt(5)
	v_mfma_f32_16x16x32_bf16 v[74:77], v[10:13], v[188:191], v[118:121]
	s_waitcnt lgkmcnt(4)
	v_mfma_f32_16x16x32_bf16 v[110:113], v[14:17], v[192:195], v[74:77]
	v_mfma_f32_16x16x32_bf16 v[74:77], v[180:183], v[188:191], v[114:117]
	v_mfma_f32_16x16x32_bf16 v[106:109], v[184:187], v[192:195], v[74:77]
	s_waitcnt lgkmcnt(3)
	v_mfma_f32_16x16x32_bf16 v[74:77], v[10:13], v[196:199], v[130:133]
	s_waitcnt lgkmcnt(2)
	v_mfma_f32_16x16x32_bf16 v[94:97], v[14:17], v[200:203], v[74:77]
	v_mfma_f32_16x16x32_bf16 v[74:77], v[180:183], v[196:199], v[160:163]
	v_mfma_f32_16x16x32_bf16 v[90:93], v[184:187], v[200:203], v[74:77]
	s_waitcnt lgkmcnt(1)
	v_mfma_f32_16x16x32_bf16 v[74:77], v[10:13], v[232:235], v[102:105]
	s_waitcnt lgkmcnt(0)
	v_mfma_f32_16x16x32_bf16 v[78:81], v[14:17], v[236:239], v[74:77]
	v_mfma_f32_16x16x32_bf16 v[74:77], v[180:183], v[232:235], v[98:101]
	v_mfma_f32_16x16x32_bf16 v[74:77], v[184:187], v[236:239], v[74:77]
	s_setprio 0
	s_barrier
	ds_read_b128 v[126:129], v151 offset:49152
	ds_read_b128 v[130:133], v151 offset:50176
	ds_read_b128 v[160:163], v151 offset:51200
	ds_read_b128 v[148:151], v151 offset:52224
	s_waitcnt vmcnt(0)
	s_barrier
	s_waitcnt lgkmcnt(0)
	s_setprio 1
	s_waitcnt lgkmcnt(3)
	v_mfma_f32_16x16x32_bf16 v[98:101], v[126:129], v[66:69], v[222:225]
	s_waitcnt lgkmcnt(1)
	v_mfma_f32_16x16x32_bf16 v[66:69], v[160:163], v[66:69], v[164:167]
	s_waitcnt lgkmcnt(0)
	v_mfma_f32_16x16x32_bf16 v[114:117], v[148:151], v[82:85], v[66:69]
	v_mfma_f32_16x16x32_bf16 v[66:69], v[126:129], v[188:191], v[86:89]
	v_mfma_f32_16x16x32_bf16 v[102:105], v[130:133], v[192:195], v[66:69]
	v_mfma_f32_16x16x32_bf16 v[66:69], v[160:163], v[188:191], v[70:73]
	v_mfma_f32_16x16x32_bf16 v[62:65], v[126:129], v[196:199], v[62:65]
	v_mfma_f32_16x16x32_bf16 v[58:61], v[160:163], v[196:199], v[58:61]
	v_mfma_f32_16x16x32_bf16 v[54:57], v[126:129], v[232:235], v[54:57]
	v_mfma_f32_16x16x32_bf16 v[50:53], v[160:163], v[232:235], v[50:53]
	v_mfma_f32_16x16x32_bf16 v[118:121], v[130:133], v[82:85], v[98:101]
	v_mfma_f32_16x16x32_bf16 v[98:101], v[148:151], v[192:195], v[66:69]
	v_mfma_f32_16x16x32_bf16 v[86:89], v[130:133], v[200:203], v[62:65]
	v_mfma_f32_16x16x32_bf16 v[82:85], v[148:151], v[200:203], v[58:61]
	v_mfma_f32_16x16x32_bf16 v[70:73], v[130:133], v[236:239], v[54:57]
	v_mfma_f32_16x16x32_bf16 v[66:69], v[148:151], v[236:239], v[50:53]
	s_setprio 0
	s_barrier
	s_nop 0
	ds_read_b128 v[50:53], v0 offset:49152
	ds_read_b128 v[164:167], v0 offset:50176
	ds_read_b128 v[188:191], v0 offset:51200
	ds_read_b128 v[192:195], v0 offset:52224
	ds_read_b128 v[196:199], v0 offset:53248
	ds_read_b128 v[200:203], v0 offset:54272
	ds_read_b128 v[222:225], v0 offset:55296
	ds_read_b128 v[232:235], v0 offset:56320
	s_barrier
	s_waitcnt lgkmcnt(0)
	s_setprio 1
	s_waitcnt lgkmcnt(7)
	v_mfma_f32_16x16x32_bf16 v[46:49], v[10:13], v[50:53], v[46:49]
	s_waitcnt lgkmcnt(5)
	v_mfma_f32_16x16x32_bf16 v[38:41], v[10:13], v[188:191], v[38:41]
	s_waitcnt lgkmcnt(3)
	v_mfma_f32_16x16x32_bf16 v[30:33], v[10:13], v[196:199], v[30:33]
	s_waitcnt lgkmcnt(1)
	v_mfma_f32_16x16x32_bf16 v[10:13], v[10:13], v[222:225], v[22:25]
	v_mfma_f32_16x16x32_bf16 v[62:65], v[14:17], v[164:167], v[46:49]
	v_mfma_f32_16x16x32_bf16 v[42:45], v[180:183], v[50:53], v[42:45]
	v_mfma_f32_16x16x32_bf16 v[46:49], v[14:17], v[192:195], v[38:41]
	v_mfma_f32_16x16x32_bf16 v[34:37], v[180:183], v[188:191], v[34:37]
	v_mfma_f32_16x16x32_bf16 v[30:33], v[14:17], v[200:203], v[30:33]
	v_mfma_f32_16x16x32_bf16 v[26:29], v[180:183], v[196:199], v[26:29]
	s_waitcnt lgkmcnt(0)
	v_mfma_f32_16x16x32_bf16 v[14:17], v[14:17], v[232:235], v[10:13]
	v_mfma_f32_16x16x32_bf16 v[10:13], v[180:183], v[222:225], v[18:21]
	v_mfma_f32_16x16x32_bf16 v[58:61], v[184:187], v[164:167], v[42:45]
	v_mfma_f32_16x16x32_bf16 v[42:45], v[184:187], v[192:195], v[34:37]
	v_mfma_f32_16x16x32_bf16 v[26:29], v[184:187], v[200:203], v[26:29]
	v_mfma_f32_16x16x32_bf16 v[10:13], v[184:187], v[232:235], v[10:13]
	s_setprio 0
	s_setprio 1
	v_mfma_f32_16x16x32_bf16 v[2:5], v[160:163], v[188:191], v[2:5]
	v_mfma_f32_16x16x32_bf16 v[18:21], v[126:129], v[50:53], v[134:137]
	v_mfma_f32_16x16x32_bf16 v[34:37], v[148:151], v[192:195], v[2:5]
	v_mfma_f32_16x16x32_bf16 v[2:5], v[126:129], v[196:199], v[156:159]
	v_mfma_f32_16x16x32_bf16 v[54:57], v[130:133], v[164:167], v[18:21]
	v_mfma_f32_16x16x32_bf16 v[18:21], v[160:163], v[50:53], v[152:155]
	v_mfma_f32_16x16x32_bf16 v[22:25], v[130:133], v[200:203], v[2:5]
	v_mfma_f32_16x16x32_bf16 v[2:5], v[160:163], v[196:199], v[168:171]
	v_mfma_f32_16x16x32_bf16 v[50:53], v[148:151], v[164:167], v[18:21]
	v_mfma_f32_16x16x32_bf16 v[6:9], v[126:129], v[188:191], v[6:9]
	v_mfma_f32_16x16x32_bf16 v[18:21], v[148:151], v[200:203], v[2:5]
	v_mfma_f32_16x16x32_bf16 v[2:5], v[126:129], v[222:225], v[172:175]
	v_mfma_f32_16x16x32_bf16 v[38:41], v[130:133], v[192:195], v[6:9]
	v_mfma_f32_16x16x32_bf16 v[6:9], v[130:133], v[232:235], v[2:5]
	v_mfma_f32_16x16x32_bf16 v[2:5], v[160:163], v[222:225], v[176:179]
	v_mfma_f32_16x16x32_bf16 v[2:5], v[148:151], v[232:235], v[2:5]
	s_setprio 0
	s_movk_i32 s0, 0x100
	v_cmp_gt_u32_e32 vcc, s0, v142
	s_barrier
	s_and_saveexec_b64 s[0:1], vcc
	s_cbranch_execz .LBB0_37
	s_barrier
.LBB0_37:
	s_or_b64 exec, exec, s[0:1]
	v_readlane_b32 s50, v253, 47
	v_readlane_b32 s51, v253, 48
	v_and_b32_e32 v126, 63, v206
	v_lshrrev_b32_e32 v127, 6, v206
	v_and_b32_e32 v128, 15, v206
	v_bfe_u32 v129, v206, 4, 2
	v_and_b32_e32 v130, 3, v127
	v_lshrrev_b32_e32 v131, 2, v127
	v_readfirstlane_b32 s0, v127
	s_mul_i32 s1, s10, 0x2c00
	s_lshl_b32 s5, s4, 1
	s_add_u32 s12, s50, s1
	s_addc_u32 s13, s51, 0
	s_add_u32 s12, s12, s5
	s_addc_u32 s13, s13, 0
	s_sub_u32 s36, s12, 0x2c00
	s_subb_u32 s37, s13, 0
	s_add_u32 s14, s20, s1
	s_addc_u32 s15, s21, 0
	s_add_u32 s14, s14, s5
	s_addc_u32 s15, s15, 0
	s_lshl_b32 s5, s4, 2
	s_add_u32 s16, s8, s5
	s_addc_u32 s17, s9, 0
	s_add_u32 s52, s16, 0x5800
	s_addc_u32 s53, s17, 0
	s_add_u32 s56, s16, 0xb000
	s_addc_u32 s57, s17, 0
	s_sub_u32 s1, s10, 0x1000
	s_and_b32 s1, s1, 0x7ff
	s_cmp_eq_u32 s1, 0
	s_cselect_b32 s62, 1, 0
	s_cmp_eq_u32 s1, 0x700
	s_cselect_b32 s63, 1, 0
	s_cmp_lt_u32 s10, 0x1000
	s_cselect_b32 s62, 1, s62
	s_cselect_b32 s63, 1, s63
	v_lshlrev_b32_e32 v136, 5, v130
	v_lshl_add_u32 v136, v129, 2, v136
	v_lshlrev_b32_e32 v137, 2, v136
	global_load_dwordx4 v[142:145], v137, s[16:17]
	global_load_dwordx4 v[146:149], v137, s[52:53]
	global_load_dwordx4 v[150:153], v137, s[56:57]
	global_load_dwordx4 v[154:157], v137, s[16:17] offset:64
	global_load_dwordx4 v[158:161], v137, s[52:53] offset:64
	global_load_dwordx4 v[162:165], v137, s[56:57] offset:64
	global_load_dwordx4 v[166:169], v137, s[16:17] offset:512
	global_load_dwordx4 v[170:173], v137, s[52:53] offset:512
	global_load_dwordx4 v[174:177], v137, s[56:57] offset:512
	global_load_dwordx4 v[178:181], v137, s[16:17] offset:576
	global_load_dwordx4 v[182:185], v137, s[52:53] offset:576
	global_load_dwordx4 v[186:189], v137, s[56:57] offset:576
	v_lshrrev_b32_e32 v132, 5, v126
	v_lshl_add_u32 v133, v127, 1, v132
	v_and_b32_e32 v134, 31, v126
	v_xor_b32_e32 v134, v134, v133
	v_mul_u32_u24_e32 v135, 0x2c00, v133
	v_lshl_add_u32 v135, v134, 4, v135
	s_lshl_b32 s1, s0, 10
	s_mov_b32 m0, s1
	s_add_i32 s1, s1, 0x2000
	global_load_lds_dwordx4 v135, s[12:13]
	s_add_u32 s12, s12, 0x2c000
	s_addc_u32 s13, s13, 0
	s_mov_b32 m0, s1
	s_add_i32 s1, s1, 0x2000
	global_load_lds_dwordx4 v135, s[12:13]
	s_add_u32 s12, s12, 0x2c000
	s_addc_u32 s13, s13, 0
	s_mov_b32 m0, s1
	s_add_i32 s1, s1, 0x2000
	global_load_lds_dwordx4 v135, s[12:13]
	s_add_u32 s12, s12, 0x2c000
	s_addc_u32 s13, s13, 0
	s_mov_b32 m0, s1
	s_add_i32 s1, s1, 0x2000
	global_load_lds_dwordx4 v135, s[12:13]
	s_add_u32 s12, s12, 0x2c000
	s_addc_u32 s13, s13, 0
	s_mov_b32 m0, s1
	s_add_i32 s1, s1, 0x2000
	global_load_lds_dwordx4 v135, s[12:13]
	s_add_u32 s12, s12, 0x2c000
	s_addc_u32 s13, s13, 0
	s_mov_b32 m0, s1
	s_add_i32 s1, s1, 0x2000
	global_load_lds_dwordx4 v135, s[12:13]
	s_add_u32 s12, s12, 0x2c000
	s_addc_u32 s13, s13, 0
	s_mov_b32 m0, s1
	s_add_i32 s1, s1, 0x2000
	global_load_lds_dwordx4 v135, s[12:13]
	s_add_u32 s12, s12, 0x2c000
	s_addc_u32 s13, s13, 0
	s_mov_b32 m0, s1
	s_add_i32 s1, s1, 0x2000
	global_load_lds_dwordx4 v135, s[12:13]
	s_add_u32 s12, s12, 0x2c000
	s_addc_u32 s13, s13, 0
	s_mov_b32 m0, s1
	s_add_i32 s1, s1, 0x2000
	global_load_lds_dwordx4 v135, s[12:13]
	s_add_u32 s12, s12, 0x2c000
	s_addc_u32 s13, s13, 0
	s_mov_b32 m0, s1
	s_add_i32 s1, s1, 0x2000
	global_load_lds_dwordx4 v135, s[12:13]
	s_add_u32 s12, s12, 0x2c000
	s_addc_u32 s13, s13, 0
	s_mov_b32 m0, s1
	s_add_i32 s1, s1, 0x2000
	global_load_lds_dwordx4 v135, s[12:13]
	s_add_u32 s12, s12, 0x2c000
	s_addc_u32 s13, s13, 0
	s_mov_b32 m0, s1
	s_add_i32 s1, s1, 0x2000
	global_load_lds_dwordx4 v135, s[12:13]
	s_add_u32 s12, s12, 0x2c000
	s_addc_u32 s13, s13, 0
	s_mov_b32 m0, s1
	s_add_i32 s1, s1, 0x2000
	global_load_lds_dwordx4 v135, s[12:13]
	s_add_u32 s12, s12, 0x2c000
	s_addc_u32 s13, s13, 0
	s_mov_b32 m0, s1
	s_add_i32 s1, s1, 0x2000
	global_load_lds_dwordx4 v135, s[12:13]
	s_add_u32 s12, s12, 0x2c000
	s_addc_u32 s13, s13, 0
	s_mov_b32 m0, s1
	s_add_i32 s1, s1, 0x2000
	global_load_lds_dwordx4 v135, s[12:13]
	s_add_u32 s12, s12, 0x2c000
	s_addc_u32 s13, s13, 0
	s_mov_b32 m0, s1
	s_add_i32 s1, s1, 0x2000
	global_load_lds_dwordx4 v135, s[12:13]
	s_cmp_lg_u32 s0, 0
	s_cbranch_scc1 .Lepiup_noextra
	v_cmp_gt_u32_e32 vcc, 32, v126
	v_and_b32_e32 v134, 31, v126
	v_xor_b32_e32 v133, 15, v134
	v_lshlrev_b32_e32 v133, 4, v133
	v_lshlrev_b32_e32 v134, 4, v134
	v_add_u32_e32 v134, 0x2c2c00, v134
	v_cndmask_b32_e32 v133, v134, v133, vcc
	v_lshlrev_b32_e32 v134, 4, v126
	v_add_u32_e32 v134, 0x20100, v134
	v_mov_b32_e32 v0, 0
	v_mov_b32_e32 v132, 0
	s_cmp_lg_u32 s62, 0
	s_cselect_b32 s38, -1, 0
	s_cmp_lg_u32 s63, 0
	s_cselect_b32 s39, -1, 0
	s_mov_b64 s[40:41], exec
	s_mov_b64 exec, s[38:39]
	s_cbranch_execz .Lepiup_nozero
	ds_write_b64 v134, v[0:1]
	ds_write_b64 v134, v[0:1] offset:8
.Lepiup_nozero:
	s_not_b64 exec, s[38:39]
	s_cbranch_execz .Lepiup_nodma
	s_mov_b32 m0, 0x20100
	s_nop 0
	global_load_lds_dwordx4 v133, s[36:37]
.Lepiup_nodma:
	s_mov_b64 exec, s[40:41]
.Lepiup_noextra:
	v_lshrrev_b32_e32 v132, 1, v129
	v_lshl_add_u32 v132, v130, 2, v132
	v_and_b32_e32 v133, 1, v129
	v_lshlrev_b32_e32 v133, 3, v133
	v_lshl_add_u32 v134, v131, 6, v128
	v_add_u32_e32 v135, 15, v128
	v_and_b32_e32 v135, 15, v135
	v_add_u32_e32 v137, 1, v128
	v_and_b32_e32 v137, 15, v137
	v_cmp_eq_u32_e64 s[38:39], 0, v134
	s_movk_i32 s1, 0x4f
	v_cmp_eq_u32_e64 s[40:41], s1, v134
	v_mov_b32_e32 v244, v132
	v_xor_b32_e32 v245, v244, v135
	v_xor_b32_e32 v246, v244, v128
	v_xor_b32_e32 v247, v244, v137
	v_lshl_add_u32 v245, v245, 4, v133
	v_lshl_add_u32 v246, v246, 4, v133
	v_lshl_add_u32 v247, v247, 4, v133
	v_lshlrev_b32_e32 v248, 9, v134
	v_add_u32_e32 v194, v248, v246
	v_add_u32_e32 v249, 0x200, v248
	v_add_u32_e32 v196, v249, v247
	v_add_u32_e32 v249, 0x1e00, v248
	v_add_u32_e32 v190, v249, v245
	v_add_u32_e32 v249, 0xfe00, v248
	v_add_u32_e32 v198, v249, v245
	v_add_u32_e32 v200, 0x10000, v194
	v_add_u32_e32 v202, 0x10000, v196
	v_subrev_u32_e32 v249, 0x200, v248
	v_add_u32_e32 v249, v249, v245
	v_add_u32_e32 v250, 0x20100, v245
	v_cndmask_b32_e64 v192, v249, v250, s[38:39]
	v_add_u32_e32 v249, 0x16200, v248
	v_add_u32_e32 v249, v249, v247
	v_add_u32_e32 v250, 0x20300, v247
	v_cndmask_b32_e64 v204, v249, v250, s[40:41]
	v_add_u32_e32 v244, 2, v132
	v_xor_b32_e32 v245, v244, v135
	v_xor_b32_e32 v246, v244, v128
	v_xor_b32_e32 v247, v244, v137
	v_lshl_add_u32 v245, v245, 4, v133
	v_lshl_add_u32 v246, v246, 4, v133
	v_lshl_add_u32 v247, v247, 4, v133
	v_lshlrev_b32_e32 v248, 9, v134
	v_add_u32_e32 v195, v248, v246
	v_add_u32_e32 v249, 0x200, v248
	v_add_u32_e32 v197, v249, v247
	v_add_u32_e32 v249, 0x1e00, v248
	v_add_u32_e32 v191, v249, v245
	v_add_u32_e32 v249, 0xfe00, v248
	v_add_u32_e32 v199, v249, v245
	v_add_u32_e32 v201, 0x10000, v195
	v_add_u32_e32 v203, 0x10000, v197
	v_subrev_u32_e32 v249, 0x200, v248
	v_add_u32_e32 v249, v249, v245
	v_add_u32_e32 v250, 0x20100, v245
	v_cndmask_b32_e64 v193, v249, v250, s[38:39]
	v_add_u32_e32 v249, 0x16200, v248
	v_add_u32_e32 v249, v249, v247
	v_add_u32_e32 v250, 0x20300, v247
	v_cndmask_b32_e64 v205, v249, v250, s[40:41]
	v_mul_u32_u24_e32 v228, 0x2c00, v134
	v_lshl_add_u32 v228, v136, 1, v228
	v_mov_b32_e32 v229, 0
	v_lshl_add_u64 v[210:211], v[228:229], 0, s[14:15]
	s_mov_b64 s[72:73], 0x2c000
	s_mov_b64 s[10:11], 0xdc000
	s_waitcnt vmcnt(0) lgkmcnt(0)
	s_barrier
	ds_read_b64 v[232:233], v192
	ds_read_b64 v[234:235], v194
	ds_read_b64 v[236:237], v196
	ds_read_b64 v[238:239], v193
	ds_read_b64 v[240:241], v195
	ds_read_b64 v[242:243], v197
	s_waitcnt lgkmcnt(3)
	v_lshlrev_b32_e32 v244, 16, v232
	v_and_b32_e32 v245, 0xffff0000, v232
	v_lshlrev_b32_e32 v246, 16, v233
	v_and_b32_e32 v247, 0xffff0000, v233
	v_mul_f32_e32 v248, v142, v244
	v_mul_f32_e32 v249, v143, v245
	v_mul_f32_e32 v250, v144, v246
	v_mul_f32_e32 v251, v145, v247
	v_lshlrev_b32_e32 v244, 16, v234
	v_and_b32_e32 v245, 0xffff0000, v234
	v_lshlrev_b32_e32 v246, 16, v235
	v_and_b32_e32 v247, 0xffff0000, v235
	v_fmac_f32_e32 v248, v146, v244
	v_fmac_f32_e32 v249, v147, v245
	v_fmac_f32_e32 v250, v148, v246
	v_fmac_f32_e32 v251, v149, v247
	v_lshlrev_b32_e32 v244, 16, v236
	v_and_b32_e32 v245, 0xffff0000, v236
	v_lshlrev_b32_e32 v246, 16, v237
	v_and_b32_e32 v247, 0xffff0000, v237
	v_fmac_f32_e32 v248, v150, v244
	v_fmac_f32_e32 v249, v151, v245
	v_fmac_f32_e32 v250, v152, v246
	v_fmac_f32_e32 v251, v153, v247
	v_mul_f32_e32 v244, 0xbfb8aa3b, v248
	v_mul_f32_e32 v245, 0xbfb8aa3b, v249
	v_mul_f32_e32 v246, 0xbfb8aa3b, v250
	v_mul_f32_e32 v247, 0xbfb8aa3b, v251
	v_exp_f32_e32 v244, v244
	v_exp_f32_e32 v245, v245
	v_exp_f32_e32 v246, v246
	v_exp_f32_e32 v247, v247
	v_add_f32_e32 v244, 1.0, v244
	v_add_f32_e32 v245, 1.0, v245
	v_add_f32_e32 v246, 1.0, v246
	v_add_f32_e32 v247, 1.0, v247
	v_rcp_f32_e32 v244, v244
	v_rcp_f32_e32 v245, v245
	v_rcp_f32_e32 v246, v246
	v_rcp_f32_e32 v247, v247
	v_mul_f32_e32 v248, v248, v244
	v_mul_f32_e32 v249, v249, v245
	v_mul_f32_e32 v250, v250, v246
	v_mul_f32_e32 v251, v251, v247
	v_mul_f32_e32 v138, v138, v248
	v_mul_f32_e32 v139, v139, v249
	v_mul_f32_e32 v140, v140, v250
	v_mul_f32_e32 v141, v141, v251
	v_cvt_pk_bf16_f32 v216, v138, v139
	v_cvt_pk_bf16_f32 v217, v140, v141
	global_store_dwordx2 v[210:211], v[216:217], off
	ds_read_b64 v[232:233], v192 offset:256
	ds_read_b64 v[234:235], v194 offset:256
	ds_read_b64 v[236:237], v196 offset:256
	s_waitcnt lgkmcnt(3)
	v_lshlrev_b32_e32 v244, 16, v238
	v_and_b32_e32 v245, 0xffff0000, v238
	v_lshlrev_b32_e32 v246, 16, v239
	v_and_b32_e32 v247, 0xffff0000, v239
	v_mul_f32_e32 v248, v154, v244
	v_mul_f32_e32 v249, v155, v245
	v_mul_f32_e32 v250, v156, v246
	v_mul_f32_e32 v251, v157, v247
	v_lshlrev_b32_e32 v244, 16, v240
	v_and_b32_e32 v245, 0xffff0000, v240
	v_lshlrev_b32_e32 v246, 16, v241
	v_and_b32_e32 v247, 0xffff0000, v241
	v_fmac_f32_e32 v248, v158, v244
	v_fmac_f32_e32 v249, v159, v245
	v_fmac_f32_e32 v250, v160, v246
	v_fmac_f32_e32 v251, v161, v247
	v_lshlrev_b32_e32 v244, 16, v242
	v_and_b32_e32 v245, 0xffff0000, v242
	v_lshlrev_b32_e32 v246, 16, v243
	v_and_b32_e32 v247, 0xffff0000, v243
	v_fmac_f32_e32 v248, v162, v244
	v_fmac_f32_e32 v249, v163, v245
	v_fmac_f32_e32 v250, v164, v246
	v_fmac_f32_e32 v251, v165, v247
	v_mul_f32_e32 v244, 0xbfb8aa3b, v248
	v_mul_f32_e32 v245, 0xbfb8aa3b, v249
	v_mul_f32_e32 v246, 0xbfb8aa3b, v250
	v_mul_f32_e32 v247, 0xbfb8aa3b, v251
	v_exp_f32_e32 v244, v244
	v_exp_f32_e32 v245, v245
	v_exp_f32_e32 v246, v246
	v_exp_f32_e32 v247, v247
	v_add_f32_e32 v244, 1.0, v244
	v_add_f32_e32 v245, 1.0, v245
	v_add_f32_e32 v246, 1.0, v246
	v_add_f32_e32 v247, 1.0, v247
	v_rcp_f32_e32 v244, v244
	v_rcp_f32_e32 v245, v245
	v_rcp_f32_e32 v246, v246
	v_rcp_f32_e32 v247, v247
	v_mul_f32_e32 v248, v248, v244
	v_mul_f32_e32 v249, v249, v245
	v_mul_f32_e32 v250, v250, v246
	v_mul_f32_e32 v251, v251, v247
	v_mul_f32_e32 v122, v122, v248
	v_mul_f32_e32 v123, v123, v249
	v_mul_f32_e32 v124, v124, v250
	v_mul_f32_e32 v125, v125, v251
	v_cvt_pk_bf16_f32 v218, v122, v123
	v_cvt_pk_bf16_f32 v219, v124, v125
	global_store_dwordx2 v[210:211], v[218:219], off offset:32
	ds_read_b64 v[238:239], v193 offset:256
	ds_read_b64 v[240:241], v195 offset:256
	ds_read_b64 v[242:243], v197 offset:256
	s_waitcnt lgkmcnt(3)
	v_lshlrev_b32_e32 v244, 16, v232
	v_and_b32_e32 v245, 0xffff0000, v232
	v_lshlrev_b32_e32 v246, 16, v233
	v_and_b32_e32 v247, 0xffff0000, v233
	v_mul_f32_e32 v248, v166, v244
	v_mul_f32_e32 v249, v167, v245
	v_mul_f32_e32 v250, v168, v246
	v_mul_f32_e32 v251, v169, v247
	v_lshlrev_b32_e32 v244, 16, v234
	v_and_b32_e32 v245, 0xffff0000, v234
	v_lshlrev_b32_e32 v246, 16, v235
	v_and_b32_e32 v247, 0xffff0000, v235
	v_fmac_f32_e32 v248, v170, v244
	v_fmac_f32_e32 v249, v171, v245
	v_fmac_f32_e32 v250, v172, v246
	v_fmac_f32_e32 v251, v173, v247
	v_lshlrev_b32_e32 v244, 16, v236
	v_and_b32_e32 v245, 0xffff0000, v236
	v_lshlrev_b32_e32 v246, 16, v237
	v_and_b32_e32 v247, 0xffff0000, v237
	v_fmac_f32_e32 v248, v174, v244
	v_fmac_f32_e32 v249, v175, v245
	v_fmac_f32_e32 v250, v176, v246
	v_fmac_f32_e32 v251, v177, v247
	v_mul_f32_e32 v244, 0xbfb8aa3b, v248
	v_mul_f32_e32 v245, 0xbfb8aa3b, v249
	v_mul_f32_e32 v246, 0xbfb8aa3b, v250
	v_mul_f32_e32 v247, 0xbfb8aa3b, v251
	v_exp_f32_e32 v244, v244
	v_exp_f32_e32 v245, v245
	v_exp_f32_e32 v246, v246
	v_exp_f32_e32 v247, v247
	v_add_f32_e32 v244, 1.0, v244
	v_add_f32_e32 v245, 1.0, v245
	v_add_f32_e32 v246, 1.0, v246
	v_add_f32_e32 v247, 1.0, v247
	v_rcp_f32_e32 v244, v244
	v_rcp_f32_e32 v245, v245
	v_rcp_f32_e32 v246, v246
	v_rcp_f32_e32 v247, v247
	v_mul_f32_e32 v248, v248, v244
	v_mul_f32_e32 v249, v249, v245
	v_mul_f32_e32 v250, v250, v246
	v_mul_f32_e32 v251, v251, v247
	v_mul_f32_e32 v118, v118, v248
	v_mul_f32_e32 v119, v119, v249
	v_mul_f32_e32 v120, v120, v250
	v_mul_f32_e32 v121, v121, v251
	v_cvt_pk_bf16_f32 v216, v118, v119
	v_cvt_pk_bf16_f32 v217, v120, v121
	global_store_dwordx2 v[210:211], v[216:217], off offset:256
	ds_read_b64 v[232:233], v190
	ds_read_b64 v[234:235], v194 offset:8192
	ds_read_b64 v[236:237], v196 offset:8192
	s_waitcnt lgkmcnt(3)
	v_lshlrev_b32_e32 v244, 16, v238
	v_and_b32_e32 v245, 0xffff0000, v238
	v_lshlrev_b32_e32 v246, 16, v239
	v_and_b32_e32 v247, 0xffff0000, v239
	v_mul_f32_e32 v248, v178, v244
	v_mul_f32_e32 v249, v179, v245
	v_mul_f32_e32 v250, v180, v246
	v_mul_f32_e32 v251, v181, v247
	v_lshlrev_b32_e32 v244, 16, v240
	v_and_b32_e32 v245, 0xffff0000, v240
	v_lshlrev_b32_e32 v246, 16, v241
	v_and_b32_e32 v247, 0xffff0000, v241
	v_fmac_f32_e32 v248, v182, v244
	v_fmac_f32_e32 v249, v183, v245
	v_fmac_f32_e32 v250, v184, v246
	v_fmac_f32_e32 v251, v185, v247
	v_lshlrev_b32_e32 v244, 16, v242
	v_and_b32_e32 v245, 0xffff0000, v242
	v_lshlrev_b32_e32 v246, 16, v243
	v_and_b32_e32 v247, 0xffff0000, v243
	v_fmac_f32_e32 v248, v186, v244
	v_fmac_f32_e32 v249, v187, v245
	v_fmac_f32_e32 v250, v188, v246
	v_fmac_f32_e32 v251, v189, v247
	v_mul_f32_e32 v244, 0xbfb8aa3b, v248
	v_mul_f32_e32 v245, 0xbfb8aa3b, v249
	v_mul_f32_e32 v246, 0xbfb8aa3b, v250
	v_mul_f32_e32 v247, 0xbfb8aa3b, v251
	v_exp_f32_e32 v244, v244
	v_exp_f32_e32 v245, v245
	v_exp_f32_e32 v246, v246
	v_exp_f32_e32 v247, v247
	v_add_f32_e32 v244, 1.0, v244
	v_add_f32_e32 v245, 1.0, v245
	v_add_f32_e32 v246, 1.0, v246
	v_add_f32_e32 v247, 1.0, v247
	v_rcp_f32_e32 v244, v244
	v_rcp_f32_e32 v245, v245
	v_rcp_f32_e32 v246, v246
	v_rcp_f32_e32 v247, v247
	v_mul_f32_e32 v248, v248, v244
	v_mul_f32_e32 v249, v249, v245
	v_mul_f32_e32 v250, v250, v246
	v_mul_f32_e32 v251, v251, v247
	v_mul_f32_e32 v114, v114, v248
	v_mul_f32_e32 v115, v115, v249
	v_mul_f32_e32 v116, v116, v250
	v_mul_f32_e32 v117, v117, v251
	v_cvt_pk_bf16_f32 v218, v114, v115
	v_cvt_pk_bf16_f32 v219, v116, v117
	global_store_dwordx2 v[210:211], v[218:219], off offset:288
	v_lshl_add_u64 v[210:211], v[210:211], 0, s[72:73]
	ds_read_b64 v[238:239], v191
	ds_read_b64 v[240:241], v195 offset:8192
	ds_read_b64 v[242:243], v197 offset:8192
	s_waitcnt lgkmcnt(3)
	v_lshlrev_b32_e32 v244, 16, v232
	v_and_b32_e32 v245, 0xffff0000, v232
	v_lshlrev_b32_e32 v246, 16, v233
	v_and_b32_e32 v247, 0xffff0000, v233
	v_mul_f32_e32 v248, v142, v244
	v_mul_f32_e32 v249, v143, v245
	v_mul_f32_e32 v250, v144, v246
	v_mul_f32_e32 v251, v145, v247
	v_lshlrev_b32_e32 v244, 16, v234
	v_and_b32_e32 v245, 0xffff0000, v234
	v_lshlrev_b32_e32 v246, 16, v235
	v_and_b32_e32 v247, 0xffff0000, v235
	v_fmac_f32_e32 v248, v146, v244
	v_fmac_f32_e32 v249, v147, v245
	v_fmac_f32_e32 v250, v148, v246
	v_fmac_f32_e32 v251, v149, v247
	v_lshlrev_b32_e32 v244, 16, v236
	v_and_b32_e32 v245, 0xffff0000, v236
	v_lshlrev_b32_e32 v246, 16, v237
	v_and_b32_e32 v247, 0xffff0000, v237
	v_fmac_f32_e32 v248, v150, v244
	v_fmac_f32_e32 v249, v151, v245
	v_fmac_f32_e32 v250, v152, v246
	v_fmac_f32_e32 v251, v153, v247
	v_mul_f32_e32 v244, 0xbfb8aa3b, v248
	v_mul_f32_e32 v245, 0xbfb8aa3b, v249
	v_mul_f32_e32 v246, 0xbfb8aa3b, v250
	v_mul_f32_e32 v247, 0xbfb8aa3b, v251
	v_exp_f32_e32 v244, v244
	v_exp_f32_e32 v245, v245
	v_exp_f32_e32 v246, v246
	v_exp_f32_e32 v247, v247
	v_add_f32_e32 v244, 1.0, v244
	v_add_f32_e32 v245, 1.0, v245
	v_add_f32_e32 v246, 1.0, v246
	v_add_f32_e32 v247, 1.0, v247
	v_rcp_f32_e32 v244, v244
	v_rcp_f32_e32 v245, v245
	v_rcp_f32_e32 v246, v246
	v_rcp_f32_e32 v247, v247
	v_mul_f32_e32 v248, v248, v244
	v_mul_f32_e32 v249, v249, v245
	v_mul_f32_e32 v250, v250, v246
	v_mul_f32_e32 v251, v251, v247
	v_mul_f32_e32 v110, v110, v248
	v_mul_f32_e32 v111, v111, v249
	v_mul_f32_e32 v112, v112, v250
	v_mul_f32_e32 v113, v113, v251
	v_cvt_pk_bf16_f32 v216, v110, v111
	v_cvt_pk_bf16_f32 v217, v112, v113
	global_store_dwordx2 v[210:211], v[216:217], off
	ds_read_b64 v[232:233], v190 offset:256
	ds_read_b64 v[234:235], v194 offset:8448
	ds_read_b64 v[236:237], v196 offset:8448
	s_waitcnt lgkmcnt(3)
	v_lshlrev_b32_e32 v244, 16, v238
	v_and_b32_e32 v245, 0xffff0000, v238
	v_lshlrev_b32_e32 v246, 16, v239
	v_and_b32_e32 v247, 0xffff0000, v239
	v_mul_f32_e32 v248, v154, v244
	v_mul_f32_e32 v249, v155, v245
	v_mul_f32_e32 v250, v156, v246
	v_mul_f32_e32 v251, v157, v247
	v_lshlrev_b32_e32 v244, 16, v240
	v_and_b32_e32 v245, 0xffff0000, v240
	v_lshlrev_b32_e32 v246, 16, v241
	v_and_b32_e32 v247, 0xffff0000, v241
	v_fmac_f32_e32 v248, v158, v244
	v_fmac_f32_e32 v249, v159, v245
	v_fmac_f32_e32 v250, v160, v246
	v_fmac_f32_e32 v251, v161, v247
	v_lshlrev_b32_e32 v244, 16, v242
	v_and_b32_e32 v245, 0xffff0000, v242
	v_lshlrev_b32_e32 v246, 16, v243
	v_and_b32_e32 v247, 0xffff0000, v243
	v_fmac_f32_e32 v248, v162, v244
	v_fmac_f32_e32 v249, v163, v245
	v_fmac_f32_e32 v250, v164, v246
	v_fmac_f32_e32 v251, v165, v247
	v_mul_f32_e32 v244, 0xbfb8aa3b, v248
	v_mul_f32_e32 v245, 0xbfb8aa3b, v249
	v_mul_f32_e32 v246, 0xbfb8aa3b, v250
	v_mul_f32_e32 v247, 0xbfb8aa3b, v251
	v_exp_f32_e32 v244, v244
	v_exp_f32_e32 v245, v245
	v_exp_f32_e32 v246, v246
	v_exp_f32_e32 v247, v247
	v_add_f32_e32 v244, 1.0, v244
	v_add_f32_e32 v245, 1.0, v245
	v_add_f32_e32 v246, 1.0, v246
	v_add_f32_e32 v247, 1.0, v247
	v_rcp_f32_e32 v244, v244
	v_rcp_f32_e32 v245, v245
	v_rcp_f32_e32 v246, v246
	v_rcp_f32_e32 v247, v247
	v_mul_f32_e32 v248, v248, v244
	v_mul_f32_e32 v249, v249, v245
	v_mul_f32_e32 v250, v250, v246
	v_mul_f32_e32 v251, v251, v247
	v_mul_f32_e32 v106, v106, v248
	v_mul_f32_e32 v107, v107, v249
	v_mul_f32_e32 v108, v108, v250
	v_mul_f32_e32 v109, v109, v251
	v_cvt_pk_bf16_f32 v218, v106, v107
	v_cvt_pk_bf16_f32 v219, v108, v109
	global_store_dwordx2 v[210:211], v[218:219], off offset:32
	ds_read_b64 v[238:239], v191 offset:256
	ds_read_b64 v[240:241], v195 offset:8448
	ds_read_b64 v[242:243], v197 offset:8448
	s_waitcnt lgkmcnt(3)
	v_lshlrev_b32_e32 v244, 16, v232
	v_and_b32_e32 v245, 0xffff0000, v232
	v_lshlrev_b32_e32 v246, 16, v233
	v_and_b32_e32 v247, 0xffff0000, v233
	v_mul_f32_e32 v248, v166, v244
	v_mul_f32_e32 v249, v167, v245
	v_mul_f32_e32 v250, v168, v246
	v_mul_f32_e32 v251, v169, v247
	v_lshlrev_b32_e32 v244, 16, v234
	v_and_b32_e32 v245, 0xffff0000, v234
	v_lshlrev_b32_e32 v246, 16, v235
	v_and_b32_e32 v247, 0xffff0000, v235
	v_fmac_f32_e32 v248, v170, v244
	v_fmac_f32_e32 v249, v171, v245
	v_fmac_f32_e32 v250, v172, v246
	v_fmac_f32_e32 v251, v173, v247
	v_lshlrev_b32_e32 v244, 16, v236
	v_and_b32_e32 v245, 0xffff0000, v236
	v_lshlrev_b32_e32 v246, 16, v237
	v_and_b32_e32 v247, 0xffff0000, v237
	v_fmac_f32_e32 v248, v174, v244
	v_fmac_f32_e32 v249, v175, v245
	v_fmac_f32_e32 v250, v176, v246
	v_fmac_f32_e32 v251, v177, v247
	v_mul_f32_e32 v244, 0xbfb8aa3b, v248
	v_mul_f32_e32 v245, 0xbfb8aa3b, v249
	v_mul_f32_e32 v246, 0xbfb8aa3b, v250
	v_mul_f32_e32 v247, 0xbfb8aa3b, v251
	v_exp_f32_e32 v244, v244
	v_exp_f32_e32 v245, v245
	v_exp_f32_e32 v246, v246
	v_exp_f32_e32 v247, v247
	v_add_f32_e32 v244, 1.0, v244
	v_add_f32_e32 v245, 1.0, v245
	v_add_f32_e32 v246, 1.0, v246
	v_add_f32_e32 v247, 1.0, v247
	v_rcp_f32_e32 v244, v244
	v_rcp_f32_e32 v245, v245
	v_rcp_f32_e32 v246, v246
	v_rcp_f32_e32 v247, v247
	v_mul_f32_e32 v248, v248, v244
	v_mul_f32_e32 v249, v249, v245
	v_mul_f32_e32 v250, v250, v246
	v_mul_f32_e32 v251, v251, v247
	v_mul_f32_e32 v102, v102, v248
	v_mul_f32_e32 v103, v103, v249
	v_mul_f32_e32 v104, v104, v250
	v_mul_f32_e32 v105, v105, v251
	v_cvt_pk_bf16_f32 v216, v102, v103
	v_cvt_pk_bf16_f32 v217, v104, v105
	global_store_dwordx2 v[210:211], v[216:217], off offset:256
	ds_read_b64 v[232:233], v190 offset:8192
	ds_read_b64 v[234:235], v194 offset:16384
	ds_read_b64 v[236:237], v196 offset:16384
	s_waitcnt lgkmcnt(3)
	v_lshlrev_b32_e32 v244, 16, v238
	v_and_b32_e32 v245, 0xffff0000, v238
	v_lshlrev_b32_e32 v246, 16, v239
	v_and_b32_e32 v247, 0xffff0000, v239
	v_mul_f32_e32 v248, v178, v244
	v_mul_f32_e32 v249, v179, v245
	v_mul_f32_e32 v250, v180, v246
	v_mul_f32_e32 v251, v181, v247
	v_lshlrev_b32_e32 v244, 16, v240
	v_and_b32_e32 v245, 0xffff0000, v240
	v_lshlrev_b32_e32 v246, 16, v241
	v_and_b32_e32 v247, 0xffff0000, v241
	v_fmac_f32_e32 v248, v182, v244
	v_fmac_f32_e32 v249, v183, v245
	v_fmac_f32_e32 v250, v184, v246
	v_fmac_f32_e32 v251, v185, v247
	v_lshlrev_b32_e32 v244, 16, v242
	v_and_b32_e32 v245, 0xffff0000, v242
	v_lshlrev_b32_e32 v246, 16, v243
	v_and_b32_e32 v247, 0xffff0000, v243
	v_fmac_f32_e32 v248, v186, v244
	v_fmac_f32_e32 v249, v187, v245
	v_fmac_f32_e32 v250, v188, v246
	v_fmac_f32_e32 v251, v189, v247
	v_mul_f32_e32 v244, 0xbfb8aa3b, v248
	v_mul_f32_e32 v245, 0xbfb8aa3b, v249
	v_mul_f32_e32 v246, 0xbfb8aa3b, v250
	v_mul_f32_e32 v247, 0xbfb8aa3b, v251
	v_exp_f32_e32 v244, v244
	v_exp_f32_e32 v245, v245
	v_exp_f32_e32 v246, v246
	v_exp_f32_e32 v247, v247
	v_add_f32_e32 v244, 1.0, v244
	v_add_f32_e32 v245, 1.0, v245
	v_add_f32_e32 v246, 1.0, v246
	v_add_f32_e32 v247, 1.0, v247
	v_rcp_f32_e32 v244, v244
	v_rcp_f32_e32 v245, v245
	v_rcp_f32_e32 v246, v246
	v_rcp_f32_e32 v247, v247
	v_mul_f32_e32 v248, v248, v244
	v_mul_f32_e32 v249, v249, v245
	v_mul_f32_e32 v250, v250, v246
	v_mul_f32_e32 v251, v251, v247
	v_mul_f32_e32 v98, v98, v248
	v_mul_f32_e32 v99, v99, v249
	v_mul_f32_e32 v100, v100, v250
	v_mul_f32_e32 v101, v101, v251
	v_cvt_pk_bf16_f32 v218, v98, v99
	v_cvt_pk_bf16_f32 v219, v100, v101
	global_store_dwordx2 v[210:211], v[218:219], off offset:288
	v_lshl_add_u64 v[210:211], v[210:211], 0, s[72:73]
	ds_read_b64 v[238:239], v191 offset:8192
	ds_read_b64 v[240:241], v195 offset:16384
	ds_read_b64 v[242:243], v197 offset:16384
	s_waitcnt lgkmcnt(3)
	v_lshlrev_b32_e32 v244, 16, v232
	v_and_b32_e32 v245, 0xffff0000, v232
	v_lshlrev_b32_e32 v246, 16, v233
	v_and_b32_e32 v247, 0xffff0000, v233
	v_mul_f32_e32 v248, v142, v244
	v_mul_f32_e32 v249, v143, v245
	v_mul_f32_e32 v250, v144, v246
	v_mul_f32_e32 v251, v145, v247
	v_lshlrev_b32_e32 v244, 16, v234
	v_and_b32_e32 v245, 0xffff0000, v234
	v_lshlrev_b32_e32 v246, 16, v235
	v_and_b32_e32 v247, 0xffff0000, v235
	v_fmac_f32_e32 v248, v146, v244
	v_fmac_f32_e32 v249, v147, v245
	v_fmac_f32_e32 v250, v148, v246
	v_fmac_f32_e32 v251, v149, v247
	v_lshlrev_b32_e32 v244, 16, v236
	v_and_b32_e32 v245, 0xffff0000, v236
	v_lshlrev_b32_e32 v246, 16, v237
	v_and_b32_e32 v247, 0xffff0000, v237
	v_fmac_f32_e32 v248, v150, v244
	v_fmac_f32_e32 v249, v151, v245
	v_fmac_f32_e32 v250, v152, v246
	v_fmac_f32_e32 v251, v153, v247
	v_mul_f32_e32 v244, 0xbfb8aa3b, v248
	v_mul_f32_e32 v245, 0xbfb8aa3b, v249
	v_mul_f32_e32 v246, 0xbfb8aa3b, v250
	v_mul_f32_e32 v247, 0xbfb8aa3b, v251
	v_exp_f32_e32 v244, v244
	v_exp_f32_e32 v245, v245
	v_exp_f32_e32 v246, v246
	v_exp_f32_e32 v247, v247
	v_add_f32_e32 v244, 1.0, v244
	v_add_f32_e32 v245, 1.0, v245
	v_add_f32_e32 v246, 1.0, v246
	v_add_f32_e32 v247, 1.0, v247
	v_rcp_f32_e32 v244, v244
	v_rcp_f32_e32 v245, v245
	v_rcp_f32_e32 v246, v246
	v_rcp_f32_e32 v247, v247
	v_mul_f32_e32 v248, v248, v244
	v_mul_f32_e32 v249, v249, v245
	v_mul_f32_e32 v250, v250, v246
	v_mul_f32_e32 v251, v251, v247
	v_mul_f32_e32 v94, v94, v248
	v_mul_f32_e32 v95, v95, v249
	v_mul_f32_e32 v96, v96, v250
	v_mul_f32_e32 v97, v97, v251
	v_cvt_pk_bf16_f32 v216, v94, v95
	v_cvt_pk_bf16_f32 v217, v96, v97
	global_store_dwordx2 v[210:211], v[216:217], off
	ds_read_b64 v[232:233], v190 offset:8448
	ds_read_b64 v[234:235], v194 offset:16640
	ds_read_b64 v[236:237], v196 offset:16640
	s_waitcnt lgkmcnt(3)
	v_lshlrev_b32_e32 v244, 16, v238
	v_and_b32_e32 v245, 0xffff0000, v238
	v_lshlrev_b32_e32 v246, 16, v239
	v_and_b32_e32 v247, 0xffff0000, v239
	v_mul_f32_e32 v248, v154, v244
	v_mul_f32_e32 v249, v155, v245
	v_mul_f32_e32 v250, v156, v246
	v_mul_f32_e32 v251, v157, v247
	v_lshlrev_b32_e32 v244, 16, v240
	v_and_b32_e32 v245, 0xffff0000, v240
	v_lshlrev_b32_e32 v246, 16, v241
	v_and_b32_e32 v247, 0xffff0000, v241
	v_fmac_f32_e32 v248, v158, v244
	v_fmac_f32_e32 v249, v159, v245
	v_fmac_f32_e32 v250, v160, v246
	v_fmac_f32_e32 v251, v161, v247
	v_lshlrev_b32_e32 v244, 16, v242
	v_and_b32_e32 v245, 0xffff0000, v242
	v_lshlrev_b32_e32 v246, 16, v243
	v_and_b32_e32 v247, 0xffff0000, v243
	v_fmac_f32_e32 v248, v162, v244
	v_fmac_f32_e32 v249, v163, v245
	v_fmac_f32_e32 v250, v164, v246
	v_fmac_f32_e32 v251, v165, v247
	v_mul_f32_e32 v244, 0xbfb8aa3b, v248
	v_mul_f32_e32 v245, 0xbfb8aa3b, v249
	v_mul_f32_e32 v246, 0xbfb8aa3b, v250
	v_mul_f32_e32 v247, 0xbfb8aa3b, v251
	v_exp_f32_e32 v244, v244
	v_exp_f32_e32 v245, v245
	v_exp_f32_e32 v246, v246
	v_exp_f32_e32 v247, v247
	v_add_f32_e32 v244, 1.0, v244
	v_add_f32_e32 v245, 1.0, v245
	v_add_f32_e32 v246, 1.0, v246
	v_add_f32_e32 v247, 1.0, v247
	v_rcp_f32_e32 v244, v244
	v_rcp_f32_e32 v245, v245
	v_rcp_f32_e32 v246, v246
	v_rcp_f32_e32 v247, v247
	v_mul_f32_e32 v248, v248, v244
	v_mul_f32_e32 v249, v249, v245
	v_mul_f32_e32 v250, v250, v246
	v_mul_f32_e32 v251, v251, v247
	v_mul_f32_e32 v90, v90, v248
	v_mul_f32_e32 v91, v91, v249
	v_mul_f32_e32 v92, v92, v250
	v_mul_f32_e32 v93, v93, v251
	v_cvt_pk_bf16_f32 v218, v90, v91
	v_cvt_pk_bf16_f32 v219, v92, v93
	global_store_dwordx2 v[210:211], v[218:219], off offset:32
	ds_read_b64 v[238:239], v191 offset:8448
	ds_read_b64 v[240:241], v195 offset:16640
	ds_read_b64 v[242:243], v197 offset:16640
	s_waitcnt lgkmcnt(3)
	v_lshlrev_b32_e32 v244, 16, v232
	v_and_b32_e32 v245, 0xffff0000, v232
	v_lshlrev_b32_e32 v246, 16, v233
	v_and_b32_e32 v247, 0xffff0000, v233
	v_mul_f32_e32 v248, v166, v244
	v_mul_f32_e32 v249, v167, v245
	v_mul_f32_e32 v250, v168, v246
	v_mul_f32_e32 v251, v169, v247
	v_lshlrev_b32_e32 v244, 16, v234
	v_and_b32_e32 v245, 0xffff0000, v234
	v_lshlrev_b32_e32 v246, 16, v235
	v_and_b32_e32 v247, 0xffff0000, v235
	v_fmac_f32_e32 v248, v170, v244
	v_fmac_f32_e32 v249, v171, v245
	v_fmac_f32_e32 v250, v172, v246
	v_fmac_f32_e32 v251, v173, v247
	v_lshlrev_b32_e32 v244, 16, v236
	v_and_b32_e32 v245, 0xffff0000, v236
	v_lshlrev_b32_e32 v246, 16, v237
	v_and_b32_e32 v247, 0xffff0000, v237
	v_fmac_f32_e32 v248, v174, v244
	v_fmac_f32_e32 v249, v175, v245
	v_fmac_f32_e32 v250, v176, v246
	v_fmac_f32_e32 v251, v177, v247
	v_mul_f32_e32 v244, 0xbfb8aa3b, v248
	v_mul_f32_e32 v245, 0xbfb8aa3b, v249
	v_mul_f32_e32 v246, 0xbfb8aa3b, v250
	v_mul_f32_e32 v247, 0xbfb8aa3b, v251
	v_exp_f32_e32 v244, v244
	v_exp_f32_e32 v245, v245
	v_exp_f32_e32 v246, v246
	v_exp_f32_e32 v247, v247
	v_add_f32_e32 v244, 1.0, v244
	v_add_f32_e32 v245, 1.0, v245
	v_add_f32_e32 v246, 1.0, v246
	v_add_f32_e32 v247, 1.0, v247
	v_rcp_f32_e32 v244, v244
	v_rcp_f32_e32 v245, v245
	v_rcp_f32_e32 v246, v246
	v_rcp_f32_e32 v247, v247
	v_mul_f32_e32 v248, v248, v244
	v_mul_f32_e32 v249, v249, v245
	v_mul_f32_e32 v250, v250, v246
	v_mul_f32_e32 v251, v251, v247
	v_mul_f32_e32 v86, v86, v248
	v_mul_f32_e32 v87, v87, v249
	v_mul_f32_e32 v88, v88, v250
	v_mul_f32_e32 v89, v89, v251
	v_cvt_pk_bf16_f32 v216, v86, v87
	v_cvt_pk_bf16_f32 v217, v88, v89
	global_store_dwordx2 v[210:211], v[216:217], off offset:256
	ds_read_b64 v[232:233], v190 offset:16384
	ds_read_b64 v[234:235], v194 offset:24576
	ds_read_b64 v[236:237], v196 offset:24576
	s_waitcnt lgkmcnt(3)
	v_lshlrev_b32_e32 v244, 16, v238
	v_and_b32_e32 v245, 0xffff0000, v238
	v_lshlrev_b32_e32 v246, 16, v239
	v_and_b32_e32 v247, 0xffff0000, v239
	v_mul_f32_e32 v248, v178, v244
	v_mul_f32_e32 v249, v179, v245
	v_mul_f32_e32 v250, v180, v246
	v_mul_f32_e32 v251, v181, v247
	v_lshlrev_b32_e32 v244, 16, v240
	v_and_b32_e32 v245, 0xffff0000, v240
	v_lshlrev_b32_e32 v246, 16, v241
	v_and_b32_e32 v247, 0xffff0000, v241
	v_fmac_f32_e32 v248, v182, v244
	v_fmac_f32_e32 v249, v183, v245
	v_fmac_f32_e32 v250, v184, v246
	v_fmac_f32_e32 v251, v185, v247
	v_lshlrev_b32_e32 v244, 16, v242
	v_and_b32_e32 v245, 0xffff0000, v242
	v_lshlrev_b32_e32 v246, 16, v243
	v_and_b32_e32 v247, 0xffff0000, v243
	v_fmac_f32_e32 v248, v186, v244
	v_fmac_f32_e32 v249, v187, v245
	v_fmac_f32_e32 v250, v188, v246
	v_fmac_f32_e32 v251, v189, v247
	v_mul_f32_e32 v244, 0xbfb8aa3b, v248
	v_mul_f32_e32 v245, 0xbfb8aa3b, v249
	v_mul_f32_e32 v246, 0xbfb8aa3b, v250
	v_mul_f32_e32 v247, 0xbfb8aa3b, v251
	v_exp_f32_e32 v244, v244
	v_exp_f32_e32 v245, v245
	v_exp_f32_e32 v246, v246
	v_exp_f32_e32 v247, v247
	v_add_f32_e32 v244, 1.0, v244
	v_add_f32_e32 v245, 1.0, v245
	v_add_f32_e32 v246, 1.0, v246
	v_add_f32_e32 v247, 1.0, v247
	v_rcp_f32_e32 v244, v244
	v_rcp_f32_e32 v245, v245
	v_rcp_f32_e32 v246, v246
	v_rcp_f32_e32 v247, v247
	v_mul_f32_e32 v248, v248, v244
	v_mul_f32_e32 v249, v249, v245
	v_mul_f32_e32 v250, v250, v246
	v_mul_f32_e32 v251, v251, v247
	v_mul_f32_e32 v82, v82, v248
	v_mul_f32_e32 v83, v83, v249
	v_mul_f32_e32 v84, v84, v250
	v_mul_f32_e32 v85, v85, v251
	v_cvt_pk_bf16_f32 v218, v82, v83
	v_cvt_pk_bf16_f32 v219, v84, v85
	global_store_dwordx2 v[210:211], v[218:219], off offset:288
	v_lshl_add_u64 v[210:211], v[210:211], 0, s[72:73]
	ds_read_b64 v[238:239], v191 offset:16384
	ds_read_b64 v[240:241], v195 offset:24576
	ds_read_b64 v[242:243], v197 offset:24576
	s_waitcnt lgkmcnt(3)
	v_lshlrev_b32_e32 v244, 16, v232
	v_and_b32_e32 v245, 0xffff0000, v232
	v_lshlrev_b32_e32 v246, 16, v233
	v_and_b32_e32 v247, 0xffff0000, v233
	v_mul_f32_e32 v248, v142, v244
	v_mul_f32_e32 v249, v143, v245
	v_mul_f32_e32 v250, v144, v246
	v_mul_f32_e32 v251, v145, v247
	v_lshlrev_b32_e32 v244, 16, v234
	v_and_b32_e32 v245, 0xffff0000, v234
	v_lshlrev_b32_e32 v246, 16, v235
	v_and_b32_e32 v247, 0xffff0000, v235
	v_fmac_f32_e32 v248, v146, v244
	v_fmac_f32_e32 v249, v147, v245
	v_fmac_f32_e32 v250, v148, v246
	v_fmac_f32_e32 v251, v149, v247
	v_lshlrev_b32_e32 v244, 16, v236
	v_and_b32_e32 v245, 0xffff0000, v236
	v_lshlrev_b32_e32 v246, 16, v237
	v_and_b32_e32 v247, 0xffff0000, v237
	v_fmac_f32_e32 v248, v150, v244
	v_fmac_f32_e32 v249, v151, v245
	v_fmac_f32_e32 v250, v152, v246
	v_fmac_f32_e32 v251, v153, v247
	v_mul_f32_e32 v244, 0xbfb8aa3b, v248
	v_mul_f32_e32 v245, 0xbfb8aa3b, v249
	v_mul_f32_e32 v246, 0xbfb8aa3b, v250
	v_mul_f32_e32 v247, 0xbfb8aa3b, v251
	v_exp_f32_e32 v244, v244
	v_exp_f32_e32 v245, v245
	v_exp_f32_e32 v246, v246
	v_exp_f32_e32 v247, v247
	v_add_f32_e32 v244, 1.0, v244
	v_add_f32_e32 v245, 1.0, v245
	v_add_f32_e32 v246, 1.0, v246
	v_add_f32_e32 v247, 1.0, v247
	v_rcp_f32_e32 v244, v244
	v_rcp_f32_e32 v245, v245
	v_rcp_f32_e32 v246, v246
	v_rcp_f32_e32 v247, v247
	v_mul_f32_e32 v248, v248, v244
	v_mul_f32_e32 v249, v249, v245
	v_mul_f32_e32 v250, v250, v246
	v_mul_f32_e32 v251, v251, v247
	v_mul_f32_e32 v78, v78, v248
	v_mul_f32_e32 v79, v79, v249
	v_mul_f32_e32 v80, v80, v250
	v_mul_f32_e32 v81, v81, v251
	v_cvt_pk_bf16_f32 v216, v78, v79
	v_cvt_pk_bf16_f32 v217, v80, v81
	global_store_dwordx2 v[210:211], v[216:217], off
	ds_read_b64 v[232:233], v190 offset:16640
	ds_read_b64 v[234:235], v194 offset:24832
	ds_read_b64 v[236:237], v196 offset:24832
	s_waitcnt lgkmcnt(3)
	v_lshlrev_b32_e32 v244, 16, v238
	v_and_b32_e32 v245, 0xffff0000, v238
	v_lshlrev_b32_e32 v246, 16, v239
	v_and_b32_e32 v247, 0xffff0000, v239
	v_mul_f32_e32 v248, v154, v244
	v_mul_f32_e32 v249, v155, v245
	v_mul_f32_e32 v250, v156, v246
	v_mul_f32_e32 v251, v157, v247
	v_lshlrev_b32_e32 v244, 16, v240
	v_and_b32_e32 v245, 0xffff0000, v240
	v_lshlrev_b32_e32 v246, 16, v241
	v_and_b32_e32 v247, 0xffff0000, v241
	v_fmac_f32_e32 v248, v158, v244
	v_fmac_f32_e32 v249, v159, v245
	v_fmac_f32_e32 v250, v160, v246
	v_fmac_f32_e32 v251, v161, v247
	v_lshlrev_b32_e32 v244, 16, v242
	v_and_b32_e32 v245, 0xffff0000, v242
	v_lshlrev_b32_e32 v246, 16, v243
	v_and_b32_e32 v247, 0xffff0000, v243
	v_fmac_f32_e32 v248, v162, v244
	v_fmac_f32_e32 v249, v163, v245
	v_fmac_f32_e32 v250, v164, v246
	v_fmac_f32_e32 v251, v165, v247
	v_mul_f32_e32 v244, 0xbfb8aa3b, v248
	v_mul_f32_e32 v245, 0xbfb8aa3b, v249
	v_mul_f32_e32 v246, 0xbfb8aa3b, v250
	v_mul_f32_e32 v247, 0xbfb8aa3b, v251
	v_exp_f32_e32 v244, v244
	v_exp_f32_e32 v245, v245
	v_exp_f32_e32 v246, v246
	v_exp_f32_e32 v247, v247
	v_add_f32_e32 v244, 1.0, v244
	v_add_f32_e32 v245, 1.0, v245
	v_add_f32_e32 v246, 1.0, v246
	v_add_f32_e32 v247, 1.0, v247
	v_rcp_f32_e32 v244, v244
	v_rcp_f32_e32 v245, v245
	v_rcp_f32_e32 v246, v246
	v_rcp_f32_e32 v247, v247
	v_mul_f32_e32 v248, v248, v244
	v_mul_f32_e32 v249, v249, v245
	v_mul_f32_e32 v250, v250, v246
	v_mul_f32_e32 v251, v251, v247
	v_mul_f32_e32 v74, v74, v248
	v_mul_f32_e32 v75, v75, v249
	v_mul_f32_e32 v76, v76, v250
	v_mul_f32_e32 v77, v77, v251
	v_cvt_pk_bf16_f32 v218, v74, v75
	v_cvt_pk_bf16_f32 v219, v76, v77
	global_store_dwordx2 v[210:211], v[218:219], off offset:32
	ds_read_b64 v[238:239], v191 offset:16640
	ds_read_b64 v[240:241], v195 offset:24832
	ds_read_b64 v[242:243], v197 offset:24832
	s_waitcnt lgkmcnt(3)
	v_lshlrev_b32_e32 v244, 16, v232
	v_and_b32_e32 v245, 0xffff0000, v232
	v_lshlrev_b32_e32 v246, 16, v233
	v_and_b32_e32 v247, 0xffff0000, v233
	v_mul_f32_e32 v248, v166, v244
	v_mul_f32_e32 v249, v167, v245
	v_mul_f32_e32 v250, v168, v246
	v_mul_f32_e32 v251, v169, v247
	v_lshlrev_b32_e32 v244, 16, v234
	v_and_b32_e32 v245, 0xffff0000, v234
	v_lshlrev_b32_e32 v246, 16, v235
	v_and_b32_e32 v247, 0xffff0000, v235
	v_fmac_f32_e32 v248, v170, v244
	v_fmac_f32_e32 v249, v171, v245
	v_fmac_f32_e32 v250, v172, v246
	v_fmac_f32_e32 v251, v173, v247
	v_lshlrev_b32_e32 v244, 16, v236
	v_and_b32_e32 v245, 0xffff0000, v236
	v_lshlrev_b32_e32 v246, 16, v237
	v_and_b32_e32 v247, 0xffff0000, v237
	v_fmac_f32_e32 v248, v174, v244
	v_fmac_f32_e32 v249, v175, v245
	v_fmac_f32_e32 v250, v176, v246
	v_fmac_f32_e32 v251, v177, v247
	v_mul_f32_e32 v244, 0xbfb8aa3b, v248
	v_mul_f32_e32 v245, 0xbfb8aa3b, v249
	v_mul_f32_e32 v246, 0xbfb8aa3b, v250
	v_mul_f32_e32 v247, 0xbfb8aa3b, v251
	v_exp_f32_e32 v244, v244
	v_exp_f32_e32 v245, v245
	v_exp_f32_e32 v246, v246
	v_exp_f32_e32 v247, v247
	v_add_f32_e32 v244, 1.0, v244
	v_add_f32_e32 v245, 1.0, v245
	v_add_f32_e32 v246, 1.0, v246
	v_add_f32_e32 v247, 1.0, v247
	v_rcp_f32_e32 v244, v244
	v_rcp_f32_e32 v245, v245
	v_rcp_f32_e32 v246, v246
	v_rcp_f32_e32 v247, v247
	v_mul_f32_e32 v248, v248, v244
	v_mul_f32_e32 v249, v249, v245
	v_mul_f32_e32 v250, v250, v246
	v_mul_f32_e32 v251, v251, v247
	v_mul_f32_e32 v70, v70, v248
	v_mul_f32_e32 v71, v71, v249
	v_mul_f32_e32 v72, v72, v250
	v_mul_f32_e32 v73, v73, v251
	v_cvt_pk_bf16_f32 v216, v70, v71
	v_cvt_pk_bf16_f32 v217, v72, v73
	global_store_dwordx2 v[210:211], v[216:217], off offset:256
	ds_read_b64 v[232:233], v198
	ds_read_b64 v[234:235], v200
	ds_read_b64 v[236:237], v202
	s_waitcnt lgkmcnt(3)
	v_lshlrev_b32_e32 v244, 16, v238
	v_and_b32_e32 v245, 0xffff0000, v238
	v_lshlrev_b32_e32 v246, 16, v239
	v_and_b32_e32 v247, 0xffff0000, v239
	v_mul_f32_e32 v248, v178, v244
	v_mul_f32_e32 v249, v179, v245
	v_mul_f32_e32 v250, v180, v246
	v_mul_f32_e32 v251, v181, v247
	v_lshlrev_b32_e32 v244, 16, v240
	v_and_b32_e32 v245, 0xffff0000, v240
	v_lshlrev_b32_e32 v246, 16, v241
	v_and_b32_e32 v247, 0xffff0000, v241
	v_fmac_f32_e32 v248, v182, v244
	v_fmac_f32_e32 v249, v183, v245
	v_fmac_f32_e32 v250, v184, v246
	v_fmac_f32_e32 v251, v185, v247
	v_lshlrev_b32_e32 v244, 16, v242
	v_and_b32_e32 v245, 0xffff0000, v242
	v_lshlrev_b32_e32 v246, 16, v243
	v_and_b32_e32 v247, 0xffff0000, v243
	v_fmac_f32_e32 v248, v186, v244
	v_fmac_f32_e32 v249, v187, v245
	v_fmac_f32_e32 v250, v188, v246
	v_fmac_f32_e32 v251, v189, v247
	v_mul_f32_e32 v244, 0xbfb8aa3b, v248
	v_mul_f32_e32 v245, 0xbfb8aa3b, v249
	v_mul_f32_e32 v246, 0xbfb8aa3b, v250
	v_mul_f32_e32 v247, 0xbfb8aa3b, v251
	v_exp_f32_e32 v244, v244
	v_exp_f32_e32 v245, v245
	v_exp_f32_e32 v246, v246
	v_exp_f32_e32 v247, v247
	v_add_f32_e32 v244, 1.0, v244
	v_add_f32_e32 v245, 1.0, v245
	v_add_f32_e32 v246, 1.0, v246
	v_add_f32_e32 v247, 1.0, v247
	v_rcp_f32_e32 v244, v244
	v_rcp_f32_e32 v245, v245
	v_rcp_f32_e32 v246, v246
	v_rcp_f32_e32 v247, v247
	v_mul_f32_e32 v248, v248, v244
	v_mul_f32_e32 v249, v249, v245
	v_mul_f32_e32 v250, v250, v246
	v_mul_f32_e32 v251, v251, v247
	v_mul_f32_e32 v66, v66, v248
	v_mul_f32_e32 v67, v67, v249
	v_mul_f32_e32 v68, v68, v250
	v_mul_f32_e32 v69, v69, v251
	v_cvt_pk_bf16_f32 v218, v66, v67
	v_cvt_pk_bf16_f32 v219, v68, v69
	global_store_dwordx2 v[210:211], v[218:219], off offset:288
	v_lshl_add_u64 v[210:211], v[210:211], 0, s[10:11]
	ds_read_b64 v[238:239], v199
	ds_read_b64 v[240:241], v201
	ds_read_b64 v[242:243], v203
	s_waitcnt lgkmcnt(3)
	v_lshlrev_b32_e32 v244, 16, v232
	v_and_b32_e32 v245, 0xffff0000, v232
	v_lshlrev_b32_e32 v246, 16, v233
	v_and_b32_e32 v247, 0xffff0000, v233
	v_mul_f32_e32 v248, v142, v244
	v_mul_f32_e32 v249, v143, v245
	v_mul_f32_e32 v250, v144, v246
	v_mul_f32_e32 v251, v145, v247
	v_lshlrev_b32_e32 v244, 16, v234
	v_and_b32_e32 v245, 0xffff0000, v234
	v_lshlrev_b32_e32 v246, 16, v235
	v_and_b32_e32 v247, 0xffff0000, v235
	v_fmac_f32_e32 v248, v146, v244
	v_fmac_f32_e32 v249, v147, v245
	v_fmac_f32_e32 v250, v148, v246
	v_fmac_f32_e32 v251, v149, v247
	v_lshlrev_b32_e32 v244, 16, v236
	v_and_b32_e32 v245, 0xffff0000, v236
	v_lshlrev_b32_e32 v246, 16, v237
	v_and_b32_e32 v247, 0xffff0000, v237
	v_fmac_f32_e32 v248, v150, v244
	v_fmac_f32_e32 v249, v151, v245
	v_fmac_f32_e32 v250, v152, v246
	v_fmac_f32_e32 v251, v153, v247
	v_mul_f32_e32 v244, 0xbfb8aa3b, v248
	v_mul_f32_e32 v245, 0xbfb8aa3b, v249
	v_mul_f32_e32 v246, 0xbfb8aa3b, v250
	v_mul_f32_e32 v247, 0xbfb8aa3b, v251
	v_exp_f32_e32 v244, v244
	v_exp_f32_e32 v245, v245
	v_exp_f32_e32 v246, v246
	v_exp_f32_e32 v247, v247
	v_add_f32_e32 v244, 1.0, v244
	v_add_f32_e32 v245, 1.0, v245
	v_add_f32_e32 v246, 1.0, v246
	v_add_f32_e32 v247, 1.0, v247
	v_rcp_f32_e32 v244, v244
	v_rcp_f32_e32 v245, v245
	v_rcp_f32_e32 v246, v246
	v_rcp_f32_e32 v247, v247
	v_mul_f32_e32 v248, v248, v244
	v_mul_f32_e32 v249, v249, v245
	v_mul_f32_e32 v250, v250, v246
	v_mul_f32_e32 v251, v251, v247
	v_mul_f32_e32 v62, v62, v248
	v_mul_f32_e32 v63, v63, v249
	v_mul_f32_e32 v64, v64, v250
	v_mul_f32_e32 v65, v65, v251
	v_cvt_pk_bf16_f32 v216, v62, v63
	v_cvt_pk_bf16_f32 v217, v64, v65
	global_store_dwordx2 v[210:211], v[216:217], off
	ds_read_b64 v[232:233], v198 offset:256
	ds_read_b64 v[234:235], v200 offset:256
	ds_read_b64 v[236:237], v202 offset:256
	s_waitcnt lgkmcnt(3)
	v_lshlrev_b32_e32 v244, 16, v238
	v_and_b32_e32 v245, 0xffff0000, v238
	v_lshlrev_b32_e32 v246, 16, v239
	v_and_b32_e32 v247, 0xffff0000, v239
	v_mul_f32_e32 v248, v154, v244
	v_mul_f32_e32 v249, v155, v245
	v_mul_f32_e32 v250, v156, v246
	v_mul_f32_e32 v251, v157, v247
	v_lshlrev_b32_e32 v244, 16, v240
	v_and_b32_e32 v245, 0xffff0000, v240
	v_lshlrev_b32_e32 v246, 16, v241
	v_and_b32_e32 v247, 0xffff0000, v241
	v_fmac_f32_e32 v248, v158, v244
	v_fmac_f32_e32 v249, v159, v245
	v_fmac_f32_e32 v250, v160, v246
	v_fmac_f32_e32 v251, v161, v247
	v_lshlrev_b32_e32 v244, 16, v242
	v_and_b32_e32 v245, 0xffff0000, v242
	v_lshlrev_b32_e32 v246, 16, v243
	v_and_b32_e32 v247, 0xffff0000, v243
	v_fmac_f32_e32 v248, v162, v244
	v_fmac_f32_e32 v249, v163, v245
	v_fmac_f32_e32 v250, v164, v246
	v_fmac_f32_e32 v251, v165, v247
	v_mul_f32_e32 v244, 0xbfb8aa3b, v248
	v_mul_f32_e32 v245, 0xbfb8aa3b, v249
	v_mul_f32_e32 v246, 0xbfb8aa3b, v250
	v_mul_f32_e32 v247, 0xbfb8aa3b, v251
	v_exp_f32_e32 v244, v244
	v_exp_f32_e32 v245, v245
	v_exp_f32_e32 v246, v246
	v_exp_f32_e32 v247, v247
	v_add_f32_e32 v244, 1.0, v244
	v_add_f32_e32 v245, 1.0, v245
	v_add_f32_e32 v246, 1.0, v246
	v_add_f32_e32 v247, 1.0, v247
	v_rcp_f32_e32 v244, v244
	v_rcp_f32_e32 v245, v245
	v_rcp_f32_e32 v246, v246
	v_rcp_f32_e32 v247, v247
	v_mul_f32_e32 v248, v248, v244
	v_mul_f32_e32 v249, v249, v245
	v_mul_f32_e32 v250, v250, v246
	v_mul_f32_e32 v251, v251, v247
	v_mul_f32_e32 v58, v58, v248
	v_mul_f32_e32 v59, v59, v249
	v_mul_f32_e32 v60, v60, v250
	v_mul_f32_e32 v61, v61, v251
	v_cvt_pk_bf16_f32 v218, v58, v59
	v_cvt_pk_bf16_f32 v219, v60, v61
	global_store_dwordx2 v[210:211], v[218:219], off offset:32
	ds_read_b64 v[238:239], v199 offset:256
	ds_read_b64 v[240:241], v201 offset:256
	ds_read_b64 v[242:243], v203 offset:256
	s_waitcnt lgkmcnt(3)
	v_lshlrev_b32_e32 v244, 16, v232
	v_and_b32_e32 v245, 0xffff0000, v232
	v_lshlrev_b32_e32 v246, 16, v233
	v_and_b32_e32 v247, 0xffff0000, v233
	v_mul_f32_e32 v248, v166, v244
	v_mul_f32_e32 v249, v167, v245
	v_mul_f32_e32 v250, v168, v246
	v_mul_f32_e32 v251, v169, v247
	v_lshlrev_b32_e32 v244, 16, v234
	v_and_b32_e32 v245, 0xffff0000, v234
	v_lshlrev_b32_e32 v246, 16, v235
	v_and_b32_e32 v247, 0xffff0000, v235
	v_fmac_f32_e32 v248, v170, v244
	v_fmac_f32_e32 v249, v171, v245
	v_fmac_f32_e32 v250, v172, v246
	v_fmac_f32_e32 v251, v173, v247
	v_lshlrev_b32_e32 v244, 16, v236
	v_and_b32_e32 v245, 0xffff0000, v236
	v_lshlrev_b32_e32 v246, 16, v237
	v_and_b32_e32 v247, 0xffff0000, v237
	v_fmac_f32_e32 v248, v174, v244
	v_fmac_f32_e32 v249, v175, v245
	v_fmac_f32_e32 v250, v176, v246
	v_fmac_f32_e32 v251, v177, v247
	v_mul_f32_e32 v244, 0xbfb8aa3b, v248
	v_mul_f32_e32 v245, 0xbfb8aa3b, v249
	v_mul_f32_e32 v246, 0xbfb8aa3b, v250
	v_mul_f32_e32 v247, 0xbfb8aa3b, v251
	v_exp_f32_e32 v244, v244
	v_exp_f32_e32 v245, v245
	v_exp_f32_e32 v246, v246
	v_exp_f32_e32 v247, v247
	v_add_f32_e32 v244, 1.0, v244
	v_add_f32_e32 v245, 1.0, v245
	v_add_f32_e32 v246, 1.0, v246
	v_add_f32_e32 v247, 1.0, v247
	v_rcp_f32_e32 v244, v244
	v_rcp_f32_e32 v245, v245
	v_rcp_f32_e32 v246, v246
	v_rcp_f32_e32 v247, v247
	v_mul_f32_e32 v248, v248, v244
	v_mul_f32_e32 v249, v249, v245
	v_mul_f32_e32 v250, v250, v246
	v_mul_f32_e32 v251, v251, v247
	v_mul_f32_e32 v54, v54, v248
	v_mul_f32_e32 v55, v55, v249
	v_mul_f32_e32 v56, v56, v250
	v_mul_f32_e32 v57, v57, v251
	v_cvt_pk_bf16_f32 v216, v54, v55
	v_cvt_pk_bf16_f32 v217, v56, v57
	global_store_dwordx2 v[210:211], v[216:217], off offset:256
	ds_read_b64 v[232:233], v198 offset:8192
	ds_read_b64 v[234:235], v200 offset:8192
	ds_read_b64 v[236:237], v202 offset:8192
	s_waitcnt lgkmcnt(3)
	v_lshlrev_b32_e32 v244, 16, v238
	v_and_b32_e32 v245, 0xffff0000, v238
	v_lshlrev_b32_e32 v246, 16, v239
	v_and_b32_e32 v247, 0xffff0000, v239
	v_mul_f32_e32 v248, v178, v244
	v_mul_f32_e32 v249, v179, v245
	v_mul_f32_e32 v250, v180, v246
	v_mul_f32_e32 v251, v181, v247
	v_lshlrev_b32_e32 v244, 16, v240
	v_and_b32_e32 v245, 0xffff0000, v240
	v_lshlrev_b32_e32 v246, 16, v241
	v_and_b32_e32 v247, 0xffff0000, v241
	v_fmac_f32_e32 v248, v182, v244
	v_fmac_f32_e32 v249, v183, v245
	v_fmac_f32_e32 v250, v184, v246
	v_fmac_f32_e32 v251, v185, v247
	v_lshlrev_b32_e32 v244, 16, v242
	v_and_b32_e32 v245, 0xffff0000, v242
	v_lshlrev_b32_e32 v246, 16, v243
	v_and_b32_e32 v247, 0xffff0000, v243
	v_fmac_f32_e32 v248, v186, v244
	v_fmac_f32_e32 v249, v187, v245
	v_fmac_f32_e32 v250, v188, v246
	v_fmac_f32_e32 v251, v189, v247
	v_mul_f32_e32 v244, 0xbfb8aa3b, v248
	v_mul_f32_e32 v245, 0xbfb8aa3b, v249
	v_mul_f32_e32 v246, 0xbfb8aa3b, v250
	v_mul_f32_e32 v247, 0xbfb8aa3b, v251
	v_exp_f32_e32 v244, v244
	v_exp_f32_e32 v245, v245
	v_exp_f32_e32 v246, v246
	v_exp_f32_e32 v247, v247
	v_add_f32_e32 v244, 1.0, v244
	v_add_f32_e32 v245, 1.0, v245
	v_add_f32_e32 v246, 1.0, v246
	v_add_f32_e32 v247, 1.0, v247
	v_rcp_f32_e32 v244, v244
	v_rcp_f32_e32 v245, v245
	v_rcp_f32_e32 v246, v246
	v_rcp_f32_e32 v247, v247
	v_mul_f32_e32 v248, v248, v244
	v_mul_f32_e32 v249, v249, v245
	v_mul_f32_e32 v250, v250, v246
	v_mul_f32_e32 v251, v251, v247
	v_mul_f32_e32 v50, v50, v248
	v_mul_f32_e32 v51, v51, v249
	v_mul_f32_e32 v52, v52, v250
	v_mul_f32_e32 v53, v53, v251
	v_cvt_pk_bf16_f32 v218, v50, v51
	v_cvt_pk_bf16_f32 v219, v52, v53
	global_store_dwordx2 v[210:211], v[218:219], off offset:288
	v_lshl_add_u64 v[210:211], v[210:211], 0, s[72:73]
	ds_read_b64 v[238:239], v199 offset:8192
	ds_read_b64 v[240:241], v201 offset:8192
	ds_read_b64 v[242:243], v203 offset:8192
	s_waitcnt lgkmcnt(3)
	v_lshlrev_b32_e32 v244, 16, v232
	v_and_b32_e32 v245, 0xffff0000, v232
	v_lshlrev_b32_e32 v246, 16, v233
	v_and_b32_e32 v247, 0xffff0000, v233
	v_mul_f32_e32 v248, v142, v244
	v_mul_f32_e32 v249, v143, v245
	v_mul_f32_e32 v250, v144, v246
	v_mul_f32_e32 v251, v145, v247
	v_lshlrev_b32_e32 v244, 16, v234
	v_and_b32_e32 v245, 0xffff0000, v234
	v_lshlrev_b32_e32 v246, 16, v235
	v_and_b32_e32 v247, 0xffff0000, v235
	v_fmac_f32_e32 v248, v146, v244
	v_fmac_f32_e32 v249, v147, v245
	v_fmac_f32_e32 v250, v148, v246
	v_fmac_f32_e32 v251, v149, v247
	v_lshlrev_b32_e32 v244, 16, v236
	v_and_b32_e32 v245, 0xffff0000, v236
	v_lshlrev_b32_e32 v246, 16, v237
	v_and_b32_e32 v247, 0xffff0000, v237
	v_fmac_f32_e32 v248, v150, v244
	v_fmac_f32_e32 v249, v151, v245
	v_fmac_f32_e32 v250, v152, v246
	v_fmac_f32_e32 v251, v153, v247
	v_mul_f32_e32 v244, 0xbfb8aa3b, v248
	v_mul_f32_e32 v245, 0xbfb8aa3b, v249
	v_mul_f32_e32 v246, 0xbfb8aa3b, v250
	v_mul_f32_e32 v247, 0xbfb8aa3b, v251
	v_exp_f32_e32 v244, v244
	v_exp_f32_e32 v245, v245
	v_exp_f32_e32 v246, v246
	v_exp_f32_e32 v247, v247
	v_add_f32_e32 v244, 1.0, v244
	v_add_f32_e32 v245, 1.0, v245
	v_add_f32_e32 v246, 1.0, v246
	v_add_f32_e32 v247, 1.0, v247
	v_rcp_f32_e32 v244, v244
	v_rcp_f32_e32 v245, v245
	v_rcp_f32_e32 v246, v246
	v_rcp_f32_e32 v247, v247
	v_mul_f32_e32 v248, v248, v244
	v_mul_f32_e32 v249, v249, v245
	v_mul_f32_e32 v250, v250, v246
	v_mul_f32_e32 v251, v251, v247
	v_mul_f32_e32 v46, v46, v248
	v_mul_f32_e32 v47, v47, v249
	v_mul_f32_e32 v48, v48, v250
	v_mul_f32_e32 v49, v49, v251
	v_cvt_pk_bf16_f32 v216, v46, v47
	v_cvt_pk_bf16_f32 v217, v48, v49
	global_store_dwordx2 v[210:211], v[216:217], off
	ds_read_b64 v[232:233], v198 offset:8448
	ds_read_b64 v[234:235], v200 offset:8448
	ds_read_b64 v[236:237], v202 offset:8448
	s_waitcnt lgkmcnt(3)
	v_lshlrev_b32_e32 v244, 16, v238
	v_and_b32_e32 v245, 0xffff0000, v238
	v_lshlrev_b32_e32 v246, 16, v239
	v_and_b32_e32 v247, 0xffff0000, v239
	v_mul_f32_e32 v248, v154, v244
	v_mul_f32_e32 v249, v155, v245
	v_mul_f32_e32 v250, v156, v246
	v_mul_f32_e32 v251, v157, v247
	v_lshlrev_b32_e32 v244, 16, v240
	v_and_b32_e32 v245, 0xffff0000, v240
	v_lshlrev_b32_e32 v246, 16, v241
	v_and_b32_e32 v247, 0xffff0000, v241
	v_fmac_f32_e32 v248, v158, v244
	v_fmac_f32_e32 v249, v159, v245
	v_fmac_f32_e32 v250, v160, v246
	v_fmac_f32_e32 v251, v161, v247
	v_lshlrev_b32_e32 v244, 16, v242
	v_and_b32_e32 v245, 0xffff0000, v242
	v_lshlrev_b32_e32 v246, 16, v243
	v_and_b32_e32 v247, 0xffff0000, v243
	v_fmac_f32_e32 v248, v162, v244
	v_fmac_f32_e32 v249, v163, v245
	v_fmac_f32_e32 v250, v164, v246
	v_fmac_f32_e32 v251, v165, v247
	v_mul_f32_e32 v244, 0xbfb8aa3b, v248
	v_mul_f32_e32 v245, 0xbfb8aa3b, v249
	v_mul_f32_e32 v246, 0xbfb8aa3b, v250
	v_mul_f32_e32 v247, 0xbfb8aa3b, v251
	v_exp_f32_e32 v244, v244
	v_exp_f32_e32 v245, v245
	v_exp_f32_e32 v246, v246
	v_exp_f32_e32 v247, v247
	v_add_f32_e32 v244, 1.0, v244
	v_add_f32_e32 v245, 1.0, v245
	v_add_f32_e32 v246, 1.0, v246
	v_add_f32_e32 v247, 1.0, v247
	v_rcp_f32_e32 v244, v244
	v_rcp_f32_e32 v245, v245
	v_rcp_f32_e32 v246, v246
	v_rcp_f32_e32 v247, v247
	v_mul_f32_e32 v248, v248, v244
	v_mul_f32_e32 v249, v249, v245
	v_mul_f32_e32 v250, v250, v246
	v_mul_f32_e32 v251, v251, v247
	v_mul_f32_e32 v42, v42, v248
	v_mul_f32_e32 v43, v43, v249
	v_mul_f32_e32 v44, v44, v250
	v_mul_f32_e32 v45, v45, v251
	v_cvt_pk_bf16_f32 v218, v42, v43
	v_cvt_pk_bf16_f32 v219, v44, v45
	global_store_dwordx2 v[210:211], v[218:219], off offset:32
	ds_read_b64 v[238:239], v199 offset:8448
	ds_read_b64 v[240:241], v201 offset:8448
	ds_read_b64 v[242:243], v203 offset:8448
	s_waitcnt lgkmcnt(3)
	v_lshlrev_b32_e32 v244, 16, v232
	v_and_b32_e32 v245, 0xffff0000, v232
	v_lshlrev_b32_e32 v246, 16, v233
	v_and_b32_e32 v247, 0xffff0000, v233
	v_mul_f32_e32 v248, v166, v244
	v_mul_f32_e32 v249, v167, v245
	v_mul_f32_e32 v250, v168, v246
	v_mul_f32_e32 v251, v169, v247
	v_lshlrev_b32_e32 v244, 16, v234
	v_and_b32_e32 v245, 0xffff0000, v234
	v_lshlrev_b32_e32 v246, 16, v235
	v_and_b32_e32 v247, 0xffff0000, v235
	v_fmac_f32_e32 v248, v170, v244
	v_fmac_f32_e32 v249, v171, v245
	v_fmac_f32_e32 v250, v172, v246
	v_fmac_f32_e32 v251, v173, v247
	v_lshlrev_b32_e32 v244, 16, v236
	v_and_b32_e32 v245, 0xffff0000, v236
	v_lshlrev_b32_e32 v246, 16, v237
	v_and_b32_e32 v247, 0xffff0000, v237
	v_fmac_f32_e32 v248, v174, v244
	v_fmac_f32_e32 v249, v175, v245
	v_fmac_f32_e32 v250, v176, v246
	v_fmac_f32_e32 v251, v177, v247
	v_mul_f32_e32 v244, 0xbfb8aa3b, v248
	v_mul_f32_e32 v245, 0xbfb8aa3b, v249
	v_mul_f32_e32 v246, 0xbfb8aa3b, v250
	v_mul_f32_e32 v247, 0xbfb8aa3b, v251
	v_exp_f32_e32 v244, v244
	v_exp_f32_e32 v245, v245
	v_exp_f32_e32 v246, v246
	v_exp_f32_e32 v247, v247
	v_add_f32_e32 v244, 1.0, v244
	v_add_f32_e32 v245, 1.0, v245
	v_add_f32_e32 v246, 1.0, v246
	v_add_f32_e32 v247, 1.0, v247
	v_rcp_f32_e32 v244, v244
	v_rcp_f32_e32 v245, v245
	v_rcp_f32_e32 v246, v246
	v_rcp_f32_e32 v247, v247
	v_mul_f32_e32 v248, v248, v244
	v_mul_f32_e32 v249, v249, v245
	v_mul_f32_e32 v250, v250, v246
	v_mul_f32_e32 v251, v251, v247
	v_mul_f32_e32 v38, v38, v248
	v_mul_f32_e32 v39, v39, v249
	v_mul_f32_e32 v40, v40, v250
	v_mul_f32_e32 v41, v41, v251
	v_cvt_pk_bf16_f32 v216, v38, v39
	v_cvt_pk_bf16_f32 v217, v40, v41
	global_store_dwordx2 v[210:211], v[216:217], off offset:256
	ds_read_b64 v[232:233], v198 offset:16384
	ds_read_b64 v[234:235], v200 offset:16384
	ds_read_b64 v[236:237], v202 offset:16384
	s_waitcnt lgkmcnt(3)
	v_lshlrev_b32_e32 v244, 16, v238
	v_and_b32_e32 v245, 0xffff0000, v238
	v_lshlrev_b32_e32 v246, 16, v239
	v_and_b32_e32 v247, 0xffff0000, v239
	v_mul_f32_e32 v248, v178, v244
	v_mul_f32_e32 v249, v179, v245
	v_mul_f32_e32 v250, v180, v246
	v_mul_f32_e32 v251, v181, v247
	v_lshlrev_b32_e32 v244, 16, v240
	v_and_b32_e32 v245, 0xffff0000, v240
	v_lshlrev_b32_e32 v246, 16, v241
	v_and_b32_e32 v247, 0xffff0000, v241
	v_fmac_f32_e32 v248, v182, v244
	v_fmac_f32_e32 v249, v183, v245
	v_fmac_f32_e32 v250, v184, v246
	v_fmac_f32_e32 v251, v185, v247
	v_lshlrev_b32_e32 v244, 16, v242
	v_and_b32_e32 v245, 0xffff0000, v242
	v_lshlrev_b32_e32 v246, 16, v243
	v_and_b32_e32 v247, 0xffff0000, v243
	v_fmac_f32_e32 v248, v186, v244
	v_fmac_f32_e32 v249, v187, v245
	v_fmac_f32_e32 v250, v188, v246
	v_fmac_f32_e32 v251, v189, v247
	v_mul_f32_e32 v244, 0xbfb8aa3b, v248
	v_mul_f32_e32 v245, 0xbfb8aa3b, v249
	v_mul_f32_e32 v246, 0xbfb8aa3b, v250
	v_mul_f32_e32 v247, 0xbfb8aa3b, v251
	v_exp_f32_e32 v244, v244
	v_exp_f32_e32 v245, v245
	v_exp_f32_e32 v246, v246
	v_exp_f32_e32 v247, v247
	v_add_f32_e32 v244, 1.0, v244
	v_add_f32_e32 v245, 1.0, v245
	v_add_f32_e32 v246, 1.0, v246
	v_add_f32_e32 v247, 1.0, v247
	v_rcp_f32_e32 v244, v244
	v_rcp_f32_e32 v245, v245
	v_rcp_f32_e32 v246, v246
	v_rcp_f32_e32 v247, v247
	v_mul_f32_e32 v248, v248, v244
	v_mul_f32_e32 v249, v249, v245
	v_mul_f32_e32 v250, v250, v246
	v_mul_f32_e32 v251, v251, v247
	v_mul_f32_e32 v34, v34, v248
	v_mul_f32_e32 v35, v35, v249
	v_mul_f32_e32 v36, v36, v250
	v_mul_f32_e32 v37, v37, v251
	v_cvt_pk_bf16_f32 v218, v34, v35
	v_cvt_pk_bf16_f32 v219, v36, v37
	global_store_dwordx2 v[210:211], v[218:219], off offset:288
	v_lshl_add_u64 v[210:211], v[210:211], 0, s[72:73]
	ds_read_b64 v[238:239], v199 offset:16384
	ds_read_b64 v[240:241], v201 offset:16384
	ds_read_b64 v[242:243], v203 offset:16384
	s_waitcnt lgkmcnt(3)
	v_lshlrev_b32_e32 v244, 16, v232
	v_and_b32_e32 v245, 0xffff0000, v232
	v_lshlrev_b32_e32 v246, 16, v233
	v_and_b32_e32 v247, 0xffff0000, v233
	v_mul_f32_e32 v248, v142, v244
	v_mul_f32_e32 v249, v143, v245
	v_mul_f32_e32 v250, v144, v246
	v_mul_f32_e32 v251, v145, v247
	v_lshlrev_b32_e32 v244, 16, v234
	v_and_b32_e32 v245, 0xffff0000, v234
	v_lshlrev_b32_e32 v246, 16, v235
	v_and_b32_e32 v247, 0xffff0000, v235
	v_fmac_f32_e32 v248, v146, v244
	v_fmac_f32_e32 v249, v147, v245
	v_fmac_f32_e32 v250, v148, v246
	v_fmac_f32_e32 v251, v149, v247
	v_lshlrev_b32_e32 v244, 16, v236
	v_and_b32_e32 v245, 0xffff0000, v236
	v_lshlrev_b32_e32 v246, 16, v237
	v_and_b32_e32 v247, 0xffff0000, v237
	v_fmac_f32_e32 v248, v150, v244
	v_fmac_f32_e32 v249, v151, v245
	v_fmac_f32_e32 v250, v152, v246
	v_fmac_f32_e32 v251, v153, v247
	v_mul_f32_e32 v244, 0xbfb8aa3b, v248
	v_mul_f32_e32 v245, 0xbfb8aa3b, v249
	v_mul_f32_e32 v246, 0xbfb8aa3b, v250
	v_mul_f32_e32 v247, 0xbfb8aa3b, v251
	v_exp_f32_e32 v244, v244
	v_exp_f32_e32 v245, v245
	v_exp_f32_e32 v246, v246
	v_exp_f32_e32 v247, v247
	v_add_f32_e32 v244, 1.0, v244
	v_add_f32_e32 v245, 1.0, v245
	v_add_f32_e32 v246, 1.0, v246
	v_add_f32_e32 v247, 1.0, v247
	v_rcp_f32_e32 v244, v244
	v_rcp_f32_e32 v245, v245
	v_rcp_f32_e32 v246, v246
	v_rcp_f32_e32 v247, v247
	v_mul_f32_e32 v248, v248, v244
	v_mul_f32_e32 v249, v249, v245
	v_mul_f32_e32 v250, v250, v246
	v_mul_f32_e32 v251, v251, v247
	v_mul_f32_e32 v30, v30, v248
	v_mul_f32_e32 v31, v31, v249
	v_mul_f32_e32 v32, v32, v250
	v_mul_f32_e32 v33, v33, v251
	v_cvt_pk_bf16_f32 v216, v30, v31
	v_cvt_pk_bf16_f32 v217, v32, v33
	global_store_dwordx2 v[210:211], v[216:217], off
	ds_read_b64 v[232:233], v198 offset:16640
	ds_read_b64 v[234:235], v200 offset:16640
	ds_read_b64 v[236:237], v202 offset:16640
	s_waitcnt lgkmcnt(3)
	v_lshlrev_b32_e32 v244, 16, v238
	v_and_b32_e32 v245, 0xffff0000, v238
	v_lshlrev_b32_e32 v246, 16, v239
	v_and_b32_e32 v247, 0xffff0000, v239
	v_mul_f32_e32 v248, v154, v244
	v_mul_f32_e32 v249, v155, v245
	v_mul_f32_e32 v250, v156, v246
	v_mul_f32_e32 v251, v157, v247
	v_lshlrev_b32_e32 v244, 16, v240
	v_and_b32_e32 v245, 0xffff0000, v240
	v_lshlrev_b32_e32 v246, 16, v241
	v_and_b32_e32 v247, 0xffff0000, v241
	v_fmac_f32_e32 v248, v158, v244
	v_fmac_f32_e32 v249, v159, v245
	v_fmac_f32_e32 v250, v160, v246
	v_fmac_f32_e32 v251, v161, v247
	v_lshlrev_b32_e32 v244, 16, v242
	v_and_b32_e32 v245, 0xffff0000, v242
	v_lshlrev_b32_e32 v246, 16, v243
	v_and_b32_e32 v247, 0xffff0000, v243
	v_fmac_f32_e32 v248, v162, v244
	v_fmac_f32_e32 v249, v163, v245
	v_fmac_f32_e32 v250, v164, v246
	v_fmac_f32_e32 v251, v165, v247
	v_mul_f32_e32 v244, 0xbfb8aa3b, v248
	v_mul_f32_e32 v245, 0xbfb8aa3b, v249
	v_mul_f32_e32 v246, 0xbfb8aa3b, v250
	v_mul_f32_e32 v247, 0xbfb8aa3b, v251
	v_exp_f32_e32 v244, v244
	v_exp_f32_e32 v245, v245
	v_exp_f32_e32 v246, v246
	v_exp_f32_e32 v247, v247
	v_add_f32_e32 v244, 1.0, v244
	v_add_f32_e32 v245, 1.0, v245
	v_add_f32_e32 v246, 1.0, v246
	v_add_f32_e32 v247, 1.0, v247
	v_rcp_f32_e32 v244, v244
	v_rcp_f32_e32 v245, v245
	v_rcp_f32_e32 v246, v246
	v_rcp_f32_e32 v247, v247
	v_mul_f32_e32 v248, v248, v244
	v_mul_f32_e32 v249, v249, v245
	v_mul_f32_e32 v250, v250, v246
	v_mul_f32_e32 v251, v251, v247
	v_mul_f32_e32 v26, v26, v248
	v_mul_f32_e32 v27, v27, v249
	v_mul_f32_e32 v28, v28, v250
	v_mul_f32_e32 v29, v29, v251
	v_cvt_pk_bf16_f32 v218, v26, v27
	v_cvt_pk_bf16_f32 v219, v28, v29
	global_store_dwordx2 v[210:211], v[218:219], off offset:32
	ds_read_b64 v[238:239], v199 offset:16640
	ds_read_b64 v[240:241], v201 offset:16640
	ds_read_b64 v[242:243], v203 offset:16640
	s_waitcnt lgkmcnt(3)
	v_lshlrev_b32_e32 v244, 16, v232
	v_and_b32_e32 v245, 0xffff0000, v232
	v_lshlrev_b32_e32 v246, 16, v233
	v_and_b32_e32 v247, 0xffff0000, v233
	v_mul_f32_e32 v248, v166, v244
	v_mul_f32_e32 v249, v167, v245
	v_mul_f32_e32 v250, v168, v246
	v_mul_f32_e32 v251, v169, v247
	v_lshlrev_b32_e32 v244, 16, v234
	v_and_b32_e32 v245, 0xffff0000, v234
	v_lshlrev_b32_e32 v246, 16, v235
	v_and_b32_e32 v247, 0xffff0000, v235
	v_fmac_f32_e32 v248, v170, v244
	v_fmac_f32_e32 v249, v171, v245
	v_fmac_f32_e32 v250, v172, v246
	v_fmac_f32_e32 v251, v173, v247
	v_lshlrev_b32_e32 v244, 16, v236
	v_and_b32_e32 v245, 0xffff0000, v236
	v_lshlrev_b32_e32 v246, 16, v237
	v_and_b32_e32 v247, 0xffff0000, v237
	v_fmac_f32_e32 v248, v174, v244
	v_fmac_f32_e32 v249, v175, v245
	v_fmac_f32_e32 v250, v176, v246
	v_fmac_f32_e32 v251, v177, v247
	v_mul_f32_e32 v244, 0xbfb8aa3b, v248
	v_mul_f32_e32 v245, 0xbfb8aa3b, v249
	v_mul_f32_e32 v246, 0xbfb8aa3b, v250
	v_mul_f32_e32 v247, 0xbfb8aa3b, v251
	v_exp_f32_e32 v244, v244
	v_exp_f32_e32 v245, v245
	v_exp_f32_e32 v246, v246
	v_exp_f32_e32 v247, v247
	v_add_f32_e32 v244, 1.0, v244
	v_add_f32_e32 v245, 1.0, v245
	v_add_f32_e32 v246, 1.0, v246
	v_add_f32_e32 v247, 1.0, v247
	v_rcp_f32_e32 v244, v244
	v_rcp_f32_e32 v245, v245
	v_rcp_f32_e32 v246, v246
	v_rcp_f32_e32 v247, v247
	v_mul_f32_e32 v248, v248, v244
	v_mul_f32_e32 v249, v249, v245
	v_mul_f32_e32 v250, v250, v246
	v_mul_f32_e32 v251, v251, v247
	v_mul_f32_e32 v22, v22, v248
	v_mul_f32_e32 v23, v23, v249
	v_mul_f32_e32 v24, v24, v250
	v_mul_f32_e32 v25, v25, v251
	v_cvt_pk_bf16_f32 v216, v22, v23
	v_cvt_pk_bf16_f32 v217, v24, v25
	global_store_dwordx2 v[210:211], v[216:217], off offset:256
	ds_read_b64 v[232:233], v198 offset:24576
	ds_read_b64 v[234:235], v200 offset:24576
	ds_read_b64 v[236:237], v204
	s_waitcnt lgkmcnt(3)
	v_lshlrev_b32_e32 v244, 16, v238
	v_and_b32_e32 v245, 0xffff0000, v238
	v_lshlrev_b32_e32 v246, 16, v239
	v_and_b32_e32 v247, 0xffff0000, v239
	v_mul_f32_e32 v248, v178, v244
	v_mul_f32_e32 v249, v179, v245
	v_mul_f32_e32 v250, v180, v246
	v_mul_f32_e32 v251, v181, v247
	v_lshlrev_b32_e32 v244, 16, v240
	v_and_b32_e32 v245, 0xffff0000, v240
	v_lshlrev_b32_e32 v246, 16, v241
	v_and_b32_e32 v247, 0xffff0000, v241
	v_fmac_f32_e32 v248, v182, v244
	v_fmac_f32_e32 v249, v183, v245
	v_fmac_f32_e32 v250, v184, v246
	v_fmac_f32_e32 v251, v185, v247
	v_lshlrev_b32_e32 v244, 16, v242
	v_and_b32_e32 v245, 0xffff0000, v242
	v_lshlrev_b32_e32 v246, 16, v243
	v_and_b32_e32 v247, 0xffff0000, v243
	v_fmac_f32_e32 v248, v186, v244
	v_fmac_f32_e32 v249, v187, v245
	v_fmac_f32_e32 v250, v188, v246
	v_fmac_f32_e32 v251, v189, v247
	v_mul_f32_e32 v244, 0xbfb8aa3b, v248
	v_mul_f32_e32 v245, 0xbfb8aa3b, v249
	v_mul_f32_e32 v246, 0xbfb8aa3b, v250
	v_mul_f32_e32 v247, 0xbfb8aa3b, v251
	v_exp_f32_e32 v244, v244
	v_exp_f32_e32 v245, v245
	v_exp_f32_e32 v246, v246
	v_exp_f32_e32 v247, v247
	v_add_f32_e32 v244, 1.0, v244
	v_add_f32_e32 v245, 1.0, v245
	v_add_f32_e32 v246, 1.0, v246
	v_add_f32_e32 v247, 1.0, v247
	v_rcp_f32_e32 v244, v244
	v_rcp_f32_e32 v245, v245
	v_rcp_f32_e32 v246, v246
	v_rcp_f32_e32 v247, v247
	v_mul_f32_e32 v248, v248, v244
	v_mul_f32_e32 v249, v249, v245
	v_mul_f32_e32 v250, v250, v246
	v_mul_f32_e32 v251, v251, v247
	v_mul_f32_e32 v18, v18, v248
	v_mul_f32_e32 v19, v19, v249
	v_mul_f32_e32 v20, v20, v250
	v_mul_f32_e32 v21, v21, v251
	v_cvt_pk_bf16_f32 v218, v18, v19
	v_cvt_pk_bf16_f32 v219, v20, v21
	global_store_dwordx2 v[210:211], v[218:219], off offset:288
	v_lshl_add_u64 v[210:211], v[210:211], 0, s[72:73]
	ds_read_b64 v[238:239], v199 offset:24576
	ds_read_b64 v[240:241], v201 offset:24576
	ds_read_b64 v[242:243], v205
	s_waitcnt lgkmcnt(3)
	v_lshlrev_b32_e32 v244, 16, v232
	v_and_b32_e32 v245, 0xffff0000, v232
	v_lshlrev_b32_e32 v246, 16, v233
	v_and_b32_e32 v247, 0xffff0000, v233
	v_mul_f32_e32 v248, v142, v244
	v_mul_f32_e32 v249, v143, v245
	v_mul_f32_e32 v250, v144, v246
	v_mul_f32_e32 v251, v145, v247
	v_lshlrev_b32_e32 v244, 16, v234
	v_and_b32_e32 v245, 0xffff0000, v234
	v_lshlrev_b32_e32 v246, 16, v235
	v_and_b32_e32 v247, 0xffff0000, v235
	v_fmac_f32_e32 v248, v146, v244
	v_fmac_f32_e32 v249, v147, v245
	v_fmac_f32_e32 v250, v148, v246
	v_fmac_f32_e32 v251, v149, v247
	v_lshlrev_b32_e32 v244, 16, v236
	v_and_b32_e32 v245, 0xffff0000, v236
	v_lshlrev_b32_e32 v246, 16, v237
	v_and_b32_e32 v247, 0xffff0000, v237
	v_fmac_f32_e32 v248, v150, v244
	v_fmac_f32_e32 v249, v151, v245
	v_fmac_f32_e32 v250, v152, v246
	v_fmac_f32_e32 v251, v153, v247
	v_mul_f32_e32 v244, 0xbfb8aa3b, v248
	v_mul_f32_e32 v245, 0xbfb8aa3b, v249
	v_mul_f32_e32 v246, 0xbfb8aa3b, v250
	v_mul_f32_e32 v247, 0xbfb8aa3b, v251
	v_exp_f32_e32 v244, v244
	v_exp_f32_e32 v245, v245
	v_exp_f32_e32 v246, v246
	v_exp_f32_e32 v247, v247
	v_add_f32_e32 v244, 1.0, v244
	v_add_f32_e32 v245, 1.0, v245
	v_add_f32_e32 v246, 1.0, v246
	v_add_f32_e32 v247, 1.0, v247
	v_rcp_f32_e32 v244, v244
	v_rcp_f32_e32 v245, v245
	v_rcp_f32_e32 v246, v246
	v_rcp_f32_e32 v247, v247
	v_mul_f32_e32 v248, v248, v244
	v_mul_f32_e32 v249, v249, v245
	v_mul_f32_e32 v250, v250, v246
	v_mul_f32_e32 v251, v251, v247
	v_mul_f32_e32 v14, v14, v248
	v_mul_f32_e32 v15, v15, v249
	v_mul_f32_e32 v16, v16, v250
	v_mul_f32_e32 v17, v17, v251
	v_cvt_pk_bf16_f32 v216, v14, v15
	v_cvt_pk_bf16_f32 v217, v16, v17
	global_store_dwordx2 v[210:211], v[216:217], off
	ds_read_b64 v[232:233], v198 offset:24832
	ds_read_b64 v[234:235], v200 offset:24832
	ds_read_b64 v[236:237], v204 offset:256
	s_waitcnt lgkmcnt(3)
	v_lshlrev_b32_e32 v244, 16, v238
	v_and_b32_e32 v245, 0xffff0000, v238
	v_lshlrev_b32_e32 v246, 16, v239
	v_and_b32_e32 v247, 0xffff0000, v239
	v_mul_f32_e32 v248, v154, v244
	v_mul_f32_e32 v249, v155, v245
	v_mul_f32_e32 v250, v156, v246
	v_mul_f32_e32 v251, v157, v247
	v_lshlrev_b32_e32 v244, 16, v240
	v_and_b32_e32 v245, 0xffff0000, v240
	v_lshlrev_b32_e32 v246, 16, v241
	v_and_b32_e32 v247, 0xffff0000, v241
	v_fmac_f32_e32 v248, v158, v244
	v_fmac_f32_e32 v249, v159, v245
	v_fmac_f32_e32 v250, v160, v246
	v_fmac_f32_e32 v251, v161, v247
	v_lshlrev_b32_e32 v244, 16, v242
	v_and_b32_e32 v245, 0xffff0000, v242
	v_lshlrev_b32_e32 v246, 16, v243
	v_and_b32_e32 v247, 0xffff0000, v243
	v_fmac_f32_e32 v248, v162, v244
	v_fmac_f32_e32 v249, v163, v245
	v_fmac_f32_e32 v250, v164, v246
	v_fmac_f32_e32 v251, v165, v247
	v_mul_f32_e32 v244, 0xbfb8aa3b, v248
	v_mul_f32_e32 v245, 0xbfb8aa3b, v249
	v_mul_f32_e32 v246, 0xbfb8aa3b, v250
	v_mul_f32_e32 v247, 0xbfb8aa3b, v251
	v_exp_f32_e32 v244, v244
	v_exp_f32_e32 v245, v245
	v_exp_f32_e32 v246, v246
	v_exp_f32_e32 v247, v247
	v_add_f32_e32 v244, 1.0, v244
	v_add_f32_e32 v245, 1.0, v245
	v_add_f32_e32 v246, 1.0, v246
	v_add_f32_e32 v247, 1.0, v247
	v_rcp_f32_e32 v244, v244
	v_rcp_f32_e32 v245, v245
	v_rcp_f32_e32 v246, v246
	v_rcp_f32_e32 v247, v247
	v_mul_f32_e32 v248, v248, v244
	v_mul_f32_e32 v249, v249, v245
	v_mul_f32_e32 v250, v250, v246
	v_mul_f32_e32 v251, v251, v247
	v_mul_f32_e32 v10, v10, v248
	v_mul_f32_e32 v11, v11, v249
	v_mul_f32_e32 v12, v12, v250
	v_mul_f32_e32 v13, v13, v251
	v_cvt_pk_bf16_f32 v218, v10, v11
	v_cvt_pk_bf16_f32 v219, v12, v13
	global_store_dwordx2 v[210:211], v[218:219], off offset:32
	ds_read_b64 v[238:239], v199 offset:24832
	ds_read_b64 v[240:241], v201 offset:24832
	ds_read_b64 v[242:243], v205 offset:256
	s_waitcnt lgkmcnt(3)
	v_lshlrev_b32_e32 v244, 16, v232
	v_and_b32_e32 v245, 0xffff0000, v232
	v_lshlrev_b32_e32 v246, 16, v233
	v_and_b32_e32 v247, 0xffff0000, v233
	v_mul_f32_e32 v248, v166, v244
	v_mul_f32_e32 v249, v167, v245
	v_mul_f32_e32 v250, v168, v246
	v_mul_f32_e32 v251, v169, v247
	v_lshlrev_b32_e32 v244, 16, v234
	v_and_b32_e32 v245, 0xffff0000, v234
	v_lshlrev_b32_e32 v246, 16, v235
	v_and_b32_e32 v247, 0xffff0000, v235
	v_fmac_f32_e32 v248, v170, v244
	v_fmac_f32_e32 v249, v171, v245
	v_fmac_f32_e32 v250, v172, v246
	v_fmac_f32_e32 v251, v173, v247
	v_lshlrev_b32_e32 v244, 16, v236
	v_and_b32_e32 v245, 0xffff0000, v236
	v_lshlrev_b32_e32 v246, 16, v237
	v_and_b32_e32 v247, 0xffff0000, v237
	v_fmac_f32_e32 v248, v174, v244
	v_fmac_f32_e32 v249, v175, v245
	v_fmac_f32_e32 v250, v176, v246
	v_fmac_f32_e32 v251, v177, v247
	v_mul_f32_e32 v244, 0xbfb8aa3b, v248
	v_mul_f32_e32 v245, 0xbfb8aa3b, v249
	v_mul_f32_e32 v246, 0xbfb8aa3b, v250
	v_mul_f32_e32 v247, 0xbfb8aa3b, v251
	v_exp_f32_e32 v244, v244
	v_exp_f32_e32 v245, v245
	v_exp_f32_e32 v246, v246
	v_exp_f32_e32 v247, v247
	v_add_f32_e32 v244, 1.0, v244
	v_add_f32_e32 v245, 1.0, v245
	v_add_f32_e32 v246, 1.0, v246
	v_add_f32_e32 v247, 1.0, v247
	v_rcp_f32_e32 v244, v244
	v_rcp_f32_e32 v245, v245
	v_rcp_f32_e32 v246, v246
	v_rcp_f32_e32 v247, v247
	v_mul_f32_e32 v248, v248, v244
	v_mul_f32_e32 v249, v249, v245
	v_mul_f32_e32 v250, v250, v246
	v_mul_f32_e32 v251, v251, v247
	v_mul_f32_e32 v6, v6, v248
	v_mul_f32_e32 v7, v7, v249
	v_mul_f32_e32 v8, v8, v250
	v_mul_f32_e32 v9, v9, v251
	v_cvt_pk_bf16_f32 v216, v6, v7
	v_cvt_pk_bf16_f32 v217, v8, v9
	global_store_dwordx2 v[210:211], v[216:217], off offset:256
	s_waitcnt lgkmcnt(0)
	v_lshlrev_b32_e32 v244, 16, v238
	v_and_b32_e32 v245, 0xffff0000, v238
	v_lshlrev_b32_e32 v246, 16, v239
	v_and_b32_e32 v247, 0xffff0000, v239
	v_mul_f32_e32 v248, v178, v244
	v_mul_f32_e32 v249, v179, v245
	v_mul_f32_e32 v250, v180, v246
	v_mul_f32_e32 v251, v181, v247
	v_lshlrev_b32_e32 v244, 16, v240
	v_and_b32_e32 v245, 0xffff0000, v240
	v_lshlrev_b32_e32 v246, 16, v241
	v_and_b32_e32 v247, 0xffff0000, v241
	v_fmac_f32_e32 v248, v182, v244
	v_fmac_f32_e32 v249, v183, v245
	v_fmac_f32_e32 v250, v184, v246
	v_fmac_f32_e32 v251, v185, v247
	v_lshlrev_b32_e32 v244, 16, v242
	v_and_b32_e32 v245, 0xffff0000, v242
	v_lshlrev_b32_e32 v246, 16, v243
	v_and_b32_e32 v247, 0xffff0000, v243
	v_fmac_f32_e32 v248, v186, v244
	v_fmac_f32_e32 v249, v187, v245
	v_fmac_f32_e32 v250, v188, v246
	v_fmac_f32_e32 v251, v189, v247
	v_mul_f32_e32 v244, 0xbfb8aa3b, v248
	v_mul_f32_e32 v245, 0xbfb8aa3b, v249
	v_mul_f32_e32 v246, 0xbfb8aa3b, v250
	v_mul_f32_e32 v247, 0xbfb8aa3b, v251
	v_exp_f32_e32 v244, v244
	v_exp_f32_e32 v245, v245
	v_exp_f32_e32 v246, v246
	v_exp_f32_e32 v247, v247
	v_add_f32_e32 v244, 1.0, v244
	v_add_f32_e32 v245, 1.0, v245
	v_add_f32_e32 v246, 1.0, v246
	v_add_f32_e32 v247, 1.0, v247
	v_rcp_f32_e32 v244, v244
	v_rcp_f32_e32 v245, v245
	v_rcp_f32_e32 v246, v246
	v_rcp_f32_e32 v247, v247
	v_mul_f32_e32 v248, v248, v244
	v_mul_f32_e32 v249, v249, v245
	v_mul_f32_e32 v250, v250, v246
	v_mul_f32_e32 v251, v251, v247
	v_mul_f32_e32 v2, v2, v248
	v_mul_f32_e32 v3, v3, v249
	v_mul_f32_e32 v4, v4, v250
	v_mul_f32_e32 v5, v5, v251
	v_cvt_pk_bf16_f32 v218, v2, v3
	v_cvt_pk_bf16_f32 v219, v4, v5
	global_store_dwordx2 v[210:211], v[218:219], off offset:288
	v_readlane_b32 s36, v253, 33
	v_readlane_b32 s37, v253, 34
	v_readlane_b32 s38, v253, 35
	v_readlane_b32 s39, v253, 36
	v_readlane_b32 s40, v253, 37
	v_readlane_b32 s41, v253, 38
	v_readlane_b32 s42, v253, 39
	v_readlane_b32 s43, v253, 40
	v_readlane_b32 s44, v253, 41
	v_readlane_b32 s45, v253, 42
	v_readlane_b32 s46, v253, 43
	v_readlane_b32 s47, v253, 44
	v_readlane_b32 s48, v253, 45
	v_readlane_b32 s49, v253, 46
	v_readlane_b32 s50, v253, 47
	v_readlane_b32 s51, v253, 48
	s_add_i32 s76, s76, s96
	s_cmpk_gt_i32 s76, 0x3ff
	s_cbranch_scc1 .LBB0_69
	s_branch .LBB0_31

.LBB0_85:
	ds_read_b128 v[164:167], v151
	ds_read_b128 v[168:171], v151 offset:1024
	ds_read_b128 v[172:175], v151 offset:2048
	ds_read_b128 v[176:179], v151 offset:3072
	v_add_u32_e32 v162, 0xc000, v147
	v_lshl_add_u64 v[204:205], v[138:139], 0, s[10:11]
	v_readfirstlane_b32 s1, v162
	v_lshl_add_u64 v[210:211], v[204:205], 0, s[60:61]
	s_mov_b32 m0, s1
	v_add_u32_e32 v163, 0xe000, v147
	ds_read_b128 v[180:183], v0
	ds_read_b128 v[184:187], v0 offset:1024
	ds_read_b128 v[188:191], v0 offset:2048
	ds_read_b128 v[192:195], v0 offset:3072
	ds_read_b128 v[196:199], v0 offset:4096
	ds_read_b128 v[200:203], v0 offset:5120
	ds_read_b128 v[222:225], v0 offset:6144
	ds_read_b128 v[232:235], v0 offset:7168
	global_load_lds_dwordx4 v[210:211], off
	v_lshl_add_u64 v[210:211], v[140:141], 0, s[10:11]
	v_readfirstlane_b32 s1, v163
	v_lshl_add_u64 v[216:217], v[210:211], 0, s[60:61]
	s_mov_b32 m0, s1
	s_nop 0
	global_load_lds_dwordx4 v[216:217], off
	s_waitcnt lgkmcnt(8)
	s_barrier
	s_waitcnt lgkmcnt(0)
	s_setprio 1
	s_waitcnt lgkmcnt(0)
	v_mfma_f32_16x16x32_bf16 v[126:129], v[164:167], v[180:183], v[126:129]
	v_mfma_f32_16x16x32_bf16 v[122:125], v[172:175], v[180:183], v[122:125]
	v_mfma_f32_16x16x32_bf16 v[118:121], v[164:167], v[188:191], v[118:121]
	v_mfma_f32_16x16x32_bf16 v[114:117], v[172:175], v[188:191], v[114:117]
	v_mfma_f32_16x16x32_bf16 v[110:113], v[164:167], v[196:199], v[110:113]
	v_mfma_f32_16x16x32_bf16 v[106:109], v[172:175], v[196:199], v[106:109]
	v_mfma_f32_16x16x32_bf16 v[102:105], v[164:167], v[222:225], v[102:105]
	v_mfma_f32_16x16x32_bf16 v[98:101], v[172:175], v[222:225], v[98:101]
	v_mfma_f32_16x16x32_bf16 v[126:129], v[168:171], v[184:187], v[126:129]
	v_mfma_f32_16x16x32_bf16 v[122:125], v[176:179], v[184:187], v[122:125]
	v_mfma_f32_16x16x32_bf16 v[118:121], v[168:171], v[192:195], v[118:121]
	v_mfma_f32_16x16x32_bf16 v[114:117], v[176:179], v[192:195], v[114:117]
	v_mfma_f32_16x16x32_bf16 v[110:113], v[168:171], v[200:203], v[110:113]
	v_mfma_f32_16x16x32_bf16 v[106:109], v[176:179], v[200:203], v[106:109]
	v_mfma_f32_16x16x32_bf16 v[102:105], v[168:171], v[232:235], v[102:105]
	v_mfma_f32_16x16x32_bf16 v[98:101], v[176:179], v[232:235], v[98:101]
	s_setprio 0
	s_barrier
	v_lshl_add_u64 v[216:217], v[134:135], 0, s[10:11]
	v_readfirstlane_b32 s1, v149
	v_lshl_add_u64 v[218:219], v[216:217], 0, s[74:75]
	s_mov_b32 m0, s1
	ds_read_b128 v[236:239], v151 offset:16384
	ds_read_b128 v[240:243], v151 offset:17408
	ds_read_b128 v[244:247], v151 offset:18432
	ds_read_b128 v[248:251], v151 offset:19456
	global_load_lds_dwordx4 v[218:219], off
	v_lshl_add_u64 v[218:219], v[136:137], 0, s[10:11]
	v_readfirstlane_b32 s1, v150
	v_lshl_add_u64 v[228:229], v[218:219], 0, s[74:75]
	s_mov_b32 m0, s1
	s_nop 0
	global_load_lds_dwordx4 v[228:229], off
	s_barrier
	s_waitcnt lgkmcnt(0)
	s_setprio 1
	s_waitcnt lgkmcnt(0)
	v_mfma_f32_16x16x32_bf16 v[94:97], v[236:239], v[180:183], v[94:97]
	v_mfma_f32_16x16x32_bf16 v[90:93], v[244:247], v[180:183], v[90:93]
	v_mfma_f32_16x16x32_bf16 v[86:89], v[236:239], v[188:191], v[86:89]
	v_mfma_f32_16x16x32_bf16 v[82:85], v[244:247], v[188:191], v[82:85]
	v_mfma_f32_16x16x32_bf16 v[78:81], v[236:239], v[196:199], v[78:81]
	v_mfma_f32_16x16x32_bf16 v[74:77], v[244:247], v[196:199], v[74:77]
	v_mfma_f32_16x16x32_bf16 v[70:73], v[236:239], v[222:225], v[70:73]
	v_mfma_f32_16x16x32_bf16 v[66:69], v[244:247], v[222:225], v[66:69]
	v_mfma_f32_16x16x32_bf16 v[94:97], v[240:243], v[184:187], v[94:97]
	v_mfma_f32_16x16x32_bf16 v[90:93], v[248:251], v[184:187], v[90:93]
	v_mfma_f32_16x16x32_bf16 v[86:89], v[240:243], v[192:195], v[86:89]
	v_mfma_f32_16x16x32_bf16 v[82:85], v[248:251], v[192:195], v[82:85]
	v_mfma_f32_16x16x32_bf16 v[78:81], v[240:243], v[200:203], v[78:81]
	v_mfma_f32_16x16x32_bf16 v[74:77], v[248:251], v[200:203], v[74:77]
	v_mfma_f32_16x16x32_bf16 v[70:73], v[240:243], v[232:235], v[70:73]
	v_mfma_f32_16x16x32_bf16 v[66:69], v[248:251], v[232:235], v[66:69]
	s_setprio 0
	v_readfirstlane_b32 s1, v147
	v_lshl_add_u64 v[228:229], v[204:205], 0, s[74:75]
	s_mov_b32 m0, s1
	v_readfirstlane_b32 s1, v148
	s_barrier
	ds_read_b128 v[180:183], v0 offset:16384
	ds_read_b128 v[184:187], v0 offset:17408
	ds_read_b128 v[188:191], v0 offset:18432
	ds_read_b128 v[192:195], v0 offset:19456
	ds_read_b128 v[196:199], v0 offset:20480
	ds_read_b128 v[200:203], v0 offset:21504
	ds_read_b128 v[222:225], v0 offset:22528
	ds_read_b128 v[232:235], v0 offset:23552
	global_load_lds_dwordx4 v[228:229], off
	v_lshl_add_u64 v[228:229], v[210:211], 0, s[74:75]
	s_mov_b32 m0, s1
	s_nop 0
	global_load_lds_dwordx4 v[228:229], off
	s_barrier
	s_waitcnt lgkmcnt(0)
	s_setprio 1
	s_waitcnt lgkmcnt(0)
	v_mfma_f32_16x16x32_bf16 v[62:65], v[164:167], v[180:183], v[62:65]
	v_mfma_f32_16x16x32_bf16 v[58:61], v[172:175], v[180:183], v[58:61]
	v_mfma_f32_16x16x32_bf16 v[54:57], v[164:167], v[188:191], v[54:57]
	v_mfma_f32_16x16x32_bf16 v[50:53], v[172:175], v[188:191], v[50:53]
	v_mfma_f32_16x16x32_bf16 v[46:49], v[164:167], v[196:199], v[46:49]
	v_mfma_f32_16x16x32_bf16 v[42:45], v[172:175], v[196:199], v[42:45]
	v_mfma_f32_16x16x32_bf16 v[38:41], v[164:167], v[222:225], v[38:41]
	v_mfma_f32_16x16x32_bf16 v[34:37], v[172:175], v[222:225], v[34:37]
	v_mfma_f32_16x16x32_bf16 v[62:65], v[168:171], v[184:187], v[62:65]
	v_mfma_f32_16x16x32_bf16 v[58:61], v[176:179], v[184:187], v[58:61]
	v_mfma_f32_16x16x32_bf16 v[54:57], v[168:171], v[192:195], v[54:57]
	v_mfma_f32_16x16x32_bf16 v[50:53], v[176:179], v[192:195], v[50:53]
	v_mfma_f32_16x16x32_bf16 v[46:49], v[168:171], v[200:203], v[46:49]
	v_mfma_f32_16x16x32_bf16 v[42:45], v[176:179], v[200:203], v[42:45]
	v_mfma_f32_16x16x32_bf16 v[38:41], v[168:171], v[232:235], v[38:41]
	v_mfma_f32_16x16x32_bf16 v[34:37], v[176:179], v[232:235], v[34:37]
	s_setprio 0
	s_barrier
	v_readfirstlane_b32 s1, v152
	v_lshl_add_u64 v[164:165], v[216:217], 0, s[18:19]
	s_mov_b32 m0, s1
	v_readfirstlane_b32 s1, v153
	global_load_lds_dwordx4 v[164:165], off
	v_lshl_add_u64 v[164:165], v[218:219], 0, s[18:19]
	s_mov_b32 m0, s1
	s_nop 0
	global_load_lds_dwordx4 v[164:165], off
	s_waitcnt vmcnt(6)
	s_barrier
	s_setprio 1
	v_mfma_f32_16x16x32_bf16 v[30:33], v[236:239], v[180:183], v[30:33]
	v_mfma_f32_16x16x32_bf16 v[26:29], v[244:247], v[180:183], v[26:29]
	v_mfma_f32_16x16x32_bf16 v[22:25], v[236:239], v[188:191], v[22:25]
	v_mfma_f32_16x16x32_bf16 v[18:21], v[244:247], v[188:191], v[18:21]
	v_mfma_f32_16x16x32_bf16 v[14:17], v[236:239], v[196:199], v[14:17]
	v_mfma_f32_16x16x32_bf16 v[10:13], v[244:247], v[196:199], v[10:13]
	v_mfma_f32_16x16x32_bf16 v[6:9], v[236:239], v[222:225], v[6:9]
	v_mfma_f32_16x16x32_bf16 v[2:5], v[244:247], v[222:225], v[2:5]
	v_mfma_f32_16x16x32_bf16 v[30:33], v[240:243], v[184:187], v[30:33]
	v_mfma_f32_16x16x32_bf16 v[26:29], v[248:251], v[184:187], v[26:29]
	v_mfma_f32_16x16x32_bf16 v[22:25], v[240:243], v[192:195], v[22:25]
	v_mfma_f32_16x16x32_bf16 v[18:21], v[248:251], v[192:195], v[18:21]
	v_mfma_f32_16x16x32_bf16 v[14:17], v[240:243], v[200:203], v[14:17]
	v_mfma_f32_16x16x32_bf16 v[10:13], v[248:251], v[200:203], v[10:13]
	v_mfma_f32_16x16x32_bf16 v[6:9], v[240:243], v[232:235], v[6:9]
	v_mfma_f32_16x16x32_bf16 v[2:5], v[248:251], v[232:235], v[2:5]
	s_setprio 0
	s_barrier
	ds_read_b128 v[164:167], v151 offset:32768
	ds_read_b128 v[168:171], v151 offset:33792
	ds_read_b128 v[172:175], v151 offset:34816
	ds_read_b128 v[176:179], v151 offset:35840
	v_readfirstlane_b32 s1, v154
	v_lshl_add_u64 v[228:229], v[204:205], 0, s[18:19]
	s_mov_b32 m0, s1
	v_readfirstlane_b32 s1, v155
	ds_read_b128 v[180:183], v0 offset:32768
	ds_read_b128 v[184:187], v0 offset:33792
	ds_read_b128 v[188:191], v0 offset:34816
	ds_read_b128 v[192:195], v0 offset:35840
	ds_read_b128 v[196:199], v0 offset:36864
	ds_read_b128 v[200:203], v0 offset:37888
	ds_read_b128 v[222:225], v0 offset:38912
	ds_read_b128 v[232:235], v0 offset:39936
	global_load_lds_dwordx4 v[228:229], off
	v_lshl_add_u64 v[228:229], v[210:211], 0, s[18:19]
	s_mov_b32 m0, s1
	s_nop 0
	global_load_lds_dwordx4 v[228:229], off
	s_waitcnt lgkmcnt(8)
	s_barrier
	s_waitcnt lgkmcnt(0)
	s_setprio 1
	s_waitcnt lgkmcnt(0)
	v_mfma_f32_16x16x32_bf16 v[126:129], v[164:167], v[180:183], v[126:129]
	v_mfma_f32_16x16x32_bf16 v[122:125], v[172:175], v[180:183], v[122:125]
	v_mfma_f32_16x16x32_bf16 v[118:121], v[164:167], v[188:191], v[118:121]
	v_mfma_f32_16x16x32_bf16 v[114:117], v[172:175], v[188:191], v[114:117]
	v_mfma_f32_16x16x32_bf16 v[110:113], v[164:167], v[196:199], v[110:113]
	v_mfma_f32_16x16x32_bf16 v[106:109], v[172:175], v[196:199], v[106:109]
	v_mfma_f32_16x16x32_bf16 v[102:105], v[164:167], v[222:225], v[102:105]
	v_mfma_f32_16x16x32_bf16 v[98:101], v[172:175], v[222:225], v[98:101]
	v_mfma_f32_16x16x32_bf16 v[126:129], v[168:171], v[184:187], v[126:129]
	v_mfma_f32_16x16x32_bf16 v[122:125], v[176:179], v[184:187], v[122:125]
	v_mfma_f32_16x16x32_bf16 v[118:121], v[168:171], v[192:195], v[118:121]
	v_mfma_f32_16x16x32_bf16 v[114:117], v[176:179], v[192:195], v[114:117]
	v_mfma_f32_16x16x32_bf16 v[110:113], v[168:171], v[200:203], v[110:113]
	v_mfma_f32_16x16x32_bf16 v[106:109], v[176:179], v[200:203], v[106:109]
	v_mfma_f32_16x16x32_bf16 v[102:105], v[168:171], v[232:235], v[102:105]
	v_mfma_f32_16x16x32_bf16 v[98:101], v[176:179], v[232:235], v[98:101]
	s_setprio 0
	s_barrier
	v_readfirstlane_b32 s1, v156
	v_lshl_add_u64 v[228:229], v[216:217], 0, s[28:29]
	s_mov_b32 m0, s1
	v_readfirstlane_b32 s1, v157
	ds_read_b128 v[236:239], v151 offset:49152
	ds_read_b128 v[240:243], v151 offset:50176
	ds_read_b128 v[244:247], v151 offset:51200
	ds_read_b128 v[248:251], v151 offset:52224
	global_load_lds_dwordx4 v[228:229], off
	v_lshl_add_u64 v[228:229], v[218:219], 0, s[28:29]
	s_mov_b32 m0, s1
	s_nop 0
	global_load_lds_dwordx4 v[228:229], off
	s_barrier
	s_waitcnt lgkmcnt(0)
	s_setprio 1
	s_waitcnt lgkmcnt(0)
	v_mfma_f32_16x16x32_bf16 v[94:97], v[236:239], v[180:183], v[94:97]
	v_mfma_f32_16x16x32_bf16 v[90:93], v[244:247], v[180:183], v[90:93]
	v_mfma_f32_16x16x32_bf16 v[86:89], v[236:239], v[188:191], v[86:89]
	v_mfma_f32_16x16x32_bf16 v[82:85], v[244:247], v[188:191], v[82:85]
	v_mfma_f32_16x16x32_bf16 v[78:81], v[236:239], v[196:199], v[78:81]
	v_mfma_f32_16x16x32_bf16 v[74:77], v[244:247], v[196:199], v[74:77]
	v_mfma_f32_16x16x32_bf16 v[70:73], v[236:239], v[222:225], v[70:73]
	v_mfma_f32_16x16x32_bf16 v[66:69], v[244:247], v[222:225], v[66:69]
	v_mfma_f32_16x16x32_bf16 v[94:97], v[240:243], v[184:187], v[94:97]
	v_mfma_f32_16x16x32_bf16 v[90:93], v[248:251], v[184:187], v[90:93]
	v_mfma_f32_16x16x32_bf16 v[86:89], v[240:243], v[192:195], v[86:89]
	v_mfma_f32_16x16x32_bf16 v[82:85], v[248:251], v[192:195], v[82:85]
	v_mfma_f32_16x16x32_bf16 v[78:81], v[240:243], v[200:203], v[78:81]
	v_mfma_f32_16x16x32_bf16 v[74:77], v[248:251], v[200:203], v[74:77]
	v_mfma_f32_16x16x32_bf16 v[70:73], v[240:243], v[232:235], v[70:73]
	v_mfma_f32_16x16x32_bf16 v[66:69], v[248:251], v[232:235], v[66:69]
	s_setprio 0
	v_readfirstlane_b32 s1, v158
	v_lshl_add_u64 v[204:205], v[204:205], 0, s[28:29]
	s_mov_b32 m0, s1
	v_readfirstlane_b32 s1, v159
	s_barrier
	ds_read_b128 v[180:183], v0 offset:49152
	ds_read_b128 v[184:187], v0 offset:50176
	ds_read_b128 v[188:191], v0 offset:51200
	ds_read_b128 v[192:195], v0 offset:52224
	ds_read_b128 v[196:199], v0 offset:53248
	ds_read_b128 v[200:203], v0 offset:54272
	ds_read_b128 v[222:225], v0 offset:55296
	ds_read_b128 v[232:235], v0 offset:56320
	global_load_lds_dwordx4 v[204:205], off
	v_lshl_add_u64 v[204:205], v[210:211], 0, s[28:29]
	s_mov_b32 m0, s1
	s_nop 0
	global_load_lds_dwordx4 v[204:205], off
	s_barrier
	s_waitcnt lgkmcnt(0)
	s_setprio 1
	s_waitcnt lgkmcnt(0)
	v_mfma_f32_16x16x32_bf16 v[62:65], v[164:167], v[180:183], v[62:65]
	v_mfma_f32_16x16x32_bf16 v[58:61], v[172:175], v[180:183], v[58:61]
	v_mfma_f32_16x16x32_bf16 v[54:57], v[164:167], v[188:191], v[54:57]
	v_mfma_f32_16x16x32_bf16 v[50:53], v[172:175], v[188:191], v[50:53]
	v_mfma_f32_16x16x32_bf16 v[46:49], v[164:167], v[196:199], v[46:49]
	v_mfma_f32_16x16x32_bf16 v[42:45], v[172:175], v[196:199], v[42:45]
	v_mfma_f32_16x16x32_bf16 v[38:41], v[164:167], v[222:225], v[38:41]
	v_mfma_f32_16x16x32_bf16 v[34:37], v[172:175], v[222:225], v[34:37]
	v_mfma_f32_16x16x32_bf16 v[62:65], v[168:171], v[184:187], v[62:65]
	v_mfma_f32_16x16x32_bf16 v[58:61], v[176:179], v[184:187], v[58:61]
	v_mfma_f32_16x16x32_bf16 v[54:57], v[168:171], v[192:195], v[54:57]
	v_mfma_f32_16x16x32_bf16 v[50:53], v[176:179], v[192:195], v[50:53]
	v_mfma_f32_16x16x32_bf16 v[46:49], v[168:171], v[200:203], v[46:49]
	v_mfma_f32_16x16x32_bf16 v[42:45], v[176:179], v[200:203], v[42:45]
	v_mfma_f32_16x16x32_bf16 v[38:41], v[168:171], v[232:235], v[38:41]
	v_mfma_f32_16x16x32_bf16 v[34:37], v[176:179], v[232:235], v[34:37]
	s_setprio 0
	s_barrier
	v_readfirstlane_b32 s1, v160
	v_lshl_add_u64 v[164:165], v[216:217], 0, s[30:31]
	s_mov_b32 m0, s1
	v_readfirstlane_b32 s1, v161
	global_load_lds_dwordx4 v[164:165], off
	v_lshl_add_u64 v[164:165], v[218:219], 0, s[30:31]
	s_mov_b32 m0, s1
	s_nop 0
	global_load_lds_dwordx4 v[164:165], off
	s_waitcnt vmcnt(6)
	s_barrier
	s_setprio 1
	v_mfma_f32_16x16x32_bf16 v[30:33], v[236:239], v[180:183], v[30:33]
	v_mfma_f32_16x16x32_bf16 v[26:29], v[244:247], v[180:183], v[26:29]
	v_mfma_f32_16x16x32_bf16 v[22:25], v[236:239], v[188:191], v[22:25]
	v_mfma_f32_16x16x32_bf16 v[18:21], v[244:247], v[188:191], v[18:21]
	v_mfma_f32_16x16x32_bf16 v[14:17], v[236:239], v[196:199], v[14:17]
	v_mfma_f32_16x16x32_bf16 v[10:13], v[244:247], v[196:199], v[10:13]
	v_mfma_f32_16x16x32_bf16 v[6:9], v[236:239], v[222:225], v[6:9]
	v_mfma_f32_16x16x32_bf16 v[2:5], v[244:247], v[222:225], v[2:5]
	v_mfma_f32_16x16x32_bf16 v[30:33], v[240:243], v[184:187], v[30:33]
	v_mfma_f32_16x16x32_bf16 v[26:29], v[248:251], v[184:187], v[26:29]
	v_mfma_f32_16x16x32_bf16 v[22:25], v[240:243], v[192:195], v[22:25]
	v_mfma_f32_16x16x32_bf16 v[18:21], v[248:251], v[192:195], v[18:21]
	v_mfma_f32_16x16x32_bf16 v[14:17], v[240:243], v[200:203], v[14:17]
	v_mfma_f32_16x16x32_bf16 v[10:13], v[248:251], v[200:203], v[10:13]
	v_mfma_f32_16x16x32_bf16 v[6:9], v[240:243], v[232:235], v[6:9]
	v_mfma_f32_16x16x32_bf16 v[2:5], v[248:251], v[232:235], v[2:5]
	s_setprio 0
	s_add_i32 s0, s0, 2
	s_add_u32 s10, s10, 0x100
	s_addc_u32 s11, s11, 0
	s_cmp_lt_u32 s0, 28
	s_barrier
	s_cbranch_scc1 .LBB0_85
	s_mov_b64 s[10:11], 0xf80
	v_readfirstlane_b32 s0, v162
	v_lshl_add_u64 v[132:133], v[132:133], 0, s[10:11]
	s_mov_b32 m0, s0
	v_readfirstlane_b32 s0, v163
	ds_read_b128 v[134:137], v151
	ds_read_b128 v[138:141], v151 offset:1024
	ds_read_b128 v[152:155], v151 offset:2048
	ds_read_b128 v[156:159], v151 offset:3072
	ds_read_b128 v[164:167], v0
	ds_read_b128 v[168:171], v0 offset:1024
	ds_read_b128 v[172:175], v0 offset:2048
	ds_read_b128 v[176:179], v0 offset:3072
	ds_read_b128 v[180:183], v0 offset:4096
	ds_read_b128 v[184:187], v0 offset:5120
	ds_read_b128 v[188:191], v0 offset:6144
	ds_read_b128 v[192:195], v0 offset:7168
	global_load_lds_dwordx4 v[132:133], off
	v_lshl_add_u64 v[130:131], v[130:131], 0, s[10:11]
	s_mov_b32 m0, s0
	s_nop 0
	global_load_lds_dwordx4 v[130:131], off
	s_barrier
	s_waitcnt lgkmcnt(0)
	s_setprio 1
	s_waitcnt lgkmcnt(0)
	v_mfma_f32_16x16x32_bf16 v[126:129], v[134:137], v[164:167], v[126:129]
	v_mfma_f32_16x16x32_bf16 v[122:125], v[152:155], v[164:167], v[122:125]
	v_mfma_f32_16x16x32_bf16 v[114:117], v[152:155], v[172:175], v[114:117]
	v_mfma_f32_16x16x32_bf16 v[106:109], v[152:155], v[180:183], v[106:109]
	v_mfma_f32_16x16x32_bf16 v[98:101], v[152:155], v[188:191], v[98:101]
	v_mfma_f32_16x16x32_bf16 v[126:129], v[138:141], v[168:171], v[126:129]
	v_mfma_f32_16x16x32_bf16 v[122:125], v[156:159], v[168:171], v[122:125]
	v_mfma_f32_16x16x32_bf16 v[118:121], v[134:137], v[172:175], v[118:121]
	v_mfma_f32_16x16x32_bf16 v[114:117], v[156:159], v[176:179], v[114:117]
	v_mfma_f32_16x16x32_bf16 v[110:113], v[134:137], v[180:183], v[110:113]
	v_mfma_f32_16x16x32_bf16 v[106:109], v[156:159], v[184:187], v[106:109]
	v_mfma_f32_16x16x32_bf16 v[102:105], v[134:137], v[188:191], v[102:105]
	v_mfma_f32_16x16x32_bf16 v[98:101], v[156:159], v[192:195], v[98:101]
	v_mfma_f32_16x16x32_bf16 v[130:133], v[138:141], v[176:179], v[118:121]
	v_mfma_f32_16x16x32_bf16 v[160:163], v[138:141], v[184:187], v[110:113]
	v_mfma_f32_16x16x32_bf16 v[196:199], v[138:141], v[192:195], v[102:105]
	s_setprio 0
	s_barrier
	s_nop 0
	ds_read_b128 v[102:105], v151 offset:16384
	ds_read_b128 v[110:113], v151 offset:17408
	ds_read_b128 v[118:121], v151 offset:18432
	ds_read_b128 v[200:203], v151 offset:19456
	s_barrier
	s_waitcnt lgkmcnt(0)
	s_setprio 1
	s_waitcnt lgkmcnt(1)
	v_mfma_f32_16x16x32_bf16 v[90:93], v[118:121], v[164:167], v[90:93]
	v_mfma_f32_16x16x32_bf16 v[86:89], v[102:105], v[172:175], v[86:89]
	v_mfma_f32_16x16x32_bf16 v[82:85], v[118:121], v[172:175], v[82:85]
	v_mfma_f32_16x16x32_bf16 v[78:81], v[102:105], v[180:183], v[78:81]
	v_mfma_f32_16x16x32_bf16 v[70:73], v[102:105], v[188:191], v[70:73]
	v_mfma_f32_16x16x32_bf16 v[94:97], v[102:105], v[164:167], v[94:97]
	s_waitcnt lgkmcnt(0)
	v_mfma_f32_16x16x32_bf16 v[90:93], v[200:203], v[168:171], v[90:93]
	v_mfma_f32_16x16x32_bf16 v[86:89], v[110:113], v[176:179], v[86:89]
	v_mfma_f32_16x16x32_bf16 v[82:85], v[200:203], v[176:179], v[82:85]
	v_mfma_f32_16x16x32_bf16 v[78:81], v[110:113], v[184:187], v[78:81]
	v_mfma_f32_16x16x32_bf16 v[74:77], v[118:121], v[180:183], v[74:77]
	v_mfma_f32_16x16x32_bf16 v[70:73], v[110:113], v[192:195], v[70:73]
	v_mfma_f32_16x16x32_bf16 v[66:69], v[118:121], v[188:191], v[66:69]
	v_mfma_f32_16x16x32_bf16 v[222:225], v[110:113], v[168:171], v[94:97]
	v_mfma_f32_16x16x32_bf16 v[164:167], v[200:203], v[184:187], v[74:77]
	v_mfma_f32_16x16x32_bf16 v[168:171], v[200:203], v[192:195], v[66:69]
	s_setprio 0
	s_barrier
	s_nop 2
	ds_read_b128 v[66:69], v0 offset:16384
	ds_read_b128 v[74:77], v0 offset:17408
	ds_read_b128 v[94:97], v0 offset:18432
	ds_read_b128 v[172:175], v0 offset:19456
	ds_read_b128 v[176:179], v0 offset:20480
	ds_read_b128 v[180:183], v0 offset:21504
	ds_read_b128 v[184:187], v0 offset:22528
	ds_read_b128 v[188:191], v0 offset:23552
	s_waitcnt vmcnt(4)
	s_barrier
	s_waitcnt lgkmcnt(0)
	s_setprio 1
	s_waitcnt lgkmcnt(5)
	v_mfma_f32_16x16x32_bf16 v[54:57], v[134:137], v[94:97], v[54:57]
	v_mfma_f32_16x16x32_bf16 v[50:53], v[152:155], v[94:97], v[50:53]
	v_mfma_f32_16x16x32_bf16 v[62:65], v[134:137], v[66:69], v[62:65]
	v_mfma_f32_16x16x32_bf16 v[58:61], v[152:155], v[66:69], v[58:61]
	s_waitcnt lgkmcnt(4)
	v_mfma_f32_16x16x32_bf16 v[54:57], v[138:141], v[172:175], v[54:57]
	v_mfma_f32_16x16x32_bf16 v[50:53], v[156:159], v[172:175], v[50:53]
	s_waitcnt lgkmcnt(3)
	v_mfma_f32_16x16x32_bf16 v[46:49], v[134:137], v[176:179], v[46:49]
	v_mfma_f32_16x16x32_bf16 v[42:45], v[152:155], v[176:179], v[42:45]
	s_waitcnt lgkmcnt(1)
	v_mfma_f32_16x16x32_bf16 v[38:41], v[134:137], v[184:187], v[38:41]
	v_mfma_f32_16x16x32_bf16 v[34:37], v[152:155], v[184:187], v[34:37]
	v_mfma_f32_16x16x32_bf16 v[192:195], v[138:141], v[74:77], v[62:65]
	v_mfma_f32_16x16x32_bf16 v[232:235], v[156:159], v[74:77], v[58:61]
	v_mfma_f32_16x16x32_bf16 v[236:239], v[138:141], v[180:183], v[46:49]
	v_mfma_f32_16x16x32_bf16 v[240:243], v[156:159], v[180:183], v[42:45]
	s_waitcnt lgkmcnt(0)
	v_mfma_f32_16x16x32_bf16 v[134:137], v[138:141], v[188:191], v[38:41]
	v_mfma_f32_16x16x32_bf16 v[138:141], v[156:159], v[188:191], v[34:37]
	s_setprio 0
	s_setprio 1
	v_mfma_f32_16x16x32_bf16 v[30:33], v[102:105], v[66:69], v[30:33]
	v_mfma_f32_16x16x32_bf16 v[26:29], v[118:121], v[66:69], v[26:29]
	v_mfma_f32_16x16x32_bf16 v[14:17], v[102:105], v[176:179], v[14:17]
	v_mfma_f32_16x16x32_bf16 v[10:13], v[118:121], v[176:179], v[10:13]
	v_mfma_f32_16x16x32_bf16 v[30:33], v[110:113], v[74:77], v[30:33]
	v_mfma_f32_16x16x32_bf16 v[26:29], v[200:203], v[74:77], v[26:29]
	v_mfma_f32_16x16x32_bf16 v[22:25], v[102:105], v[94:97], v[22:25]
	v_mfma_f32_16x16x32_bf16 v[18:21], v[118:121], v[94:97], v[18:21]
	v_mfma_f32_16x16x32_bf16 v[14:17], v[110:113], v[180:183], v[14:17]
	v_mfma_f32_16x16x32_bf16 v[10:13], v[200:203], v[180:183], v[10:13]
	v_mfma_f32_16x16x32_bf16 v[6:9], v[102:105], v[184:187], v[6:9]
	v_mfma_f32_16x16x32_bf16 v[2:5], v[118:121], v[184:187], v[2:5]
	v_mfma_f32_16x16x32_bf16 v[152:155], v[110:113], v[172:175], v[22:25]
	v_mfma_f32_16x16x32_bf16 v[156:159], v[200:203], v[172:175], v[18:21]
	v_mfma_f32_16x16x32_bf16 v[172:175], v[110:113], v[188:191], v[6:9]
	v_mfma_f32_16x16x32_bf16 v[176:179], v[200:203], v[188:191], v[2:5]
	s_setprio 0
	s_barrier
	s_nop 1
	ds_read_b128 v[2:5], v151 offset:32768
	ds_read_b128 v[6:9], v151 offset:33792
	ds_read_b128 v[180:183], v151 offset:34816
	ds_read_b128 v[184:187], v151 offset:35840
	ds_read_b128 v[18:21], v0 offset:32768
	ds_read_b128 v[22:25], v0 offset:33792
	ds_read_b128 v[38:41], v0 offset:34816
	ds_read_b128 v[46:49], v0 offset:35840
	ds_read_b128 v[58:61], v0 offset:36864
	ds_read_b128 v[66:69], v0 offset:37888
	ds_read_b128 v[188:191], v0 offset:38912
	ds_read_b128 v[200:203], v0 offset:39936
	s_waitcnt vmcnt(2)
	s_barrier
	s_waitcnt lgkmcnt(0)
	s_setprio 1
	s_waitcnt lgkmcnt(7)
	v_mfma_f32_16x16x32_bf16 v[34:37], v[2:5], v[18:21], v[126:129]
	s_waitcnt lgkmcnt(6)
	v_mfma_f32_16x16x32_bf16 v[118:121], v[6:9], v[22:25], v[34:37]
	v_mfma_f32_16x16x32_bf16 v[34:37], v[180:183], v[18:21], v[122:125]
	v_mfma_f32_16x16x32_bf16 v[110:113], v[184:187], v[22:25], v[34:37]
	s_waitcnt lgkmcnt(5)
	v_mfma_f32_16x16x32_bf16 v[34:37], v[2:5], v[38:41], v[130:133]
	s_waitcnt lgkmcnt(4)
	v_mfma_f32_16x16x32_bf16 v[102:105], v[6:9], v[46:49], v[34:37]
	v_mfma_f32_16x16x32_bf16 v[34:37], v[180:183], v[38:41], v[114:117]
	v_mfma_f32_16x16x32_bf16 v[94:97], v[184:187], v[46:49], v[34:37]
	s_waitcnt lgkmcnt(3)
	v_mfma_f32_16x16x32_bf16 v[34:37], v[2:5], v[58:61], v[160:163]
	s_waitcnt lgkmcnt(2)
	v_mfma_f32_16x16x32_bf16 v[74:77], v[6:9], v[66:69], v[34:37]
	v_mfma_f32_16x16x32_bf16 v[34:37], v[180:183], v[58:61], v[106:109]
	v_mfma_f32_16x16x32_bf16 v[62:65], v[184:187], v[66:69], v[34:37]
	s_waitcnt lgkmcnt(1)
	v_mfma_f32_16x16x32_bf16 v[34:37], v[2:5], v[188:191], v[196:199]
	s_waitcnt lgkmcnt(0)
	v_mfma_f32_16x16x32_bf16 v[42:45], v[6:9], v[200:203], v[34:37]
	v_mfma_f32_16x16x32_bf16 v[34:37], v[180:183], v[188:191], v[98:101]
	v_mfma_f32_16x16x32_bf16 v[34:37], v[184:187], v[200:203], v[34:37]
	s_setprio 0
	s_barrier
	ds_read_b128 v[130:133], v151 offset:49152
	ds_read_b128 v[160:163], v151 offset:50176
	ds_read_b128 v[196:199], v151 offset:51200
	ds_read_b128 v[148:151], v151 offset:52224
	s_waitcnt vmcnt(0)
	s_barrier
	s_waitcnt lgkmcnt(0)
	s_setprio 1
	s_waitcnt lgkmcnt(3)
	v_mfma_f32_16x16x32_bf16 v[98:101], v[130:133], v[18:21], v[222:225]
	s_waitcnt lgkmcnt(1)
	v_mfma_f32_16x16x32_bf16 v[18:21], v[196:199], v[18:21], v[90:93]
	s_waitcnt lgkmcnt(0)
	v_mfma_f32_16x16x32_bf16 v[122:125], v[148:151], v[22:25], v[18:21]
	v_mfma_f32_16x16x32_bf16 v[18:21], v[130:133], v[38:41], v[86:89]
	v_mfma_f32_16x16x32_bf16 v[114:117], v[160:163], v[46:49], v[18:21]
	v_mfma_f32_16x16x32_bf16 v[18:21], v[196:199], v[38:41], v[82:85]
	v_mfma_f32_16x16x32_bf16 v[106:109], v[148:151], v[46:49], v[18:21]
	v_mfma_f32_16x16x32_bf16 v[18:21], v[130:133], v[58:61], v[78:81]
	v_mfma_f32_16x16x32_bf16 v[126:129], v[160:163], v[22:25], v[98:101]
	v_mfma_f32_16x16x32_bf16 v[98:101], v[160:163], v[66:69], v[18:21]
	v_mfma_f32_16x16x32_bf16 v[18:21], v[196:199], v[58:61], v[164:167]
	v_mfma_f32_16x16x32_bf16 v[90:93], v[148:151], v[66:69], v[18:21]
	v_mfma_f32_16x16x32_bf16 v[18:21], v[130:133], v[188:191], v[70:73]
	v_mfma_f32_16x16x32_bf16 v[66:69], v[160:163], v[200:203], v[18:21]
	v_mfma_f32_16x16x32_bf16 v[18:21], v[196:199], v[188:191], v[168:171]
	v_mfma_f32_16x16x32_bf16 v[58:61], v[148:151], v[200:203], v[18:21]
	s_setprio 0
	s_barrier
	ds_read_b128 v[82:85], v0 offset:49152
	ds_read_b128 v[164:167], v0 offset:50176
	ds_read_b128 v[168:171], v0 offset:51200
	ds_read_b128 v[188:191], v0 offset:52224
	ds_read_b128 v[200:203], v0 offset:53248
	ds_read_b128 v[222:225], v0 offset:54272
	ds_read_b128 v[244:247], v0 offset:55296
	ds_read_b128 v[248:251], v0 offset:56320
	s_barrier
	s_waitcnt lgkmcnt(0)
	s_setprio 1
	s_waitcnt lgkmcnt(7)
	v_mfma_f32_16x16x32_bf16 v[18:21], v[2:5], v[82:85], v[192:195]
	s_waitcnt lgkmcnt(6)
	v_mfma_f32_16x16x32_bf16 v[78:81], v[6:9], v[164:167], v[18:21]
	v_mfma_f32_16x16x32_bf16 v[18:21], v[180:183], v[82:85], v[232:235]
	v_mfma_f32_16x16x32_bf16 v[70:73], v[184:187], v[164:167], v[18:21]
	s_waitcnt lgkmcnt(5)
	v_mfma_f32_16x16x32_bf16 v[18:21], v[2:5], v[168:171], v[54:57]
	s_waitcnt lgkmcnt(4)
	v_mfma_f32_16x16x32_bf16 v[46:49], v[6:9], v[188:191], v[18:21]
	v_mfma_f32_16x16x32_bf16 v[18:21], v[180:183], v[168:171], v[50:53]
	v_mfma_f32_16x16x32_bf16 v[38:41], v[184:187], v[188:191], v[18:21]
	s_waitcnt lgkmcnt(3)
	v_mfma_f32_16x16x32_bf16 v[18:21], v[2:5], v[200:203], v[236:239]
	s_waitcnt lgkmcnt(1)
	v_mfma_f32_16x16x32_bf16 v[2:5], v[2:5], v[244:247], v[134:137]
	v_mfma_f32_16x16x32_bf16 v[22:25], v[6:9], v[222:225], v[18:21]
	v_mfma_f32_16x16x32_bf16 v[18:21], v[180:183], v[200:203], v[240:243]
	s_waitcnt lgkmcnt(0)
	v_mfma_f32_16x16x32_bf16 v[6:9], v[6:9], v[248:251], v[2:5]
	v_mfma_f32_16x16x32_bf16 v[2:5], v[180:183], v[244:247], v[138:141]
	v_mfma_f32_16x16x32_bf16 v[18:21], v[184:187], v[222:225], v[18:21]
	v_mfma_f32_16x16x32_bf16 v[2:5], v[184:187], v[248:251], v[2:5]
	s_setprio 0
	s_setprio 1
	v_mfma_f32_16x16x32_bf16 v[26:29], v[196:199], v[82:85], v[26:29]
	v_mfma_f32_16x16x32_bf16 v[30:33], v[130:133], v[82:85], v[30:33]
	v_mfma_f32_16x16x32_bf16 v[82:85], v[148:151], v[164:167], v[26:29]
	v_mfma_f32_16x16x32_bf16 v[26:29], v[130:133], v[168:171], v[152:155]
	v_mfma_f32_16x16x32_bf16 v[54:57], v[160:163], v[188:191], v[26:29]
	v_mfma_f32_16x16x32_bf16 v[26:29], v[196:199], v[168:171], v[156:159]
	v_mfma_f32_16x16x32_bf16 v[10:13], v[196:199], v[200:203], v[10:13]
	v_mfma_f32_16x16x32_bf16 v[50:53], v[148:151], v[188:191], v[26:29]
	v_mfma_f32_16x16x32_bf16 v[14:17], v[130:133], v[200:203], v[14:17]
	v_mfma_f32_16x16x32_bf16 v[26:29], v[148:151], v[222:225], v[10:13]
	v_mfma_f32_16x16x32_bf16 v[10:13], v[130:133], v[244:247], v[172:175]
	v_mfma_f32_16x16x32_bf16 v[86:89], v[160:163], v[164:167], v[30:33]
	v_mfma_f32_16x16x32_bf16 v[30:33], v[160:163], v[222:225], v[14:17]
	v_mfma_f32_16x16x32_bf16 v[14:17], v[160:163], v[248:251], v[10:13]
	v_mfma_f32_16x16x32_bf16 v[10:13], v[196:199], v[244:247], v[176:179]
	v_mfma_f32_16x16x32_bf16 v[10:13], v[148:151], v[248:251], v[10:13]
	s_setprio 0
	s_movk_i32 s0, 0x100
	v_cmp_gt_u32_e32 vcc, s0, v142
	s_barrier
	s_and_saveexec_b64 s[0:1], vcc
	s_cbranch_execz .LBB0_81
	s_barrier
	s_branch .LBB0_81

.LBB0_107:
	s_or_b64 exec, exec, s[72:73]
	v_mov_b32_e32 v3, v1
	s_waitcnt vmcnt(8)
	v_lshl_add_u64 v[14:15], s[0:1], 0, v[2:3]
	v_lshl_add_u64 v[18:19], s[12:13], 0, v[2:3]
	v_lshl_add_u64 v[22:23], s[14:15], 0, v[2:3]
	v_lshl_add_u64 v[66:67], s[16:17], 0, v[2:3]
	v_and_b32_e32 v84, 15, v82
	v_bfe_u32 v86, v82, 4, 2
	v_lshlrev_b32_e32 v3, 2, v82
	v_add_u32_e32 v95, 0x18000, v87
	v_lshl_add_u64 v[12:13], s[0:1], 0, v[0:1]
	v_lshl_add_u64 v[16:17], s[12:13], 0, v[0:1]
	v_lshl_add_u64 v[20:21], s[14:15], 0, v[0:1]
	v_lshl_add_u64 v[68:69], s[16:17], 0, v[0:1]
	v_lshlrev_b32_e32 v0, 6, v84
	v_lshlrev_b32_e32 v2, 4, v86
	v_and_b32_e32 v3, 32, v3
	s_mov_b64 s[12:13], 0x80
	v_readfirstlane_b32 s1, v95
	v_add_u32_e32 v96, 0x1a000, v87
	v_bitop3_b32 v24, v2, v3, v0 bitop3:0x36
	v_lshl_add_u64 v[2:3], v[12:13], 0, s[12:13]
	s_mov_b32 m0, s1
	v_readfirstlane_b32 s1, v96
	v_add_u32_e32 v97, 0x8000, v87
	s_waitcnt vmcnt(4)
	s_barrier
	global_load_lds_dwordx4 v[2:3], off
	v_lshl_add_u64 v[2:3], v[14:15], 0, s[12:13]
	s_mov_b32 m0, s1
	v_readfirstlane_b32 s1, v97
	v_add_u32_e32 v98, 0xa000, v87
	global_load_lds_dwordx4 v[2:3], off
	v_lshl_add_u64 v[2:3], v[16:17], 0, s[12:13]
	s_mov_b32 m0, s1
	v_readfirstlane_b32 s1, v98
	v_add_u32_e32 v100, 0x1c000, v87
	global_load_lds_dwordx4 v[2:3], off
	v_lshl_add_u64 v[2:3], v[18:19], 0, s[12:13]
	s_mov_b32 m0, s1
	v_readfirstlane_b32 s1, v100
	v_add_u32_e32 v101, 0x1e000, v87
	global_load_lds_dwordx4 v[2:3], off
	v_lshl_add_u64 v[2:3], v[20:21], 0, s[12:13]
	s_mov_b32 m0, s1
	v_readfirstlane_b32 s1, v101
	global_load_lds_dwordx4 v[2:3], off
	v_lshl_add_u64 v[2:3], v[22:23], 0, s[12:13]
	s_mov_b32 m0, s1
	s_sub_i32 s5, s56, s54
	global_load_lds_dwordx4 v[2:3], off
	s_sub_i32 s5, s5, s77
	s_sext_i32_i16 s5, s5
	s_lshl_b32 s1, s76, 10
	s_lshl_b32 s5, s5, 8
	s_and_b32 s0, s52, 0x80
	s_add_i32 s1, s1, s5
	s_or_b32 s0, s0, s1
	s_ashr_i32 s1, s0, 31
	s_lshl_b64 s[12:13], s[0:1], 12
	s_add_u32 s12, s57, s12
	v_readlane_b32 s36, v253, 33
	s_addc_u32 s13, s63, s13
	v_readlane_b32 s48, v253, 45
	v_readlane_b32 s49, v253, 46
	s_add_u32 s10, s48, s10
	v_lshlrev_b32_e32 v2, 14, v7
	s_addc_u32 s11, s49, s11
	s_addk_i32 s0, 0x80
	v_lshlrev_b32_e32 v0, 14, v4
	v_and_b32_e32 v2, 0x7fff8000, v2
	s_ashr_i32 s1, s0, 31
	v_and_b32_e32 v0, 0x7fff8000, v0
	v_lshl_add_u32 v2, v9, 11, v2
	s_lshl_b64 s[0:1], s[0:1], 12
	v_lshl_add_u32 v0, v5, 11, v0
	v_or_b32_e32 v2, v2, v10
	s_add_u32 s0, s57, s0
	v_bfe_u32 v85, v82, 6, 2
	s_waitcnt vmcnt(6)
	v_or_b32_e32 v0, v0, v6
	v_add_lshl_u32 v2, v2, v11, 1
	v_mov_b32_e32 v3, v1
	s_addc_u32 s1, s63, s1
	v_lshlrev_b32_e32 v25, 13, v83
	v_lshl_or_b32 v26, v85, 12, v212
	v_add_lshl_u32 v0, v0, v8, 1
	v_lshl_add_u64 v[72:73], s[12:13], 0, v[2:3]
	v_lshl_add_u64 v[76:77], s[10:11], 0, v[2:3]
	v_lshl_add_u64 v[80:81], s[0:1], 0, v[2:3]
	v_mov_b32_e32 v2, 0
	v_lshl_add_u64 v[70:71], s[12:13], 0, v[0:1]
	v_lshl_add_u64 v[74:75], s[10:11], 0, v[0:1]
	v_lshl_add_u64 v[78:79], s[0:1], 0, v[0:1]
	s_mov_b32 s0, -2
	s_mov_b64 s[10:11], 0
	v_add_u32_e32 v99, v26, v24
	v_add_u32_e32 v0, v25, v24
	v_mov_b32_e32 v3, v2
	v_mov_b32_e32 v4, v2
	v_mov_b32_e32 v5, v2
	v_mov_b32_e32 v6, v2
	v_mov_b32_e32 v7, v2
	v_mov_b32_e32 v8, v2
	v_mov_b32_e32 v9, v2
	v_mov_b32_e32 v10, v2
	v_mov_b32_e32 v11, v2
	v_mov_b32_e32 v12, v2
	v_mov_b32_e32 v13, v2
	v_mov_b32_e32 v14, v2
	v_mov_b32_e32 v15, v2
	v_mov_b32_e32 v16, v2
	v_mov_b32_e32 v17, v2
	v_mov_b32_e32 v18, v2
	v_mov_b32_e32 v19, v2
	v_mov_b32_e32 v20, v2
	v_mov_b32_e32 v21, v2
	v_mov_b32_e32 v22, v2
	v_mov_b32_e32 v23, v2
	v_mov_b32_e32 v24, v2
	v_mov_b32_e32 v25, v2
	v_mov_b32_e32 v26, v2
	v_mov_b32_e32 v27, v2
	v_mov_b32_e32 v28, v2
	v_mov_b32_e32 v29, v2
	v_mov_b32_e32 v34, v2
	v_mov_b32_e32 v35, v2
	v_mov_b32_e32 v36, v2
	v_mov_b32_e32 v37, v2
	v_mov_b32_e32 v38, v2
	v_mov_b32_e32 v39, v2
	v_mov_b32_e32 v40, v2
	v_mov_b32_e32 v41, v2
	v_mov_b32_e32 v42, v2
	v_mov_b32_e32 v43, v2
	v_mov_b32_e32 v44, v2
	v_mov_b32_e32 v45, v2
	v_mov_b32_e32 v46, v2
	v_mov_b32_e32 v47, v2
	v_mov_b32_e32 v48, v2
	v_mov_b32_e32 v49, v2
	v_mov_b32_e32 v50, v2
	v_mov_b32_e32 v51, v2
	v_mov_b32_e32 v52, v2
	v_mov_b32_e32 v53, v2
	v_mov_b32_e32 v54, v2
	v_mov_b32_e32 v55, v2
	v_mov_b32_e32 v56, v2
	v_mov_b32_e32 v57, v2
	v_mov_b32_e32 v58, v2
	v_mov_b32_e32 v59, v2
	v_mov_b32_e32 v60, v2
	v_mov_b32_e32 v61, v2
	v_mov_b32_e32 v62, v2
	v_mov_b32_e32 v63, v2
	v_mov_b32_e32 v64, v2
	v_mov_b32_e32 v65, v2
	v_mov_b32_e32 v30, v2
	v_mov_b32_e32 v31, v2
	v_mov_b32_e32 v32, v2
	v_mov_b32_e32 v33, v2
	s_barrier
	v_readlane_b32 s37, v253, 34
	v_readlane_b32 s38, v253, 35
	v_readlane_b32 s39, v253, 36
	v_readlane_b32 s40, v253, 37
	v_readlane_b32 s41, v253, 38
	v_readlane_b32 s42, v253, 39
	v_readlane_b32 s43, v253, 40
	v_readlane_b32 s44, v253, 41
	v_readlane_b32 s45, v253, 42
	v_readlane_b32 s46, v253, 43
	v_readlane_b32 s47, v253, 44
	v_readlane_b32 s50, v253, 47
	v_readlane_b32 s51, v253, 48
.LBB0_108:
	ds_read_b128 v[104:107], v99
	ds_read_b128 v[108:111], v99 offset:1024
	ds_read_b128 v[112:115], v99 offset:2048
	ds_read_b128 v[116:119], v99 offset:3072
	v_add_u32_e32 v102, 0xc000, v87
	v_lshl_add_u64 v[152:153], v[74:75], 0, s[10:11]
	v_readfirstlane_b32 s1, v102
	v_lshl_add_u64 v[154:155], v[152:153], 0, s[60:61]
	s_mov_b32 m0, s1
	v_add_u32_e32 v103, 0xe000, v87
	ds_read_b128 v[120:123], v0
	ds_read_b128 v[124:127], v0 offset:1024
	ds_read_b128 v[128:131], v0 offset:2048
	ds_read_b128 v[132:135], v0 offset:3072
	ds_read_b128 v[136:139], v0 offset:4096
	ds_read_b128 v[140:143], v0 offset:5120
	ds_read_b128 v[144:147], v0 offset:6144
	ds_read_b128 v[148:151], v0 offset:7168
	global_load_lds_dwordx4 v[154:155], off
	v_lshl_add_u64 v[154:155], v[76:77], 0, s[10:11]
	v_readfirstlane_b32 s1, v103
	v_lshl_add_u64 v[156:157], v[154:155], 0, s[60:61]
	s_mov_b32 m0, s1
	s_nop 0
	global_load_lds_dwordx4 v[156:157], off
	s_waitcnt lgkmcnt(8)
	s_barrier
	s_waitcnt lgkmcnt(0)
	s_setprio 1
	s_waitcnt lgkmcnt(0)
	v_mfma_f32_16x16x32_bf16 v[62:65], v[104:107], v[120:123], v[62:65]
	v_mfma_f32_16x16x32_bf16 v[58:61], v[112:115], v[120:123], v[58:61]
	v_mfma_f32_16x16x32_bf16 v[54:57], v[104:107], v[128:131], v[54:57]
	v_mfma_f32_16x16x32_bf16 v[50:53], v[112:115], v[128:131], v[50:53]
	v_mfma_f32_16x16x32_bf16 v[46:49], v[104:107], v[136:139], v[46:49]
	v_mfma_f32_16x16x32_bf16 v[42:45], v[112:115], v[136:139], v[42:45]
	v_mfma_f32_16x16x32_bf16 v[38:41], v[104:107], v[144:147], v[38:41]
	v_mfma_f32_16x16x32_bf16 v[34:37], v[112:115], v[144:147], v[34:37]
	v_mfma_f32_16x16x32_bf16 v[62:65], v[108:111], v[124:127], v[62:65]
	v_mfma_f32_16x16x32_bf16 v[58:61], v[116:119], v[124:127], v[58:61]
	v_mfma_f32_16x16x32_bf16 v[54:57], v[108:111], v[132:135], v[54:57]
	v_mfma_f32_16x16x32_bf16 v[50:53], v[116:119], v[132:135], v[50:53]
	v_mfma_f32_16x16x32_bf16 v[46:49], v[108:111], v[140:143], v[46:49]
	v_mfma_f32_16x16x32_bf16 v[42:45], v[116:119], v[140:143], v[42:45]
	v_mfma_f32_16x16x32_bf16 v[38:41], v[108:111], v[148:151], v[38:41]
	v_mfma_f32_16x16x32_bf16 v[34:37], v[116:119], v[148:151], v[34:37]
	s_setprio 0
	s_barrier
	v_lshl_add_u64 v[156:157], v[70:71], 0, s[10:11]
	v_readfirstlane_b32 s1, v89
	v_lshl_add_u64 v[120:121], v[156:157], 0, s[74:75]
	s_mov_b32 m0, s1
	v_lshl_add_u64 v[158:159], v[72:73], 0, s[10:11]
	v_readfirstlane_b32 s1, v90
	global_load_lds_dwordx4 v[120:121], off
	v_lshl_add_u64 v[120:121], v[158:159], 0, s[74:75]
	s_mov_b32 m0, s1
	v_readfirstlane_b32 s1, v87
	global_load_lds_dwordx4 v[120:121], off
	v_lshl_add_u64 v[160:161], v[152:153], 0, s[74:75]
	s_mov_b32 m0, s1
	v_readfirstlane_b32 s1, v88
	s_barrier
	s_waitcnt lgkmcnt(0)
	s_barrier
	ds_read_b128 v[120:123], v0 offset:16384
	ds_read_b128 v[124:127], v0 offset:17408
	ds_read_b128 v[128:131], v0 offset:18432
	ds_read_b128 v[132:135], v0 offset:19456
	ds_read_b128 v[136:139], v0 offset:20480
	ds_read_b128 v[140:143], v0 offset:21504
	ds_read_b128 v[144:147], v0 offset:22528
	ds_read_b128 v[148:151], v0 offset:23552
	global_load_lds_dwordx4 v[160:161], off
	v_lshl_add_u64 v[160:161], v[154:155], 0, s[74:75]
	s_mov_b32 m0, s1
	s_nop 0
	global_load_lds_dwordx4 v[160:161], off
	s_barrier
	s_waitcnt lgkmcnt(0)
	s_setprio 1
	s_waitcnt lgkmcnt(0)
	v_mfma_f32_16x16x32_bf16 v[2:5], v[104:107], v[120:123], v[2:5]
	v_mfma_f32_16x16x32_bf16 v[6:9], v[112:115], v[120:123], v[6:9]
	v_mfma_f32_16x16x32_bf16 v[10:13], v[104:107], v[128:131], v[10:13]
	v_mfma_f32_16x16x32_bf16 v[14:17], v[112:115], v[128:131], v[14:17]
	v_mfma_f32_16x16x32_bf16 v[18:21], v[104:107], v[136:139], v[18:21]
	v_mfma_f32_16x16x32_bf16 v[22:25], v[112:115], v[136:139], v[22:25]
	v_mfma_f32_16x16x32_bf16 v[26:29], v[104:107], v[144:147], v[26:29]
	v_mfma_f32_16x16x32_bf16 v[30:33], v[112:115], v[144:147], v[30:33]
	v_mfma_f32_16x16x32_bf16 v[2:5], v[108:111], v[124:127], v[2:5]
	v_mfma_f32_16x16x32_bf16 v[6:9], v[116:119], v[124:127], v[6:9]
	v_mfma_f32_16x16x32_bf16 v[10:13], v[108:111], v[132:135], v[10:13]
	v_mfma_f32_16x16x32_bf16 v[14:17], v[116:119], v[132:135], v[14:17]
	v_mfma_f32_16x16x32_bf16 v[18:21], v[108:111], v[140:143], v[18:21]
	v_mfma_f32_16x16x32_bf16 v[22:25], v[116:119], v[140:143], v[22:25]
	v_mfma_f32_16x16x32_bf16 v[26:29], v[108:111], v[148:151], v[26:29]
	v_mfma_f32_16x16x32_bf16 v[30:33], v[116:119], v[148:151], v[30:33]
	s_setprio 0
	s_barrier
	v_lshl_add_u64 v[160:161], v[78:79], 0, s[10:11]
	v_readfirstlane_b32 s1, v91
	v_lshl_add_u64 v[104:105], v[160:161], 0, s[74:75]
	s_mov_b32 m0, s1
	v_lshl_add_u64 v[162:163], v[80:81], 0, s[10:11]
	v_readfirstlane_b32 s1, v92
	global_load_lds_dwordx4 v[104:105], off
	v_lshl_add_u64 v[104:105], v[162:163], 0, s[74:75]
	s_mov_b32 m0, s1
	s_nop 0
	global_load_lds_dwordx4 v[104:105], off
	s_waitcnt vmcnt(6)
	s_barrier
	s_barrier
	ds_read_b128 v[104:107], v99 offset:32768
	ds_read_b128 v[108:111], v99 offset:33792
	ds_read_b128 v[112:115], v99 offset:34816
	ds_read_b128 v[116:119], v99 offset:35840
	v_readfirstlane_b32 s1, v93
	v_lshl_add_u64 v[164:165], v[152:153], 0, s[18:19]
	s_mov_b32 m0, s1
	v_readfirstlane_b32 s1, v94
	ds_read_b128 v[120:123], v0 offset:32768
	ds_read_b128 v[124:127], v0 offset:33792
	ds_read_b128 v[128:131], v0 offset:34816
	ds_read_b128 v[132:135], v0 offset:35840
	ds_read_b128 v[136:139], v0 offset:36864
	ds_read_b128 v[140:143], v0 offset:37888
	ds_read_b128 v[144:147], v0 offset:38912
	ds_read_b128 v[148:151], v0 offset:39936
	global_load_lds_dwordx4 v[164:165], off
	v_lshl_add_u64 v[164:165], v[154:155], 0, s[18:19]
	s_mov_b32 m0, s1
	s_nop 0
	global_load_lds_dwordx4 v[164:165], off
	s_waitcnt lgkmcnt(8)
	s_barrier
	s_waitcnt lgkmcnt(0)
	s_setprio 1
	s_waitcnt lgkmcnt(0)
	v_mfma_f32_16x16x32_bf16 v[62:65], v[104:107], v[120:123], v[62:65]
	v_mfma_f32_16x16x32_bf16 v[58:61], v[112:115], v[120:123], v[58:61]
	v_mfma_f32_16x16x32_bf16 v[54:57], v[104:107], v[128:131], v[54:57]
	v_mfma_f32_16x16x32_bf16 v[50:53], v[112:115], v[128:131], v[50:53]
	v_mfma_f32_16x16x32_bf16 v[46:49], v[104:107], v[136:139], v[46:49]
	v_mfma_f32_16x16x32_bf16 v[42:45], v[112:115], v[136:139], v[42:45]
	v_mfma_f32_16x16x32_bf16 v[38:41], v[104:107], v[144:147], v[38:41]
	v_mfma_f32_16x16x32_bf16 v[34:37], v[112:115], v[144:147], v[34:37]
	v_mfma_f32_16x16x32_bf16 v[62:65], v[108:111], v[124:127], v[62:65]
	v_mfma_f32_16x16x32_bf16 v[58:61], v[116:119], v[124:127], v[58:61]
	v_mfma_f32_16x16x32_bf16 v[54:57], v[108:111], v[132:135], v[54:57]
	v_mfma_f32_16x16x32_bf16 v[50:53], v[116:119], v[132:135], v[50:53]
	v_mfma_f32_16x16x32_bf16 v[46:49], v[108:111], v[140:143], v[46:49]
	v_mfma_f32_16x16x32_bf16 v[42:45], v[116:119], v[140:143], v[42:45]
	v_mfma_f32_16x16x32_bf16 v[38:41], v[108:111], v[148:151], v[38:41]
	v_mfma_f32_16x16x32_bf16 v[34:37], v[116:119], v[148:151], v[34:37]
	s_setprio 0
	s_barrier
	v_readfirstlane_b32 s1, v95
	v_lshl_add_u64 v[120:121], v[156:157], 0, s[28:29]
	s_mov_b32 m0, s1
	v_readfirstlane_b32 s1, v96
	global_load_lds_dwordx4 v[120:121], off
	v_lshl_add_u64 v[120:121], v[158:159], 0, s[28:29]
	s_mov_b32 m0, s1
	v_readfirstlane_b32 s1, v97
	global_load_lds_dwordx4 v[120:121], off
	v_lshl_add_u64 v[152:153], v[152:153], 0, s[28:29]
	s_mov_b32 m0, s1
	v_readfirstlane_b32 s1, v98
	s_barrier
	s_waitcnt lgkmcnt(0)
	s_barrier
	ds_read_b128 v[120:123], v0 offset:49152
	ds_read_b128 v[124:127], v0 offset:50176
	ds_read_b128 v[128:131], v0 offset:51200
	ds_read_b128 v[132:135], v0 offset:52224
	ds_read_b128 v[136:139], v0 offset:53248
	ds_read_b128 v[140:143], v0 offset:54272
	ds_read_b128 v[144:147], v0 offset:55296
	ds_read_b128 v[148:151], v0 offset:56320
	global_load_lds_dwordx4 v[152:153], off
	v_lshl_add_u64 v[152:153], v[154:155], 0, s[28:29]
	s_mov_b32 m0, s1
	s_nop 0
	global_load_lds_dwordx4 v[152:153], off
	s_barrier
	s_waitcnt lgkmcnt(0)
	s_setprio 1
	s_waitcnt lgkmcnt(0)
	v_mfma_f32_16x16x32_bf16 v[2:5], v[104:107], v[120:123], v[2:5]
	v_mfma_f32_16x16x32_bf16 v[6:9], v[112:115], v[120:123], v[6:9]
	v_mfma_f32_16x16x32_bf16 v[10:13], v[104:107], v[128:131], v[10:13]
	v_mfma_f32_16x16x32_bf16 v[14:17], v[112:115], v[128:131], v[14:17]
	v_mfma_f32_16x16x32_bf16 v[18:21], v[104:107], v[136:139], v[18:21]
	v_mfma_f32_16x16x32_bf16 v[22:25], v[112:115], v[136:139], v[22:25]
	v_mfma_f32_16x16x32_bf16 v[26:29], v[104:107], v[144:147], v[26:29]
	v_mfma_f32_16x16x32_bf16 v[30:33], v[112:115], v[144:147], v[30:33]
	v_mfma_f32_16x16x32_bf16 v[2:5], v[108:111], v[124:127], v[2:5]
	v_mfma_f32_16x16x32_bf16 v[6:9], v[116:119], v[124:127], v[6:9]
	v_mfma_f32_16x16x32_bf16 v[10:13], v[108:111], v[132:135], v[10:13]
	v_mfma_f32_16x16x32_bf16 v[14:17], v[116:119], v[132:135], v[14:17]
	v_mfma_f32_16x16x32_bf16 v[18:21], v[108:111], v[140:143], v[18:21]
	v_mfma_f32_16x16x32_bf16 v[22:25], v[116:119], v[140:143], v[22:25]
	v_mfma_f32_16x16x32_bf16 v[26:29], v[108:111], v[148:151], v[26:29]
	v_mfma_f32_16x16x32_bf16 v[30:33], v[116:119], v[148:151], v[30:33]
	s_setprio 0
	s_barrier
	v_readfirstlane_b32 s1, v100
	v_lshl_add_u64 v[104:105], v[160:161], 0, s[28:29]
	s_mov_b32 m0, s1
	v_readfirstlane_b32 s1, v101
	global_load_lds_dwordx4 v[104:105], off
	v_lshl_add_u64 v[104:105], v[162:163], 0, s[28:29]
	s_mov_b32 m0, s1
	s_add_i32 s0, s0, 2
	global_load_lds_dwordx4 v[104:105], off
	s_waitcnt vmcnt(6)
	s_add_u32 s10, s10, 0x100
	s_addc_u32 s11, s11, 0
	s_cmp_lt_u32 s0, 28
	s_barrier
	s_barrier
	s_cbranch_scc1 .LBB0_108
	s_mov_b64 s[10:11], 0xf80
	v_readfirstlane_b32 s0, v102
	v_lshl_add_u64 v[68:69], v[68:69], 0, s[10:11]
	s_mov_b32 m0, s0
	v_readfirstlane_b32 s0, v103
	ds_read_b128 v[70:73], v99
	ds_read_b128 v[74:77], v99 offset:1024
	ds_read_b128 v[78:81], v99 offset:2048
	ds_read_b128 v[88:91], v99 offset:3072
	ds_read_b128 v[92:95], v0
	ds_read_b128 v[104:107], v0 offset:1024
	ds_read_b128 v[108:111], v0 offset:2048
	ds_read_b128 v[112:115], v0 offset:3072
	ds_read_b128 v[116:119], v0 offset:4096
	ds_read_b128 v[120:123], v0 offset:5120
	ds_read_b128 v[124:127], v0 offset:6144
	ds_read_b128 v[128:131], v0 offset:7168
	global_load_lds_dwordx4 v[68:69], off
	v_lshl_add_u64 v[66:67], v[66:67], 0, s[10:11]
	s_mov_b32 m0, s0
	s_nop 0
	global_load_lds_dwordx4 v[66:67], off
	s_barrier
	s_waitcnt lgkmcnt(0)
	s_setprio 1
	s_waitcnt lgkmcnt(0)
	v_mfma_f32_16x16x32_bf16 v[62:65], v[70:73], v[92:95], v[62:65]
	v_mfma_f32_16x16x32_bf16 v[58:61], v[78:81], v[92:95], v[58:61]
	v_mfma_f32_16x16x32_bf16 v[54:57], v[70:73], v[108:111], v[54:57]
	v_mfma_f32_16x16x32_bf16 v[50:53], v[78:81], v[108:111], v[50:53]
	v_mfma_f32_16x16x32_bf16 v[46:49], v[70:73], v[116:119], v[46:49]
	v_mfma_f32_16x16x32_bf16 v[42:45], v[78:81], v[116:119], v[42:45]
	v_mfma_f32_16x16x32_bf16 v[38:41], v[70:73], v[124:127], v[38:41]
	v_mfma_f32_16x16x32_bf16 v[34:37], v[78:81], v[124:127], v[34:37]
	v_mfma_f32_16x16x32_bf16 v[62:65], v[74:77], v[104:107], v[62:65]
	v_mfma_f32_16x16x32_bf16 v[58:61], v[88:91], v[104:107], v[58:61]
	v_mfma_f32_16x16x32_bf16 v[54:57], v[74:77], v[112:115], v[54:57]
	v_mfma_f32_16x16x32_bf16 v[50:53], v[88:91], v[112:115], v[50:53]
	v_mfma_f32_16x16x32_bf16 v[46:49], v[74:77], v[120:123], v[46:49]
	v_mfma_f32_16x16x32_bf16 v[42:45], v[88:91], v[120:123], v[42:45]
	v_mfma_f32_16x16x32_bf16 v[38:41], v[74:77], v[128:131], v[38:41]
	v_mfma_f32_16x16x32_bf16 v[34:37], v[88:91], v[128:131], v[34:37]
	s_setprio 0
	s_barrier
	s_barrier
	s_waitcnt lgkmcnt(0)
	s_barrier
	ds_read_b128 v[66:69], v0 offset:16384
	ds_read_b128 v[92:95], v0 offset:17408
	ds_read_b128 v[100:103], v0 offset:18432
	ds_read_b128 v[104:107], v0 offset:19456
	ds_read_b128 v[108:111], v0 offset:20480
	ds_read_b128 v[112:115], v0 offset:21504
	ds_read_b128 v[116:119], v0 offset:22528
	ds_read_b128 v[120:123], v0 offset:23552
	s_waitcnt vmcnt(4)
	s_barrier
	s_waitcnt lgkmcnt(0)
	s_setprio 1
	s_waitcnt lgkmcnt(3)
	v_mfma_f32_16x16x32_bf16 v[18:21], v[70:73], v[108:111], v[18:21]
	v_mfma_f32_16x16x32_bf16 v[2:5], v[70:73], v[66:69], v[2:5]
	v_mfma_f32_16x16x32_bf16 v[6:9], v[78:81], v[66:69], v[6:9]
	s_waitcnt lgkmcnt(2)
	v_mfma_f32_16x16x32_bf16 v[66:69], v[74:77], v[112:115], v[18:21]
	v_mfma_f32_16x16x32_bf16 v[18:21], v[78:81], v[108:111], v[22:25]
	v_mfma_f32_16x16x32_bf16 v[2:5], v[74:77], v[92:95], v[2:5]
	v_mfma_f32_16x16x32_bf16 v[6:9], v[88:91], v[92:95], v[6:9]
	v_mfma_f32_16x16x32_bf16 v[10:13], v[70:73], v[100:103], v[10:13]
	v_mfma_f32_16x16x32_bf16 v[14:17], v[78:81], v[100:103], v[14:17]
	v_mfma_f32_16x16x32_bf16 v[92:95], v[88:91], v[112:115], v[18:21]
	s_waitcnt lgkmcnt(1)
	v_mfma_f32_16x16x32_bf16 v[18:21], v[70:73], v[116:119], v[26:29]
	v_mfma_f32_16x16x32_bf16 v[10:13], v[74:77], v[104:107], v[10:13]
	v_mfma_f32_16x16x32_bf16 v[14:17], v[88:91], v[104:107], v[14:17]
	s_waitcnt lgkmcnt(0)
	v_mfma_f32_16x16x32_bf16 v[70:73], v[74:77], v[120:123], v[18:21]
	v_mfma_f32_16x16x32_bf16 v[18:21], v[78:81], v[116:119], v[30:33]
	v_mfma_f32_16x16x32_bf16 v[74:77], v[88:91], v[120:123], v[18:21]
	s_setprio 0
	s_barrier
	ds_read_b128 v[78:81], v99 offset:32768
	ds_read_b128 v[88:91], v99 offset:33792
	ds_read_b128 v[100:103], v99 offset:34816
	ds_read_b128 v[96:99], v99 offset:35840
	s_nop 0
	ds_read_b128 v[18:21], v0 offset:32768
	ds_read_b128 v[22:25], v0 offset:33792
	ds_read_b128 v[26:29], v0 offset:34816
	ds_read_b128 v[30:33], v0 offset:35840
	ds_read_b128 v[104:107], v0 offset:36864
	ds_read_b128 v[108:111], v0 offset:37888
	ds_read_b128 v[112:115], v0 offset:38912
	ds_read_b128 v[116:119], v0 offset:39936
	s_waitcnt vmcnt(2)
	s_barrier
	s_waitcnt lgkmcnt(0)
	s_setprio 1
	s_waitcnt lgkmcnt(7)
	v_mfma_f32_16x16x32_bf16 v[62:65], v[78:81], v[18:21], v[62:65]
	v_mfma_f32_16x16x32_bf16 v[18:21], v[100:103], v[18:21], v[58:61]
	s_waitcnt lgkmcnt(6)
	v_mfma_f32_16x16x32_bf16 v[58:61], v[96:99], v[22:25], v[18:21]
	s_waitcnt lgkmcnt(5)
	v_mfma_f32_16x16x32_bf16 v[18:21], v[78:81], v[26:29], v[54:57]
	s_waitcnt lgkmcnt(4)
	v_mfma_f32_16x16x32_bf16 v[54:57], v[88:91], v[30:33], v[18:21]
	v_mfma_f32_16x16x32_bf16 v[18:21], v[100:103], v[26:29], v[50:53]
	v_mfma_f32_16x16x32_bf16 v[50:53], v[96:99], v[30:33], v[18:21]
	s_waitcnt lgkmcnt(3)
	v_mfma_f32_16x16x32_bf16 v[18:21], v[78:81], v[104:107], v[46:49]
	s_waitcnt lgkmcnt(2)
	v_mfma_f32_16x16x32_bf16 v[46:49], v[88:91], v[108:111], v[18:21]
	v_mfma_f32_16x16x32_bf16 v[18:21], v[100:103], v[104:107], v[42:45]
	v_mfma_f32_16x16x32_bf16 v[42:45], v[96:99], v[108:111], v[18:21]
	s_waitcnt lgkmcnt(1)
	v_mfma_f32_16x16x32_bf16 v[18:21], v[78:81], v[112:115], v[38:41]
	s_waitcnt lgkmcnt(0)
	v_mfma_f32_16x16x32_bf16 v[38:41], v[88:91], v[116:119], v[18:21]
	v_mfma_f32_16x16x32_bf16 v[18:21], v[100:103], v[112:115], v[34:37]
	v_mfma_f32_16x16x32_bf16 v[62:65], v[88:91], v[22:25], v[62:65]
	v_mfma_f32_16x16x32_bf16 v[34:37], v[96:99], v[116:119], v[18:21]
	s_setprio 0
	s_barrier
	s_waitcnt vmcnt(0)
	s_barrier
	s_waitcnt lgkmcnt(0)
	s_barrier
	s_nop 1
	ds_read_b128 v[18:21], v0 offset:49152
	ds_read_b128 v[22:25], v0 offset:50176
	ds_read_b128 v[104:107], v0 offset:51200
	ds_read_b128 v[108:111], v0 offset:52224
	ds_read_b128 v[112:115], v0 offset:53248
	ds_read_b128 v[116:119], v0 offset:54272
	ds_read_b128 v[120:123], v0 offset:55296
	ds_read_b128 v[124:127], v0 offset:56320
	s_barrier
	s_waitcnt lgkmcnt(0)
	s_setprio 1
	s_waitcnt lgkmcnt(7)
	v_mfma_f32_16x16x32_bf16 v[2:5], v[78:81], v[18:21], v[2:5]
	s_waitcnt lgkmcnt(6)
	v_mfma_f32_16x16x32_bf16 v[30:33], v[88:91], v[22:25], v[2:5]
	v_mfma_f32_16x16x32_bf16 v[2:5], v[100:103], v[18:21], v[6:9]
	v_mfma_f32_16x16x32_bf16 v[26:29], v[96:99], v[22:25], v[2:5]
	s_waitcnt lgkmcnt(5)
	v_mfma_f32_16x16x32_bf16 v[2:5], v[78:81], v[104:107], v[10:13]
	s_waitcnt lgkmcnt(4)
	v_mfma_f32_16x16x32_bf16 v[22:25], v[88:91], v[108:111], v[2:5]
	v_mfma_f32_16x16x32_bf16 v[2:5], v[100:103], v[104:107], v[14:17]
	v_mfma_f32_16x16x32_bf16 v[18:21], v[96:99], v[108:111], v[2:5]
	s_waitcnt lgkmcnt(3)
	v_mfma_f32_16x16x32_bf16 v[2:5], v[78:81], v[112:115], v[66:69]
	s_waitcnt lgkmcnt(2)
	v_mfma_f32_16x16x32_bf16 v[14:17], v[88:91], v[116:119], v[2:5]
	v_mfma_f32_16x16x32_bf16 v[2:5], v[100:103], v[112:115], v[92:95]
	v_mfma_f32_16x16x32_bf16 v[10:13], v[96:99], v[116:119], v[2:5]
	s_waitcnt lgkmcnt(1)
	v_mfma_f32_16x16x32_bf16 v[2:5], v[78:81], v[120:123], v[70:73]
	s_waitcnt lgkmcnt(0)
	v_mfma_f32_16x16x32_bf16 v[6:9], v[88:91], v[124:127], v[2:5]
	v_mfma_f32_16x16x32_bf16 v[2:5], v[100:103], v[120:123], v[74:77]
	v_mfma_f32_16x16x32_bf16 v[2:5], v[96:99], v[124:127], v[2:5]
	s_setprio 0
	s_movk_i32 s0, 0x100
	v_cmp_gt_u32_e32 vcc, s0, v82
	s_barrier
	s_and_saveexec_b64 s[0:1], vcc
	s_cbranch_execz .LBB0_111
	s_barrier

.LBB0_180:
	ds_read_b128 v[164:167], v151
	ds_read_b128 v[168:171], v151 offset:1024
	ds_read_b128 v[172:175], v151 offset:2048
	ds_read_b128 v[176:179], v151 offset:3072
	v_add_u32_e32 v162, 0xc000, v147
	v_lshl_add_u64 v[204:205], v[138:139], 0, s[12:13]
	v_readfirstlane_b32 s1, v162
	v_lshl_add_u64 v[210:211], v[204:205], 0, s[60:61]
	s_mov_b32 m0, s1
	v_add_u32_e32 v163, 0xe000, v147
	ds_read_b128 v[180:183], v0
	ds_read_b128 v[184:187], v0 offset:1024
	ds_read_b128 v[188:191], v0 offset:2048
	ds_read_b128 v[192:195], v0 offset:3072
	ds_read_b128 v[196:199], v0 offset:4096
	ds_read_b128 v[200:203], v0 offset:5120
	ds_read_b128 v[222:225], v0 offset:6144
	ds_read_b128 v[232:235], v0 offset:7168
	global_load_lds_dwordx4 v[210:211], off
	v_lshl_add_u64 v[210:211], v[140:141], 0, s[12:13]
	v_readfirstlane_b32 s1, v163
	v_lshl_add_u64 v[216:217], v[210:211], 0, s[60:61]
	s_mov_b32 m0, s1
	s_nop 0
	global_load_lds_dwordx4 v[216:217], off
	s_waitcnt lgkmcnt(8)
	s_barrier
	s_waitcnt lgkmcnt(0)
	s_setprio 1
	s_waitcnt lgkmcnt(0)
	v_mfma_f32_16x16x32_bf16 v[126:129], v[164:167], v[180:183], v[126:129]
	v_mfma_f32_16x16x32_bf16 v[122:125], v[172:175], v[180:183], v[122:125]
	v_mfma_f32_16x16x32_bf16 v[118:121], v[164:167], v[188:191], v[118:121]
	v_mfma_f32_16x16x32_bf16 v[114:117], v[172:175], v[188:191], v[114:117]
	v_mfma_f32_16x16x32_bf16 v[110:113], v[164:167], v[196:199], v[110:113]
	v_mfma_f32_16x16x32_bf16 v[106:109], v[172:175], v[196:199], v[106:109]
	v_mfma_f32_16x16x32_bf16 v[102:105], v[164:167], v[222:225], v[102:105]
	v_mfma_f32_16x16x32_bf16 v[98:101], v[172:175], v[222:225], v[98:101]
	v_mfma_f32_16x16x32_bf16 v[126:129], v[168:171], v[184:187], v[126:129]
	v_mfma_f32_16x16x32_bf16 v[122:125], v[176:179], v[184:187], v[122:125]
	v_mfma_f32_16x16x32_bf16 v[118:121], v[168:171], v[192:195], v[118:121]
	v_mfma_f32_16x16x32_bf16 v[114:117], v[176:179], v[192:195], v[114:117]
	v_mfma_f32_16x16x32_bf16 v[110:113], v[168:171], v[200:203], v[110:113]
	v_mfma_f32_16x16x32_bf16 v[106:109], v[176:179], v[200:203], v[106:109]
	v_mfma_f32_16x16x32_bf16 v[102:105], v[168:171], v[232:235], v[102:105]
	v_mfma_f32_16x16x32_bf16 v[98:101], v[176:179], v[232:235], v[98:101]
	s_setprio 0
	s_barrier
	v_lshl_add_u64 v[216:217], v[134:135], 0, s[12:13]
	v_readfirstlane_b32 s1, v149
	v_lshl_add_u64 v[218:219], v[216:217], 0, s[74:75]
	s_mov_b32 m0, s1
	ds_read_b128 v[236:239], v151 offset:16384
	ds_read_b128 v[240:243], v151 offset:17408
	ds_read_b128 v[244:247], v151 offset:18432
	ds_read_b128 v[248:251], v151 offset:19456
	global_load_lds_dwordx4 v[218:219], off
	v_lshl_add_u64 v[218:219], v[136:137], 0, s[12:13]
	v_readfirstlane_b32 s1, v150
	v_lshl_add_u64 v[228:229], v[218:219], 0, s[74:75]
	s_mov_b32 m0, s1
	s_nop 0
	global_load_lds_dwordx4 v[228:229], off
	s_barrier
	s_waitcnt lgkmcnt(0)
	s_setprio 1
	s_waitcnt lgkmcnt(0)
	v_mfma_f32_16x16x32_bf16 v[94:97], v[236:239], v[180:183], v[94:97]
	v_mfma_f32_16x16x32_bf16 v[90:93], v[244:247], v[180:183], v[90:93]
	v_mfma_f32_16x16x32_bf16 v[86:89], v[236:239], v[188:191], v[86:89]
	v_mfma_f32_16x16x32_bf16 v[82:85], v[244:247], v[188:191], v[82:85]
	v_mfma_f32_16x16x32_bf16 v[78:81], v[236:239], v[196:199], v[78:81]
	v_mfma_f32_16x16x32_bf16 v[74:77], v[244:247], v[196:199], v[74:77]
	v_mfma_f32_16x16x32_bf16 v[70:73], v[236:239], v[222:225], v[70:73]
	v_mfma_f32_16x16x32_bf16 v[66:69], v[244:247], v[222:225], v[66:69]
	v_mfma_f32_16x16x32_bf16 v[94:97], v[240:243], v[184:187], v[94:97]
	v_mfma_f32_16x16x32_bf16 v[90:93], v[248:251], v[184:187], v[90:93]
	v_mfma_f32_16x16x32_bf16 v[86:89], v[240:243], v[192:195], v[86:89]
	v_mfma_f32_16x16x32_bf16 v[82:85], v[248:251], v[192:195], v[82:85]
	v_mfma_f32_16x16x32_bf16 v[78:81], v[240:243], v[200:203], v[78:81]
	v_mfma_f32_16x16x32_bf16 v[74:77], v[248:251], v[200:203], v[74:77]
	v_mfma_f32_16x16x32_bf16 v[70:73], v[240:243], v[232:235], v[70:73]
	v_mfma_f32_16x16x32_bf16 v[66:69], v[248:251], v[232:235], v[66:69]
	s_setprio 0
	v_readfirstlane_b32 s1, v147
	v_lshl_add_u64 v[228:229], v[204:205], 0, s[74:75]
	s_mov_b32 m0, s1
	v_readfirstlane_b32 s1, v148
	s_barrier
	ds_read_b128 v[180:183], v0 offset:16384
	ds_read_b128 v[184:187], v0 offset:17408
	ds_read_b128 v[188:191], v0 offset:18432
	ds_read_b128 v[192:195], v0 offset:19456
	ds_read_b128 v[196:199], v0 offset:20480
	ds_read_b128 v[200:203], v0 offset:21504
	ds_read_b128 v[222:225], v0 offset:22528
	ds_read_b128 v[232:235], v0 offset:23552
	global_load_lds_dwordx4 v[228:229], off
	v_lshl_add_u64 v[228:229], v[210:211], 0, s[74:75]
	s_mov_b32 m0, s1
	s_nop 0
	global_load_lds_dwordx4 v[228:229], off
	s_barrier
	s_waitcnt lgkmcnt(0)
	s_setprio 1
	s_waitcnt lgkmcnt(0)
	v_mfma_f32_16x16x32_bf16 v[62:65], v[164:167], v[180:183], v[62:65]
	v_mfma_f32_16x16x32_bf16 v[58:61], v[172:175], v[180:183], v[58:61]
	v_mfma_f32_16x16x32_bf16 v[54:57], v[164:167], v[188:191], v[54:57]
	v_mfma_f32_16x16x32_bf16 v[50:53], v[172:175], v[188:191], v[50:53]
	v_mfma_f32_16x16x32_bf16 v[46:49], v[164:167], v[196:199], v[46:49]
	v_mfma_f32_16x16x32_bf16 v[42:45], v[172:175], v[196:199], v[42:45]
	v_mfma_f32_16x16x32_bf16 v[38:41], v[164:167], v[222:225], v[38:41]
	v_mfma_f32_16x16x32_bf16 v[34:37], v[172:175], v[222:225], v[34:37]
	v_mfma_f32_16x16x32_bf16 v[62:65], v[168:171], v[184:187], v[62:65]
	v_mfma_f32_16x16x32_bf16 v[58:61], v[176:179], v[184:187], v[58:61]
	v_mfma_f32_16x16x32_bf16 v[54:57], v[168:171], v[192:195], v[54:57]
	v_mfma_f32_16x16x32_bf16 v[50:53], v[176:179], v[192:195], v[50:53]
	v_mfma_f32_16x16x32_bf16 v[46:49], v[168:171], v[200:203], v[46:49]
	v_mfma_f32_16x16x32_bf16 v[42:45], v[176:179], v[200:203], v[42:45]
	v_mfma_f32_16x16x32_bf16 v[38:41], v[168:171], v[232:235], v[38:41]
	v_mfma_f32_16x16x32_bf16 v[34:37], v[176:179], v[232:235], v[34:37]
	s_setprio 0
	s_barrier
	v_readfirstlane_b32 s1, v152
	v_lshl_add_u64 v[164:165], v[216:217], 0, s[18:19]
	s_mov_b32 m0, s1
	v_readfirstlane_b32 s1, v153
	global_load_lds_dwordx4 v[164:165], off
	v_lshl_add_u64 v[164:165], v[218:219], 0, s[18:19]
	s_mov_b32 m0, s1
	s_nop 0
	global_load_lds_dwordx4 v[164:165], off
	s_waitcnt vmcnt(6)
	s_barrier
	s_setprio 1
	v_mfma_f32_16x16x32_bf16 v[30:33], v[236:239], v[180:183], v[30:33]
	v_mfma_f32_16x16x32_bf16 v[26:29], v[244:247], v[180:183], v[26:29]
	v_mfma_f32_16x16x32_bf16 v[22:25], v[236:239], v[188:191], v[22:25]
	v_mfma_f32_16x16x32_bf16 v[18:21], v[244:247], v[188:191], v[18:21]
	v_mfma_f32_16x16x32_bf16 v[14:17], v[236:239], v[196:199], v[14:17]
	v_mfma_f32_16x16x32_bf16 v[10:13], v[244:247], v[196:199], v[10:13]
	v_mfma_f32_16x16x32_bf16 v[6:9], v[236:239], v[222:225], v[6:9]
	v_mfma_f32_16x16x32_bf16 v[2:5], v[244:247], v[222:225], v[2:5]
	v_mfma_f32_16x16x32_bf16 v[30:33], v[240:243], v[184:187], v[30:33]
	v_mfma_f32_16x16x32_bf16 v[26:29], v[248:251], v[184:187], v[26:29]
	v_mfma_f32_16x16x32_bf16 v[22:25], v[240:243], v[192:195], v[22:25]
	v_mfma_f32_16x16x32_bf16 v[18:21], v[248:251], v[192:195], v[18:21]
	v_mfma_f32_16x16x32_bf16 v[14:17], v[240:243], v[200:203], v[14:17]
	v_mfma_f32_16x16x32_bf16 v[10:13], v[248:251], v[200:203], v[10:13]
	v_mfma_f32_16x16x32_bf16 v[6:9], v[240:243], v[232:235], v[6:9]
	v_mfma_f32_16x16x32_bf16 v[2:5], v[248:251], v[232:235], v[2:5]
	s_setprio 0
	s_barrier
	ds_read_b128 v[164:167], v151 offset:32768
	ds_read_b128 v[168:171], v151 offset:33792
	ds_read_b128 v[172:175], v151 offset:34816
	ds_read_b128 v[176:179], v151 offset:35840
	v_readfirstlane_b32 s1, v154
	v_lshl_add_u64 v[228:229], v[204:205], 0, s[18:19]
	s_mov_b32 m0, s1
	v_readfirstlane_b32 s1, v155
	ds_read_b128 v[180:183], v0 offset:32768
	ds_read_b128 v[184:187], v0 offset:33792
	ds_read_b128 v[188:191], v0 offset:34816
	ds_read_b128 v[192:195], v0 offset:35840
	ds_read_b128 v[196:199], v0 offset:36864
	ds_read_b128 v[200:203], v0 offset:37888
	ds_read_b128 v[222:225], v0 offset:38912
	ds_read_b128 v[232:235], v0 offset:39936
	global_load_lds_dwordx4 v[228:229], off
	v_lshl_add_u64 v[228:229], v[210:211], 0, s[18:19]
	s_mov_b32 m0, s1
	s_nop 0
	global_load_lds_dwordx4 v[228:229], off
	s_waitcnt lgkmcnt(8)
	s_barrier
	s_waitcnt lgkmcnt(0)
	s_setprio 1
	s_waitcnt lgkmcnt(0)
	v_mfma_f32_16x16x32_bf16 v[126:129], v[164:167], v[180:183], v[126:129]
	v_mfma_f32_16x16x32_bf16 v[122:125], v[172:175], v[180:183], v[122:125]
	v_mfma_f32_16x16x32_bf16 v[118:121], v[164:167], v[188:191], v[118:121]
	v_mfma_f32_16x16x32_bf16 v[114:117], v[172:175], v[188:191], v[114:117]
	v_mfma_f32_16x16x32_bf16 v[110:113], v[164:167], v[196:199], v[110:113]
	v_mfma_f32_16x16x32_bf16 v[106:109], v[172:175], v[196:199], v[106:109]
	v_mfma_f32_16x16x32_bf16 v[102:105], v[164:167], v[222:225], v[102:105]
	v_mfma_f32_16x16x32_bf16 v[98:101], v[172:175], v[222:225], v[98:101]
	v_mfma_f32_16x16x32_bf16 v[126:129], v[168:171], v[184:187], v[126:129]
	v_mfma_f32_16x16x32_bf16 v[122:125], v[176:179], v[184:187], v[122:125]
	v_mfma_f32_16x16x32_bf16 v[118:121], v[168:171], v[192:195], v[118:121]
	v_mfma_f32_16x16x32_bf16 v[114:117], v[176:179], v[192:195], v[114:117]
	v_mfma_f32_16x16x32_bf16 v[110:113], v[168:171], v[200:203], v[110:113]
	v_mfma_f32_16x16x32_bf16 v[106:109], v[176:179], v[200:203], v[106:109]
	v_mfma_f32_16x16x32_bf16 v[102:105], v[168:171], v[232:235], v[102:105]
	v_mfma_f32_16x16x32_bf16 v[98:101], v[176:179], v[232:235], v[98:101]
	s_setprio 0
	s_barrier
	v_readfirstlane_b32 s1, v156
	v_lshl_add_u64 v[228:229], v[216:217], 0, s[28:29]
	s_mov_b32 m0, s1
	v_readfirstlane_b32 s1, v157
	ds_read_b128 v[236:239], v151 offset:49152
	ds_read_b128 v[240:243], v151 offset:50176
	ds_read_b128 v[244:247], v151 offset:51200
	ds_read_b128 v[248:251], v151 offset:52224
	global_load_lds_dwordx4 v[228:229], off
	v_lshl_add_u64 v[228:229], v[218:219], 0, s[28:29]
	s_mov_b32 m0, s1
	s_nop 0
	global_load_lds_dwordx4 v[228:229], off
	s_barrier
	s_waitcnt lgkmcnt(0)
	s_setprio 1
	s_waitcnt lgkmcnt(0)
	v_mfma_f32_16x16x32_bf16 v[94:97], v[236:239], v[180:183], v[94:97]
	v_mfma_f32_16x16x32_bf16 v[90:93], v[244:247], v[180:183], v[90:93]
	v_mfma_f32_16x16x32_bf16 v[86:89], v[236:239], v[188:191], v[86:89]
	v_mfma_f32_16x16x32_bf16 v[82:85], v[244:247], v[188:191], v[82:85]
	v_mfma_f32_16x16x32_bf16 v[78:81], v[236:239], v[196:199], v[78:81]
	v_mfma_f32_16x16x32_bf16 v[74:77], v[244:247], v[196:199], v[74:77]
	v_mfma_f32_16x16x32_bf16 v[70:73], v[236:239], v[222:225], v[70:73]
	v_mfma_f32_16x16x32_bf16 v[66:69], v[244:247], v[222:225], v[66:69]
	v_mfma_f32_16x16x32_bf16 v[94:97], v[240:243], v[184:187], v[94:97]
	v_mfma_f32_16x16x32_bf16 v[90:93], v[248:251], v[184:187], v[90:93]
	v_mfma_f32_16x16x32_bf16 v[86:89], v[240:243], v[192:195], v[86:89]
	v_mfma_f32_16x16x32_bf16 v[82:85], v[248:251], v[192:195], v[82:85]
	v_mfma_f32_16x16x32_bf16 v[78:81], v[240:243], v[200:203], v[78:81]
	v_mfma_f32_16x16x32_bf16 v[74:77], v[248:251], v[200:203], v[74:77]
	v_mfma_f32_16x16x32_bf16 v[70:73], v[240:243], v[232:235], v[70:73]
	v_mfma_f32_16x16x32_bf16 v[66:69], v[248:251], v[232:235], v[66:69]
	s_setprio 0
	v_readfirstlane_b32 s1, v158
	v_lshl_add_u64 v[204:205], v[204:205], 0, s[28:29]
	s_mov_b32 m0, s1
	v_readfirstlane_b32 s1, v159
	s_barrier
	ds_read_b128 v[180:183], v0 offset:49152
	ds_read_b128 v[184:187], v0 offset:50176
	ds_read_b128 v[188:191], v0 offset:51200
	ds_read_b128 v[192:195], v0 offset:52224
	ds_read_b128 v[196:199], v0 offset:53248
	ds_read_b128 v[200:203], v0 offset:54272
	ds_read_b128 v[222:225], v0 offset:55296
	ds_read_b128 v[232:235], v0 offset:56320
	global_load_lds_dwordx4 v[204:205], off
	v_lshl_add_u64 v[204:205], v[210:211], 0, s[28:29]
	s_mov_b32 m0, s1
	s_nop 0
	global_load_lds_dwordx4 v[204:205], off
	s_barrier
	s_waitcnt lgkmcnt(0)
	s_setprio 1
	s_waitcnt lgkmcnt(0)
	v_mfma_f32_16x16x32_bf16 v[62:65], v[164:167], v[180:183], v[62:65]
	v_mfma_f32_16x16x32_bf16 v[58:61], v[172:175], v[180:183], v[58:61]
	v_mfma_f32_16x16x32_bf16 v[54:57], v[164:167], v[188:191], v[54:57]
	v_mfma_f32_16x16x32_bf16 v[50:53], v[172:175], v[188:191], v[50:53]
	v_mfma_f32_16x16x32_bf16 v[46:49], v[164:167], v[196:199], v[46:49]
	v_mfma_f32_16x16x32_bf16 v[42:45], v[172:175], v[196:199], v[42:45]
	v_mfma_f32_16x16x32_bf16 v[38:41], v[164:167], v[222:225], v[38:41]
	v_mfma_f32_16x16x32_bf16 v[34:37], v[172:175], v[222:225], v[34:37]
	v_mfma_f32_16x16x32_bf16 v[62:65], v[168:171], v[184:187], v[62:65]
	v_mfma_f32_16x16x32_bf16 v[58:61], v[176:179], v[184:187], v[58:61]
	v_mfma_f32_16x16x32_bf16 v[54:57], v[168:171], v[192:195], v[54:57]
	v_mfma_f32_16x16x32_bf16 v[50:53], v[176:179], v[192:195], v[50:53]
	v_mfma_f32_16x16x32_bf16 v[46:49], v[168:171], v[200:203], v[46:49]
	v_mfma_f32_16x16x32_bf16 v[42:45], v[176:179], v[200:203], v[42:45]
	v_mfma_f32_16x16x32_bf16 v[38:41], v[168:171], v[232:235], v[38:41]
	v_mfma_f32_16x16x32_bf16 v[34:37], v[176:179], v[232:235], v[34:37]
	s_setprio 0
	s_barrier
	v_readfirstlane_b32 s1, v160
	v_lshl_add_u64 v[164:165], v[216:217], 0, s[30:31]
	s_mov_b32 m0, s1
	v_readfirstlane_b32 s1, v161
	global_load_lds_dwordx4 v[164:165], off
	v_lshl_add_u64 v[164:165], v[218:219], 0, s[30:31]
	s_mov_b32 m0, s1
	s_nop 0
	global_load_lds_dwordx4 v[164:165], off
	s_waitcnt vmcnt(6)
	s_barrier
	s_setprio 1
	v_mfma_f32_16x16x32_bf16 v[30:33], v[236:239], v[180:183], v[30:33]
	v_mfma_f32_16x16x32_bf16 v[26:29], v[244:247], v[180:183], v[26:29]
	v_mfma_f32_16x16x32_bf16 v[22:25], v[236:239], v[188:191], v[22:25]
	v_mfma_f32_16x16x32_bf16 v[18:21], v[244:247], v[188:191], v[18:21]
	v_mfma_f32_16x16x32_bf16 v[14:17], v[236:239], v[196:199], v[14:17]
	v_mfma_f32_16x16x32_bf16 v[10:13], v[244:247], v[196:199], v[10:13]
	v_mfma_f32_16x16x32_bf16 v[6:9], v[236:239], v[222:225], v[6:9]
	v_mfma_f32_16x16x32_bf16 v[2:5], v[244:247], v[222:225], v[2:5]
	v_mfma_f32_16x16x32_bf16 v[30:33], v[240:243], v[184:187], v[30:33]
	v_mfma_f32_16x16x32_bf16 v[26:29], v[248:251], v[184:187], v[26:29]
	v_mfma_f32_16x16x32_bf16 v[22:25], v[240:243], v[192:195], v[22:25]
	v_mfma_f32_16x16x32_bf16 v[18:21], v[248:251], v[192:195], v[18:21]
	v_mfma_f32_16x16x32_bf16 v[14:17], v[240:243], v[200:203], v[14:17]
	v_mfma_f32_16x16x32_bf16 v[10:13], v[248:251], v[200:203], v[10:13]
	v_mfma_f32_16x16x32_bf16 v[6:9], v[240:243], v[232:235], v[6:9]
	v_mfma_f32_16x16x32_bf16 v[2:5], v[248:251], v[232:235], v[2:5]
	s_setprio 0
	s_add_i32 s0, s0, 2
	s_add_u32 s12, s12, 0x100
	s_addc_u32 s13, s13, 0
	s_cmp_lt_u32 s0, 28
	s_barrier
	s_cbranch_scc1 .LBB0_180
	s_mov_b64 s[12:13], 0xf80
	v_readfirstlane_b32 s0, v162
	v_lshl_add_u64 v[132:133], v[132:133], 0, s[12:13]
	s_mov_b32 m0, s0
	v_readfirstlane_b32 s0, v163
	ds_read_b128 v[134:137], v151
	ds_read_b128 v[138:141], v151 offset:1024
	ds_read_b128 v[152:155], v151 offset:2048
	ds_read_b128 v[156:159], v151 offset:3072
	ds_read_b128 v[164:167], v0
	ds_read_b128 v[168:171], v0 offset:1024
	ds_read_b128 v[172:175], v0 offset:2048
	ds_read_b128 v[176:179], v0 offset:3072
	ds_read_b128 v[180:183], v0 offset:4096
	ds_read_b128 v[184:187], v0 offset:5120
	ds_read_b128 v[188:191], v0 offset:6144
	ds_read_b128 v[192:195], v0 offset:7168
	global_load_lds_dwordx4 v[132:133], off
	v_lshl_add_u64 v[130:131], v[130:131], 0, s[12:13]
	s_mov_b32 m0, s0
	s_nop 0
	global_load_lds_dwordx4 v[130:131], off
	s_barrier
	s_waitcnt lgkmcnt(0)
	s_setprio 1
	s_waitcnt lgkmcnt(0)
	v_mfma_f32_16x16x32_bf16 v[126:129], v[134:137], v[164:167], v[126:129]
	v_mfma_f32_16x16x32_bf16 v[122:125], v[152:155], v[164:167], v[122:125]
	v_mfma_f32_16x16x32_bf16 v[114:117], v[152:155], v[172:175], v[114:117]
	v_mfma_f32_16x16x32_bf16 v[106:109], v[152:155], v[180:183], v[106:109]
	v_mfma_f32_16x16x32_bf16 v[98:101], v[152:155], v[188:191], v[98:101]
	v_mfma_f32_16x16x32_bf16 v[126:129], v[138:141], v[168:171], v[126:129]
	v_mfma_f32_16x16x32_bf16 v[122:125], v[156:159], v[168:171], v[122:125]
	v_mfma_f32_16x16x32_bf16 v[118:121], v[134:137], v[172:175], v[118:121]
	v_mfma_f32_16x16x32_bf16 v[114:117], v[156:159], v[176:179], v[114:117]
	v_mfma_f32_16x16x32_bf16 v[110:113], v[134:137], v[180:183], v[110:113]
	v_mfma_f32_16x16x32_bf16 v[106:109], v[156:159], v[184:187], v[106:109]
	v_mfma_f32_16x16x32_bf16 v[102:105], v[134:137], v[188:191], v[102:105]
	v_mfma_f32_16x16x32_bf16 v[98:101], v[156:159], v[192:195], v[98:101]
	v_mfma_f32_16x16x32_bf16 v[130:133], v[138:141], v[176:179], v[118:121]
	v_mfma_f32_16x16x32_bf16 v[160:163], v[138:141], v[184:187], v[110:113]
	v_mfma_f32_16x16x32_bf16 v[196:199], v[138:141], v[192:195], v[102:105]
	s_setprio 0
	s_barrier
	s_nop 0
	ds_read_b128 v[102:105], v151 offset:16384
	ds_read_b128 v[110:113], v151 offset:17408
	ds_read_b128 v[118:121], v151 offset:18432
	ds_read_b128 v[200:203], v151 offset:19456
	s_barrier
	s_waitcnt lgkmcnt(0)
	s_setprio 1
	s_waitcnt lgkmcnt(1)
	v_mfma_f32_16x16x32_bf16 v[90:93], v[118:121], v[164:167], v[90:93]
	v_mfma_f32_16x16x32_bf16 v[82:85], v[118:121], v[172:175], v[82:85]
	v_mfma_f32_16x16x32_bf16 v[74:77], v[118:121], v[180:183], v[74:77]
	v_mfma_f32_16x16x32_bf16 v[66:69], v[118:121], v[188:191], v[66:69]
	v_mfma_f32_16x16x32_bf16 v[94:97], v[102:105], v[164:167], v[94:97]
	s_waitcnt lgkmcnt(0)
	v_mfma_f32_16x16x32_bf16 v[90:93], v[200:203], v[168:171], v[90:93]
	v_mfma_f32_16x16x32_bf16 v[86:89], v[102:105], v[172:175], v[86:89]
	v_mfma_f32_16x16x32_bf16 v[82:85], v[200:203], v[176:179], v[82:85]
	v_mfma_f32_16x16x32_bf16 v[78:81], v[102:105], v[180:183], v[78:81]
	v_mfma_f32_16x16x32_bf16 v[74:77], v[200:203], v[184:187], v[74:77]
	v_mfma_f32_16x16x32_bf16 v[70:73], v[102:105], v[188:191], v[70:73]
	v_mfma_f32_16x16x32_bf16 v[66:69], v[200:203], v[192:195], v[66:69]
	v_mfma_f32_16x16x32_bf16 v[222:225], v[110:113], v[168:171], v[94:97]
	v_mfma_f32_16x16x32_bf16 v[164:167], v[110:113], v[176:179], v[86:89]
	v_mfma_f32_16x16x32_bf16 v[168:171], v[110:113], v[184:187], v[78:81]
	v_mfma_f32_16x16x32_bf16 v[172:175], v[110:113], v[192:195], v[70:73]
	s_setprio 0
	s_barrier
	s_nop 0
	ds_read_b128 v[70:73], v0 offset:16384
	ds_read_b128 v[78:81], v0 offset:17408
	ds_read_b128 v[86:89], v0 offset:18432
	ds_read_b128 v[94:97], v0 offset:19456
	ds_read_b128 v[176:179], v0 offset:20480
	ds_read_b128 v[180:183], v0 offset:21504
	ds_read_b128 v[184:187], v0 offset:22528
	ds_read_b128 v[188:191], v0 offset:23552
	s_waitcnt vmcnt(4)
	s_barrier
	s_waitcnt lgkmcnt(0)
	s_setprio 1
	s_waitcnt lgkmcnt(7)
	v_mfma_f32_16x16x32_bf16 v[62:65], v[134:137], v[70:73], v[62:65]
	v_mfma_f32_16x16x32_bf16 v[58:61], v[152:155], v[70:73], v[58:61]
	s_waitcnt lgkmcnt(5)
	v_mfma_f32_16x16x32_bf16 v[50:53], v[152:155], v[86:89], v[50:53]
	s_waitcnt lgkmcnt(3)
	v_mfma_f32_16x16x32_bf16 v[42:45], v[152:155], v[176:179], v[42:45]
	s_waitcnt lgkmcnt(1)
	v_mfma_f32_16x16x32_bf16 v[34:37], v[152:155], v[184:187], v[34:37]
	v_mfma_f32_16x16x32_bf16 v[62:65], v[138:141], v[78:81], v[62:65]
	v_mfma_f32_16x16x32_bf16 v[58:61], v[156:159], v[78:81], v[58:61]
	v_mfma_f32_16x16x32_bf16 v[54:57], v[134:137], v[86:89], v[54:57]
	v_mfma_f32_16x16x32_bf16 v[50:53], v[156:159], v[94:97], v[50:53]
	v_mfma_f32_16x16x32_bf16 v[46:49], v[134:137], v[176:179], v[46:49]
	v_mfma_f32_16x16x32_bf16 v[42:45], v[156:159], v[180:183], v[42:45]
	v_mfma_f32_16x16x32_bf16 v[38:41], v[134:137], v[184:187], v[38:41]
	s_waitcnt lgkmcnt(0)
	v_mfma_f32_16x16x32_bf16 v[34:37], v[156:159], v[188:191], v[34:37]
	v_mfma_f32_16x16x32_bf16 v[192:195], v[138:141], v[94:97], v[54:57]
	v_mfma_f32_16x16x32_bf16 v[232:235], v[138:141], v[180:183], v[46:49]
	v_mfma_f32_16x16x32_bf16 v[134:137], v[138:141], v[188:191], v[38:41]
	s_setprio 0
	s_setprio 1
	v_mfma_f32_16x16x32_bf16 v[26:29], v[118:121], v[70:73], v[26:29]
	v_mfma_f32_16x16x32_bf16 v[18:21], v[118:121], v[86:89], v[18:21]
	v_mfma_f32_16x16x32_bf16 v[10:13], v[118:121], v[176:179], v[10:13]
	v_mfma_f32_16x16x32_bf16 v[2:5], v[118:121], v[184:187], v[2:5]
	v_mfma_f32_16x16x32_bf16 v[30:33], v[102:105], v[70:73], v[30:33]
	v_mfma_f32_16x16x32_bf16 v[26:29], v[200:203], v[78:81], v[26:29]
	v_mfma_f32_16x16x32_bf16 v[22:25], v[102:105], v[86:89], v[22:25]
	v_mfma_f32_16x16x32_bf16 v[18:21], v[200:203], v[94:97], v[18:21]
	v_mfma_f32_16x16x32_bf16 v[14:17], v[102:105], v[176:179], v[14:17]
	v_mfma_f32_16x16x32_bf16 v[10:13], v[200:203], v[180:183], v[10:13]
	v_mfma_f32_16x16x32_bf16 v[6:9], v[102:105], v[184:187], v[6:9]
	v_mfma_f32_16x16x32_bf16 v[2:5], v[200:203], v[188:191], v[2:5]
	v_mfma_f32_16x16x32_bf16 v[138:141], v[110:113], v[78:81], v[30:33]
	v_mfma_f32_16x16x32_bf16 v[152:155], v[110:113], v[94:97], v[22:25]
	v_mfma_f32_16x16x32_bf16 v[156:159], v[110:113], v[180:183], v[14:17]
	v_mfma_f32_16x16x32_bf16 v[176:179], v[110:113], v[188:191], v[6:9]
	s_setprio 0
	s_barrier
	s_nop 0
	ds_read_b128 v[6:9], v151 offset:32768
	ds_read_b128 v[14:17], v151 offset:33792
	ds_read_b128 v[180:183], v151 offset:34816
	ds_read_b128 v[184:187], v151 offset:35840
	ds_read_b128 v[22:25], v0 offset:32768
	ds_read_b128 v[30:33], v0 offset:33792
	ds_read_b128 v[38:41], v0 offset:34816
	ds_read_b128 v[46:49], v0 offset:35840
	ds_read_b128 v[54:57], v0 offset:36864
	ds_read_b128 v[188:191], v0 offset:37888
	ds_read_b128 v[200:203], v0 offset:38912
	ds_read_b128 v[236:239], v0 offset:39936
	s_waitcnt vmcnt(2)
	s_barrier
	s_waitcnt lgkmcnt(0)
	s_setprio 1
	s_waitcnt lgkmcnt(7)
	v_mfma_f32_16x16x32_bf16 v[70:73], v[6:9], v[22:25], v[126:129]
	s_waitcnt lgkmcnt(6)
	v_mfma_f32_16x16x32_bf16 v[126:129], v[14:17], v[30:33], v[70:73]
	v_mfma_f32_16x16x32_bf16 v[70:73], v[180:183], v[22:25], v[122:125]
	v_mfma_f32_16x16x32_bf16 v[118:121], v[184:187], v[30:33], v[70:73]
	s_waitcnt lgkmcnt(5)
	v_mfma_f32_16x16x32_bf16 v[70:73], v[6:9], v[38:41], v[130:133]
	s_waitcnt lgkmcnt(4)
	v_mfma_f32_16x16x32_bf16 v[110:113], v[14:17], v[46:49], v[70:73]
	v_mfma_f32_16x16x32_bf16 v[70:73], v[180:183], v[38:41], v[114:117]
	v_mfma_f32_16x16x32_bf16 v[102:105], v[184:187], v[46:49], v[70:73]
	s_waitcnt lgkmcnt(3)
	v_mfma_f32_16x16x32_bf16 v[70:73], v[6:9], v[54:57], v[160:163]
	s_waitcnt lgkmcnt(2)
	v_mfma_f32_16x16x32_bf16 v[94:97], v[14:17], v[188:191], v[70:73]
	v_mfma_f32_16x16x32_bf16 v[70:73], v[180:183], v[54:57], v[106:109]
	v_mfma_f32_16x16x32_bf16 v[86:89], v[184:187], v[188:191], v[70:73]
	s_waitcnt lgkmcnt(1)
	v_mfma_f32_16x16x32_bf16 v[70:73], v[6:9], v[200:203], v[196:199]
	s_waitcnt lgkmcnt(0)
	v_mfma_f32_16x16x32_bf16 v[78:81], v[14:17], v[236:239], v[70:73]
	v_mfma_f32_16x16x32_bf16 v[70:73], v[180:183], v[200:203], v[98:101]
	v_mfma_f32_16x16x32_bf16 v[70:73], v[184:187], v[236:239], v[70:73]
	s_setprio 0
	s_barrier
	ds_read_b128 v[130:133], v151 offset:49152
	ds_read_b128 v[160:163], v151 offset:50176
	ds_read_b128 v[196:199], v151 offset:51200
	ds_read_b128 v[148:151], v151 offset:52224
	s_waitcnt vmcnt(0)
	s_barrier
	s_waitcnt lgkmcnt(0)
	s_setprio 1
	s_waitcnt lgkmcnt(3)
	v_mfma_f32_16x16x32_bf16 v[98:101], v[130:133], v[22:25], v[222:225]
	s_waitcnt lgkmcnt(1)
	v_mfma_f32_16x16x32_bf16 v[22:25], v[196:199], v[22:25], v[90:93]
	s_waitcnt lgkmcnt(0)
	v_mfma_f32_16x16x32_bf16 v[114:117], v[148:151], v[30:33], v[22:25]
	v_mfma_f32_16x16x32_bf16 v[22:25], v[130:133], v[38:41], v[164:167]
	v_mfma_f32_16x16x32_bf16 v[106:109], v[160:163], v[46:49], v[22:25]
	v_mfma_f32_16x16x32_bf16 v[22:25], v[196:199], v[38:41], v[82:85]
	v_mfma_f32_16x16x32_bf16 v[122:125], v[160:163], v[30:33], v[98:101]
	v_mfma_f32_16x16x32_bf16 v[98:101], v[148:151], v[46:49], v[22:25]
	v_mfma_f32_16x16x32_bf16 v[22:25], v[130:133], v[54:57], v[168:171]
	v_mfma_f32_16x16x32_bf16 v[90:93], v[160:163], v[188:191], v[22:25]
	v_mfma_f32_16x16x32_bf16 v[22:25], v[196:199], v[54:57], v[74:77]
	v_mfma_f32_16x16x32_bf16 v[82:85], v[148:151], v[188:191], v[22:25]
	v_mfma_f32_16x16x32_bf16 v[22:25], v[130:133], v[200:203], v[172:175]
	v_mfma_f32_16x16x32_bf16 v[74:77], v[160:163], v[236:239], v[22:25]
	v_mfma_f32_16x16x32_bf16 v[22:25], v[196:199], v[200:203], v[66:69]
	v_mfma_f32_16x16x32_bf16 v[66:69], v[148:151], v[236:239], v[22:25]
	s_setprio 0
	s_barrier
	ds_read_b128 v[164:167], v0 offset:49152
	ds_read_b128 v[168:171], v0 offset:50176
	ds_read_b128 v[172:175], v0 offset:51200
	ds_read_b128 v[188:191], v0 offset:52224
	ds_read_b128 v[200:203], v0 offset:53248
	ds_read_b128 v[222:225], v0 offset:54272
	ds_read_b128 v[236:239], v0 offset:55296
	ds_read_b128 v[240:243], v0 offset:56320
	s_barrier
	s_waitcnt lgkmcnt(0)
	s_setprio 1
	s_waitcnt lgkmcnt(7)
	v_mfma_f32_16x16x32_bf16 v[22:25], v[6:9], v[164:167], v[62:65]
	s_waitcnt lgkmcnt(6)
	v_mfma_f32_16x16x32_bf16 v[62:65], v[14:17], v[168:171], v[22:25]
	v_mfma_f32_16x16x32_bf16 v[22:25], v[180:183], v[164:167], v[58:61]
	v_mfma_f32_16x16x32_bf16 v[54:57], v[184:187], v[168:171], v[22:25]
	s_waitcnt lgkmcnt(5)
	v_mfma_f32_16x16x32_bf16 v[22:25], v[6:9], v[172:175], v[192:195]
	s_waitcnt lgkmcnt(4)
	v_mfma_f32_16x16x32_bf16 v[46:49], v[14:17], v[188:191], v[22:25]
	v_mfma_f32_16x16x32_bf16 v[22:25], v[180:183], v[172:175], v[50:53]
	v_mfma_f32_16x16x32_bf16 v[38:41], v[184:187], v[188:191], v[22:25]
	s_waitcnt lgkmcnt(3)
	v_mfma_f32_16x16x32_bf16 v[22:25], v[6:9], v[200:203], v[232:235]
	s_waitcnt lgkmcnt(1)
	v_mfma_f32_16x16x32_bf16 v[6:9], v[6:9], v[236:239], v[134:137]
	v_mfma_f32_16x16x32_bf16 v[30:33], v[14:17], v[222:225], v[22:25]
	v_mfma_f32_16x16x32_bf16 v[22:25], v[180:183], v[200:203], v[42:45]
	s_waitcnt lgkmcnt(0)
	v_mfma_f32_16x16x32_bf16 v[14:17], v[14:17], v[240:243], v[6:9]
	v_mfma_f32_16x16x32_bf16 v[6:9], v[180:183], v[236:239], v[34:37]
	v_mfma_f32_16x16x32_bf16 v[22:25], v[184:187], v[222:225], v[22:25]
	v_mfma_f32_16x16x32_bf16 v[6:9], v[184:187], v[240:243], v[6:9]
	s_setprio 0
	s_setprio 1
	v_mfma_f32_16x16x32_bf16 v[34:37], v[130:133], v[164:167], v[138:141]
	v_mfma_f32_16x16x32_bf16 v[26:29], v[196:199], v[164:167], v[26:29]
	v_mfma_f32_16x16x32_bf16 v[18:21], v[196:199], v[172:175], v[18:21]
	v_mfma_f32_16x16x32_bf16 v[58:61], v[160:163], v[168:171], v[34:37]
	v_mfma_f32_16x16x32_bf16 v[50:53], v[148:151], v[168:171], v[26:29]
	v_mfma_f32_16x16x32_bf16 v[26:29], v[130:133], v[172:175], v[152:155]
	v_mfma_f32_16x16x32_bf16 v[34:37], v[148:151], v[188:191], v[18:21]
	v_mfma_f32_16x16x32_bf16 v[18:21], v[130:133], v[200:203], v[156:159]
	v_mfma_f32_16x16x32_bf16 v[10:13], v[196:199], v[200:203], v[10:13]
	v_mfma_f32_16x16x32_bf16 v[42:45], v[160:163], v[188:191], v[26:29]
	v_mfma_f32_16x16x32_bf16 v[26:29], v[160:163], v[222:225], v[18:21]
	v_mfma_f32_16x16x32_bf16 v[18:21], v[148:151], v[222:225], v[10:13]
	v_mfma_f32_16x16x32_bf16 v[10:13], v[130:133], v[236:239], v[176:179]
	v_mfma_f32_16x16x32_bf16 v[2:5], v[196:199], v[236:239], v[2:5]
	v_mfma_f32_16x16x32_bf16 v[10:13], v[160:163], v[240:243], v[10:13]
	v_mfma_f32_16x16x32_bf16 v[2:5], v[148:151], v[240:243], v[2:5]
	s_setprio 0
	s_movk_i32 s0, 0x100
	v_cmp_gt_u32_e32 vcc, s0, v142
	s_barrier
	s_and_saveexec_b64 s[0:1], vcc
	s_cbranch_execz .LBB0_183
	s_barrier

.LBB0_678:
	ds_read_b128 v[164:167], v151
	ds_read_b128 v[168:171], v151 offset:1024
	ds_read_b128 v[172:175], v151 offset:2048
	ds_read_b128 v[176:179], v151 offset:3072
	v_add_u32_e32 v162, 0xc000, v147
	v_lshl_add_u64 v[204:205], v[138:139], 0, s[8:9]
	v_readfirstlane_b32 s1, v162
	v_add_u32_e32 v163, 0xe000, v147
	v_lshl_add_u64 v[222:223], v[204:205], 0, s[60:61]
	s_mov_b32 m0, s1
	v_lshl_add_u64 v[216:217], v[140:141], 0, s[8:9]
	v_readfirstlane_b32 s1, v163
	ds_read_b128 v[180:183], v0
	ds_read_b128 v[184:187], v0 offset:1024
	ds_read_b128 v[188:191], v0 offset:2048
	ds_read_b128 v[192:195], v0 offset:3072
	ds_read_b128 v[196:199], v0 offset:4096
	ds_read_b128 v[200:203], v0 offset:5120
	ds_read_b128 v[232:235], v0 offset:6144
	ds_read_b128 v[236:239], v0 offset:7168
	global_load_lds_dwordx4 v[222:223], off
	v_lshl_add_u64 v[222:223], v[216:217], 0, s[60:61]
	s_mov_b32 m0, s1
	s_nop 0
	global_load_lds_dwordx4 v[222:223], off
	s_waitcnt lgkmcnt(8)
	s_barrier
	s_waitcnt lgkmcnt(0)
	s_setprio 1
	s_waitcnt lgkmcnt(0)
	v_mfma_f32_16x16x32_bf16 v[126:129], v[164:167], v[180:183], v[126:129]
	v_mfma_f32_16x16x32_bf16 v[122:125], v[172:175], v[180:183], v[122:125]
	v_mfma_f32_16x16x32_bf16 v[118:121], v[164:167], v[188:191], v[118:121]
	v_mfma_f32_16x16x32_bf16 v[114:117], v[172:175], v[188:191], v[114:117]
	v_mfma_f32_16x16x32_bf16 v[110:113], v[164:167], v[196:199], v[110:113]
	v_mfma_f32_16x16x32_bf16 v[106:109], v[172:175], v[196:199], v[106:109]
	v_mfma_f32_16x16x32_bf16 v[102:105], v[164:167], v[232:235], v[102:105]
	v_mfma_f32_16x16x32_bf16 v[98:101], v[172:175], v[232:235], v[98:101]
	v_mfma_f32_16x16x32_bf16 v[126:129], v[168:171], v[184:187], v[126:129]
	v_mfma_f32_16x16x32_bf16 v[122:125], v[176:179], v[184:187], v[122:125]
	v_mfma_f32_16x16x32_bf16 v[118:121], v[168:171], v[192:195], v[118:121]
	v_mfma_f32_16x16x32_bf16 v[114:117], v[176:179], v[192:195], v[114:117]
	v_mfma_f32_16x16x32_bf16 v[110:113], v[168:171], v[200:203], v[110:113]
	v_mfma_f32_16x16x32_bf16 v[106:109], v[176:179], v[200:203], v[106:109]
	v_mfma_f32_16x16x32_bf16 v[102:105], v[168:171], v[236:239], v[102:105]
	v_mfma_f32_16x16x32_bf16 v[98:101], v[176:179], v[236:239], v[98:101]
	s_setprio 0
	s_barrier
	v_lshl_add_u64 v[210:211], v[134:135], 0, s[8:9]
	v_readfirstlane_b32 s1, v149
	v_lshl_add_u64 v[228:229], v[210:211], 0, s[74:75]
	s_mov_b32 m0, s1
	ds_read_b128 v[240:243], v151 offset:16384
	ds_read_b128 v[244:247], v151 offset:17408
	ds_read_b128 v[248:251], v151 offset:18432
	ds_read_b128 v[222:225], v151 offset:19456
	global_load_lds_dwordx4 v[228:229], off
	v_lshl_add_u64 v[228:229], v[136:137], 0, s[8:9]
	v_readfirstlane_b32 s1, v150
	v_lshl_add_u64 v[218:219], v[228:229], 0, s[74:75]
	s_mov_b32 m0, s1
	s_nop 0
	global_load_lds_dwordx4 v[218:219], off
	s_barrier
	s_waitcnt lgkmcnt(0)
	s_setprio 1
	s_waitcnt lgkmcnt(0)
	v_mfma_f32_16x16x32_bf16 v[94:97], v[240:243], v[180:183], v[94:97]
	v_mfma_f32_16x16x32_bf16 v[90:93], v[248:251], v[180:183], v[90:93]
	v_mfma_f32_16x16x32_bf16 v[86:89], v[240:243], v[188:191], v[86:89]
	v_mfma_f32_16x16x32_bf16 v[82:85], v[248:251], v[188:191], v[82:85]
	v_mfma_f32_16x16x32_bf16 v[78:81], v[240:243], v[196:199], v[78:81]
	v_mfma_f32_16x16x32_bf16 v[74:77], v[248:251], v[196:199], v[74:77]
	v_mfma_f32_16x16x32_bf16 v[70:73], v[240:243], v[232:235], v[70:73]
	v_mfma_f32_16x16x32_bf16 v[66:69], v[248:251], v[232:235], v[66:69]
	v_mfma_f32_16x16x32_bf16 v[94:97], v[244:247], v[184:187], v[94:97]
	v_mfma_f32_16x16x32_bf16 v[90:93], v[222:225], v[184:187], v[90:93]
	v_mfma_f32_16x16x32_bf16 v[86:89], v[244:247], v[192:195], v[86:89]
	v_mfma_f32_16x16x32_bf16 v[82:85], v[222:225], v[192:195], v[82:85]
	v_mfma_f32_16x16x32_bf16 v[78:81], v[244:247], v[200:203], v[78:81]
	v_mfma_f32_16x16x32_bf16 v[74:77], v[222:225], v[200:203], v[74:77]
	v_mfma_f32_16x16x32_bf16 v[70:73], v[244:247], v[236:239], v[70:73]
	v_mfma_f32_16x16x32_bf16 v[66:69], v[222:225], v[236:239], v[66:69]
	s_setprio 0
	v_readfirstlane_b32 s1, v147
	v_lshl_add_u64 v[218:219], v[204:205], 0, s[74:75]
	s_mov_b32 m0, s1
	v_readfirstlane_b32 s1, v148
	s_barrier
	ds_read_b128 v[180:183], v0 offset:16384
	ds_read_b128 v[184:187], v0 offset:17408
	ds_read_b128 v[188:191], v0 offset:18432
	ds_read_b128 v[192:195], v0 offset:19456
	ds_read_b128 v[196:199], v0 offset:20480
	ds_read_b128 v[200:203], v0 offset:21504
	ds_read_b128 v[232:235], v0 offset:22528
	ds_read_b128 v[236:239], v0 offset:23552
	global_load_lds_dwordx4 v[218:219], off
	v_lshl_add_u64 v[218:219], v[216:217], 0, s[74:75]
	s_mov_b32 m0, s1
	s_nop 0
	global_load_lds_dwordx4 v[218:219], off
	s_barrier
	s_waitcnt lgkmcnt(0)
	s_setprio 1
	s_waitcnt lgkmcnt(0)
	v_mfma_f32_16x16x32_bf16 v[62:65], v[164:167], v[180:183], v[62:65]
	v_mfma_f32_16x16x32_bf16 v[58:61], v[172:175], v[180:183], v[58:61]
	v_mfma_f32_16x16x32_bf16 v[54:57], v[164:167], v[188:191], v[54:57]
	v_mfma_f32_16x16x32_bf16 v[50:53], v[172:175], v[188:191], v[50:53]
	v_mfma_f32_16x16x32_bf16 v[46:49], v[164:167], v[196:199], v[46:49]
	v_mfma_f32_16x16x32_bf16 v[42:45], v[172:175], v[196:199], v[42:45]
	v_mfma_f32_16x16x32_bf16 v[38:41], v[164:167], v[232:235], v[38:41]
	v_mfma_f32_16x16x32_bf16 v[34:37], v[172:175], v[232:235], v[34:37]
	v_mfma_f32_16x16x32_bf16 v[62:65], v[168:171], v[184:187], v[62:65]
	v_mfma_f32_16x16x32_bf16 v[58:61], v[176:179], v[184:187], v[58:61]
	v_mfma_f32_16x16x32_bf16 v[54:57], v[168:171], v[192:195], v[54:57]
	v_mfma_f32_16x16x32_bf16 v[50:53], v[176:179], v[192:195], v[50:53]
	v_mfma_f32_16x16x32_bf16 v[46:49], v[168:171], v[200:203], v[46:49]
	v_mfma_f32_16x16x32_bf16 v[42:45], v[176:179], v[200:203], v[42:45]
	v_mfma_f32_16x16x32_bf16 v[38:41], v[168:171], v[236:239], v[38:41]
	v_mfma_f32_16x16x32_bf16 v[34:37], v[176:179], v[236:239], v[34:37]
	s_setprio 0
	s_barrier
	v_readfirstlane_b32 s1, v152
	v_lshl_add_u64 v[164:165], v[210:211], 0, s[18:19]
	s_mov_b32 m0, s1
	v_readfirstlane_b32 s1, v153
	global_load_lds_dwordx4 v[164:165], off
	v_lshl_add_u64 v[164:165], v[228:229], 0, s[18:19]
	s_mov_b32 m0, s1
	s_nop 0
	global_load_lds_dwordx4 v[164:165], off
	s_waitcnt vmcnt(6)
	s_barrier
	s_setprio 1
	v_mfma_f32_16x16x32_bf16 v[30:33], v[240:243], v[180:183], v[30:33]
	v_mfma_f32_16x16x32_bf16 v[26:29], v[248:251], v[180:183], v[26:29]
	v_mfma_f32_16x16x32_bf16 v[22:25], v[240:243], v[188:191], v[22:25]
	v_mfma_f32_16x16x32_bf16 v[18:21], v[248:251], v[188:191], v[18:21]
	v_mfma_f32_16x16x32_bf16 v[14:17], v[240:243], v[196:199], v[14:17]
	v_mfma_f32_16x16x32_bf16 v[10:13], v[248:251], v[196:199], v[10:13]
	v_mfma_f32_16x16x32_bf16 v[6:9], v[240:243], v[232:235], v[6:9]
	v_mfma_f32_16x16x32_bf16 v[2:5], v[248:251], v[232:235], v[2:5]
	v_mfma_f32_16x16x32_bf16 v[30:33], v[244:247], v[184:187], v[30:33]
	v_mfma_f32_16x16x32_bf16 v[26:29], v[222:225], v[184:187], v[26:29]
	v_mfma_f32_16x16x32_bf16 v[22:25], v[244:247], v[192:195], v[22:25]
	v_mfma_f32_16x16x32_bf16 v[18:21], v[222:225], v[192:195], v[18:21]
	v_mfma_f32_16x16x32_bf16 v[14:17], v[244:247], v[200:203], v[14:17]
	v_mfma_f32_16x16x32_bf16 v[10:13], v[222:225], v[200:203], v[10:13]
	v_mfma_f32_16x16x32_bf16 v[6:9], v[244:247], v[236:239], v[6:9]
	v_mfma_f32_16x16x32_bf16 v[2:5], v[222:225], v[236:239], v[2:5]
	s_setprio 0
	s_barrier
	ds_read_b128 v[164:167], v151 offset:32768
	ds_read_b128 v[168:171], v151 offset:33792
	ds_read_b128 v[172:175], v151 offset:34816
	ds_read_b128 v[176:179], v151 offset:35840
	v_readfirstlane_b32 s1, v154
	v_lshl_add_u64 v[218:219], v[204:205], 0, s[18:19]
	s_mov_b32 m0, s1
	v_readfirstlane_b32 s1, v155
	ds_read_b128 v[180:183], v0 offset:32768
	ds_read_b128 v[184:187], v0 offset:33792
	ds_read_b128 v[188:191], v0 offset:34816
	ds_read_b128 v[192:195], v0 offset:35840
	ds_read_b128 v[196:199], v0 offset:36864
	ds_read_b128 v[200:203], v0 offset:37888
	ds_read_b128 v[222:225], v0 offset:38912
	ds_read_b128 v[232:235], v0 offset:39936
	global_load_lds_dwordx4 v[218:219], off
	v_lshl_add_u64 v[218:219], v[216:217], 0, s[18:19]
	s_mov_b32 m0, s1
	s_nop 0
	global_load_lds_dwordx4 v[218:219], off
	s_waitcnt lgkmcnt(8)
	s_barrier
	s_waitcnt lgkmcnt(0)
	s_setprio 1
	s_waitcnt lgkmcnt(0)
	v_mfma_f32_16x16x32_bf16 v[126:129], v[164:167], v[180:183], v[126:129]
	v_mfma_f32_16x16x32_bf16 v[122:125], v[172:175], v[180:183], v[122:125]
	v_mfma_f32_16x16x32_bf16 v[118:121], v[164:167], v[188:191], v[118:121]
	v_mfma_f32_16x16x32_bf16 v[114:117], v[172:175], v[188:191], v[114:117]
	v_mfma_f32_16x16x32_bf16 v[110:113], v[164:167], v[196:199], v[110:113]
	v_mfma_f32_16x16x32_bf16 v[106:109], v[172:175], v[196:199], v[106:109]
	v_mfma_f32_16x16x32_bf16 v[102:105], v[164:167], v[222:225], v[102:105]
	v_mfma_f32_16x16x32_bf16 v[98:101], v[172:175], v[222:225], v[98:101]
	v_mfma_f32_16x16x32_bf16 v[126:129], v[168:171], v[184:187], v[126:129]
	v_mfma_f32_16x16x32_bf16 v[122:125], v[176:179], v[184:187], v[122:125]
	v_mfma_f32_16x16x32_bf16 v[118:121], v[168:171], v[192:195], v[118:121]
	v_mfma_f32_16x16x32_bf16 v[114:117], v[176:179], v[192:195], v[114:117]
	v_mfma_f32_16x16x32_bf16 v[110:113], v[168:171], v[200:203], v[110:113]
	v_mfma_f32_16x16x32_bf16 v[106:109], v[176:179], v[200:203], v[106:109]
	v_mfma_f32_16x16x32_bf16 v[102:105], v[168:171], v[232:235], v[102:105]
	v_mfma_f32_16x16x32_bf16 v[98:101], v[176:179], v[232:235], v[98:101]
	s_setprio 0
	s_barrier
	v_readfirstlane_b32 s1, v156
	v_lshl_add_u64 v[218:219], v[210:211], 0, s[28:29]
	s_mov_b32 m0, s1
	v_readfirstlane_b32 s1, v157
	ds_read_b128 v[236:239], v151 offset:49152
	ds_read_b128 v[240:243], v151 offset:50176
	ds_read_b128 v[244:247], v151 offset:51200
	ds_read_b128 v[248:251], v151 offset:52224
	global_load_lds_dwordx4 v[218:219], off
	v_lshl_add_u64 v[218:219], v[228:229], 0, s[28:29]
	s_mov_b32 m0, s1
	s_nop 0
	global_load_lds_dwordx4 v[218:219], off
	s_barrier
	s_waitcnt lgkmcnt(0)
	s_setprio 1
	s_waitcnt lgkmcnt(0)
	v_mfma_f32_16x16x32_bf16 v[94:97], v[236:239], v[180:183], v[94:97]
	v_mfma_f32_16x16x32_bf16 v[90:93], v[244:247], v[180:183], v[90:93]
	v_mfma_f32_16x16x32_bf16 v[86:89], v[236:239], v[188:191], v[86:89]
	v_mfma_f32_16x16x32_bf16 v[82:85], v[244:247], v[188:191], v[82:85]
	v_mfma_f32_16x16x32_bf16 v[78:81], v[236:239], v[196:199], v[78:81]
	v_mfma_f32_16x16x32_bf16 v[74:77], v[244:247], v[196:199], v[74:77]
	v_mfma_f32_16x16x32_bf16 v[70:73], v[236:239], v[222:225], v[70:73]
	v_mfma_f32_16x16x32_bf16 v[66:69], v[244:247], v[222:225], v[66:69]
	v_mfma_f32_16x16x32_bf16 v[94:97], v[240:243], v[184:187], v[94:97]
	v_mfma_f32_16x16x32_bf16 v[90:93], v[248:251], v[184:187], v[90:93]
	v_mfma_f32_16x16x32_bf16 v[86:89], v[240:243], v[192:195], v[86:89]
	v_mfma_f32_16x16x32_bf16 v[82:85], v[248:251], v[192:195], v[82:85]
	v_mfma_f32_16x16x32_bf16 v[78:81], v[240:243], v[200:203], v[78:81]
	v_mfma_f32_16x16x32_bf16 v[74:77], v[248:251], v[200:203], v[74:77]
	v_mfma_f32_16x16x32_bf16 v[70:73], v[240:243], v[232:235], v[70:73]
	v_mfma_f32_16x16x32_bf16 v[66:69], v[248:251], v[232:235], v[66:69]
	s_setprio 0
	v_readfirstlane_b32 s1, v158
	v_lshl_add_u64 v[204:205], v[204:205], 0, s[28:29]
	s_mov_b32 m0, s1
	v_readfirstlane_b32 s1, v159
	s_barrier
	ds_read_b128 v[180:183], v0 offset:49152
	ds_read_b128 v[184:187], v0 offset:50176
	ds_read_b128 v[188:191], v0 offset:51200
	ds_read_b128 v[192:195], v0 offset:52224
	ds_read_b128 v[196:199], v0 offset:53248
	ds_read_b128 v[200:203], v0 offset:54272
	ds_read_b128 v[222:225], v0 offset:55296
	ds_read_b128 v[232:235], v0 offset:56320
	global_load_lds_dwordx4 v[204:205], off
	v_lshl_add_u64 v[204:205], v[216:217], 0, s[28:29]
	s_mov_b32 m0, s1
	s_nop 0
	global_load_lds_dwordx4 v[204:205], off
	s_barrier
	s_waitcnt lgkmcnt(0)
	s_setprio 1
	s_waitcnt lgkmcnt(0)
	v_mfma_f32_16x16x32_bf16 v[62:65], v[164:167], v[180:183], v[62:65]
	v_mfma_f32_16x16x32_bf16 v[58:61], v[172:175], v[180:183], v[58:61]
	v_mfma_f32_16x16x32_bf16 v[54:57], v[164:167], v[188:191], v[54:57]
	v_mfma_f32_16x16x32_bf16 v[50:53], v[172:175], v[188:191], v[50:53]
	v_mfma_f32_16x16x32_bf16 v[46:49], v[164:167], v[196:199], v[46:49]
	v_mfma_f32_16x16x32_bf16 v[42:45], v[172:175], v[196:199], v[42:45]
	v_mfma_f32_16x16x32_bf16 v[38:41], v[164:167], v[222:225], v[38:41]
	v_mfma_f32_16x16x32_bf16 v[34:37], v[172:175], v[222:225], v[34:37]
	v_mfma_f32_16x16x32_bf16 v[62:65], v[168:171], v[184:187], v[62:65]
	v_mfma_f32_16x16x32_bf16 v[58:61], v[176:179], v[184:187], v[58:61]
	v_mfma_f32_16x16x32_bf16 v[54:57], v[168:171], v[192:195], v[54:57]
	v_mfma_f32_16x16x32_bf16 v[50:53], v[176:179], v[192:195], v[50:53]
	v_mfma_f32_16x16x32_bf16 v[46:49], v[168:171], v[200:203], v[46:49]
	v_mfma_f32_16x16x32_bf16 v[42:45], v[176:179], v[200:203], v[42:45]
	v_mfma_f32_16x16x32_bf16 v[38:41], v[168:171], v[232:235], v[38:41]
	v_mfma_f32_16x16x32_bf16 v[34:37], v[176:179], v[232:235], v[34:37]
	s_setprio 0
	s_barrier
	v_readfirstlane_b32 s1, v160
	v_lshl_add_u64 v[164:165], v[210:211], 0, s[30:31]
	s_mov_b32 m0, s1
	v_readfirstlane_b32 s1, v161
	global_load_lds_dwordx4 v[164:165], off
	v_lshl_add_u64 v[164:165], v[228:229], 0, s[30:31]
	s_mov_b32 m0, s1
	s_nop 0
	global_load_lds_dwordx4 v[164:165], off
	s_waitcnt vmcnt(6)
	s_barrier
	s_setprio 1
	v_mfma_f32_16x16x32_bf16 v[30:33], v[236:239], v[180:183], v[30:33]
	v_mfma_f32_16x16x32_bf16 v[26:29], v[244:247], v[180:183], v[26:29]
	v_mfma_f32_16x16x32_bf16 v[22:25], v[236:239], v[188:191], v[22:25]
	v_mfma_f32_16x16x32_bf16 v[18:21], v[244:247], v[188:191], v[18:21]
	v_mfma_f32_16x16x32_bf16 v[14:17], v[236:239], v[196:199], v[14:17]
	v_mfma_f32_16x16x32_bf16 v[10:13], v[244:247], v[196:199], v[10:13]
	v_mfma_f32_16x16x32_bf16 v[6:9], v[236:239], v[222:225], v[6:9]
	v_mfma_f32_16x16x32_bf16 v[2:5], v[244:247], v[222:225], v[2:5]
	v_mfma_f32_16x16x32_bf16 v[30:33], v[240:243], v[184:187], v[30:33]
	v_mfma_f32_16x16x32_bf16 v[26:29], v[248:251], v[184:187], v[26:29]
	v_mfma_f32_16x16x32_bf16 v[22:25], v[240:243], v[192:195], v[22:25]
	v_mfma_f32_16x16x32_bf16 v[18:21], v[248:251], v[192:195], v[18:21]
	v_mfma_f32_16x16x32_bf16 v[14:17], v[240:243], v[200:203], v[14:17]
	v_mfma_f32_16x16x32_bf16 v[10:13], v[248:251], v[200:203], v[10:13]
	v_mfma_f32_16x16x32_bf16 v[6:9], v[240:243], v[232:235], v[6:9]
	v_mfma_f32_16x16x32_bf16 v[2:5], v[248:251], v[232:235], v[2:5]
	s_setprio 0
	s_add_i32 s0, s0, 2
	s_add_u32 s8, s8, 0x100
	s_addc_u32 s9, s9, 0
	s_cmp_lt_u32 s0, 28
	s_barrier
	s_cbranch_scc1 .LBB0_678
	s_mov_b64 s[8:9], 0xf80
	v_readfirstlane_b32 s0, v162
	v_lshl_add_u64 v[132:133], v[132:133], 0, s[8:9]
	s_mov_b32 m0, s0
	v_readfirstlane_b32 s0, v163
	ds_read_b128 v[134:137], v151
	ds_read_b128 v[138:141], v151 offset:1024
	ds_read_b128 v[152:155], v151 offset:2048
	ds_read_b128 v[156:159], v151 offset:3072
	ds_read_b128 v[164:167], v0
	ds_read_b128 v[168:171], v0 offset:1024
	ds_read_b128 v[172:175], v0 offset:2048
	ds_read_b128 v[176:179], v0 offset:3072
	ds_read_b128 v[180:183], v0 offset:4096
	ds_read_b128 v[184:187], v0 offset:5120
	ds_read_b128 v[188:191], v0 offset:6144
	ds_read_b128 v[192:195], v0 offset:7168
	global_load_lds_dwordx4 v[132:133], off
	v_lshl_add_u64 v[130:131], v[130:131], 0, s[8:9]
	s_mov_b32 m0, s0
	s_nop 0
	global_load_lds_dwordx4 v[130:131], off
	s_barrier
	s_waitcnt lgkmcnt(0)
	s_setprio 1
	s_waitcnt lgkmcnt(0)
	v_mfma_f32_16x16x32_bf16 v[126:129], v[134:137], v[164:167], v[126:129]
	v_mfma_f32_16x16x32_bf16 v[122:125], v[152:155], v[164:167], v[122:125]
	v_mfma_f32_16x16x32_bf16 v[114:117], v[152:155], v[172:175], v[114:117]
	v_mfma_f32_16x16x32_bf16 v[106:109], v[152:155], v[180:183], v[106:109]
	v_mfma_f32_16x16x32_bf16 v[98:101], v[152:155], v[188:191], v[98:101]
	v_mfma_f32_16x16x32_bf16 v[126:129], v[138:141], v[168:171], v[126:129]
	v_mfma_f32_16x16x32_bf16 v[122:125], v[156:159], v[168:171], v[122:125]
	v_mfma_f32_16x16x32_bf16 v[118:121], v[134:137], v[172:175], v[118:121]
	v_mfma_f32_16x16x32_bf16 v[114:117], v[156:159], v[176:179], v[114:117]
	v_mfma_f32_16x16x32_bf16 v[110:113], v[134:137], v[180:183], v[110:113]
	v_mfma_f32_16x16x32_bf16 v[106:109], v[156:159], v[184:187], v[106:109]
	v_mfma_f32_16x16x32_bf16 v[102:105], v[134:137], v[188:191], v[102:105]
	v_mfma_f32_16x16x32_bf16 v[98:101], v[156:159], v[192:195], v[98:101]
	v_mfma_f32_16x16x32_bf16 v[130:133], v[138:141], v[176:179], v[118:121]
	v_mfma_f32_16x16x32_bf16 v[160:163], v[138:141], v[184:187], v[110:113]
	v_mfma_f32_16x16x32_bf16 v[196:199], v[138:141], v[192:195], v[102:105]
	s_setprio 0
	s_barrier
	s_nop 0
	ds_read_b128 v[102:105], v151 offset:16384
	ds_read_b128 v[110:113], v151 offset:17408
	ds_read_b128 v[118:121], v151 offset:18432
	ds_read_b128 v[200:203], v151 offset:19456
	s_barrier
	s_waitcnt lgkmcnt(0)
	s_setprio 1
	s_waitcnt lgkmcnt(1)
	v_mfma_f32_16x16x32_bf16 v[90:93], v[118:121], v[164:167], v[90:93]
	v_mfma_f32_16x16x32_bf16 v[86:89], v[102:105], v[172:175], v[86:89]
	v_mfma_f32_16x16x32_bf16 v[82:85], v[118:121], v[172:175], v[82:85]
	v_mfma_f32_16x16x32_bf16 v[78:81], v[102:105], v[180:183], v[78:81]
	v_mfma_f32_16x16x32_bf16 v[70:73], v[102:105], v[188:191], v[70:73]
	v_mfma_f32_16x16x32_bf16 v[94:97], v[102:105], v[164:167], v[94:97]
	s_waitcnt lgkmcnt(0)
	v_mfma_f32_16x16x32_bf16 v[90:93], v[200:203], v[168:171], v[90:93]
	v_mfma_f32_16x16x32_bf16 v[86:89], v[110:113], v[176:179], v[86:89]
	v_mfma_f32_16x16x32_bf16 v[82:85], v[200:203], v[176:179], v[82:85]
	v_mfma_f32_16x16x32_bf16 v[78:81], v[110:113], v[184:187], v[78:81]
	v_mfma_f32_16x16x32_bf16 v[74:77], v[118:121], v[180:183], v[74:77]
	v_mfma_f32_16x16x32_bf16 v[70:73], v[110:113], v[192:195], v[70:73]
	v_mfma_f32_16x16x32_bf16 v[66:69], v[118:121], v[188:191], v[66:69]
	v_mfma_f32_16x16x32_bf16 v[222:225], v[110:113], v[168:171], v[94:97]
	v_mfma_f32_16x16x32_bf16 v[164:167], v[200:203], v[184:187], v[74:77]
	v_mfma_f32_16x16x32_bf16 v[168:171], v[200:203], v[192:195], v[66:69]
	s_setprio 0
	s_barrier
	s_nop 2
	ds_read_b128 v[66:69], v0 offset:16384
	ds_read_b128 v[74:77], v0 offset:17408
	ds_read_b128 v[94:97], v0 offset:18432
	ds_read_b128 v[172:175], v0 offset:19456
	ds_read_b128 v[176:179], v0 offset:20480
	ds_read_b128 v[180:183], v0 offset:21504
	ds_read_b128 v[184:187], v0 offset:22528
	ds_read_b128 v[188:191], v0 offset:23552
	s_waitcnt vmcnt(4)
	s_barrier
	s_waitcnt lgkmcnt(0)
	s_setprio 1
	s_waitcnt lgkmcnt(5)
	v_mfma_f32_16x16x32_bf16 v[54:57], v[134:137], v[94:97], v[54:57]
	v_mfma_f32_16x16x32_bf16 v[50:53], v[152:155], v[94:97], v[50:53]
	v_mfma_f32_16x16x32_bf16 v[62:65], v[134:137], v[66:69], v[62:65]
	v_mfma_f32_16x16x32_bf16 v[58:61], v[152:155], v[66:69], v[58:61]
	s_waitcnt lgkmcnt(4)
	v_mfma_f32_16x16x32_bf16 v[54:57], v[138:141], v[172:175], v[54:57]
	v_mfma_f32_16x16x32_bf16 v[50:53], v[156:159], v[172:175], v[50:53]
	s_waitcnt lgkmcnt(3)
	v_mfma_f32_16x16x32_bf16 v[46:49], v[134:137], v[176:179], v[46:49]
	v_mfma_f32_16x16x32_bf16 v[42:45], v[152:155], v[176:179], v[42:45]
	s_waitcnt lgkmcnt(1)
	v_mfma_f32_16x16x32_bf16 v[38:41], v[134:137], v[184:187], v[38:41]
	v_mfma_f32_16x16x32_bf16 v[34:37], v[152:155], v[184:187], v[34:37]
	v_mfma_f32_16x16x32_bf16 v[192:195], v[138:141], v[74:77], v[62:65]
	v_mfma_f32_16x16x32_bf16 v[232:235], v[156:159], v[74:77], v[58:61]
	v_mfma_f32_16x16x32_bf16 v[236:239], v[138:141], v[180:183], v[46:49]
	v_mfma_f32_16x16x32_bf16 v[240:243], v[156:159], v[180:183], v[42:45]
	s_waitcnt lgkmcnt(0)
	v_mfma_f32_16x16x32_bf16 v[134:137], v[138:141], v[188:191], v[38:41]
	v_mfma_f32_16x16x32_bf16 v[138:141], v[156:159], v[188:191], v[34:37]
	s_setprio 0
	s_setprio 1
	v_mfma_f32_16x16x32_bf16 v[30:33], v[102:105], v[66:69], v[30:33]
	v_mfma_f32_16x16x32_bf16 v[26:29], v[118:121], v[66:69], v[26:29]
	v_mfma_f32_16x16x32_bf16 v[14:17], v[102:105], v[176:179], v[14:17]
	v_mfma_f32_16x16x32_bf16 v[10:13], v[118:121], v[176:179], v[10:13]
	v_mfma_f32_16x16x32_bf16 v[30:33], v[110:113], v[74:77], v[30:33]
	v_mfma_f32_16x16x32_bf16 v[26:29], v[200:203], v[74:77], v[26:29]
	v_mfma_f32_16x16x32_bf16 v[22:25], v[102:105], v[94:97], v[22:25]
	v_mfma_f32_16x16x32_bf16 v[18:21], v[118:121], v[94:97], v[18:21]
	v_mfma_f32_16x16x32_bf16 v[14:17], v[110:113], v[180:183], v[14:17]
	v_mfma_f32_16x16x32_bf16 v[10:13], v[200:203], v[180:183], v[10:13]
	v_mfma_f32_16x16x32_bf16 v[6:9], v[102:105], v[184:187], v[6:9]
	v_mfma_f32_16x16x32_bf16 v[2:5], v[118:121], v[184:187], v[2:5]
	v_mfma_f32_16x16x32_bf16 v[152:155], v[110:113], v[172:175], v[22:25]
	v_mfma_f32_16x16x32_bf16 v[156:159], v[200:203], v[172:175], v[18:21]
	v_mfma_f32_16x16x32_bf16 v[172:175], v[110:113], v[188:191], v[6:9]
	v_mfma_f32_16x16x32_bf16 v[176:179], v[200:203], v[188:191], v[2:5]
	s_setprio 0
	s_barrier
	s_nop 1
	ds_read_b128 v[2:5], v151 offset:32768
	ds_read_b128 v[6:9], v151 offset:33792
	ds_read_b128 v[180:183], v151 offset:34816
	ds_read_b128 v[184:187], v151 offset:35840
	ds_read_b128 v[18:21], v0 offset:32768
	ds_read_b128 v[22:25], v0 offset:33792
	ds_read_b128 v[38:41], v0 offset:34816
	ds_read_b128 v[46:49], v0 offset:35840
	ds_read_b128 v[58:61], v0 offset:36864
	ds_read_b128 v[66:69], v0 offset:37888
	ds_read_b128 v[188:191], v0 offset:38912
	ds_read_b128 v[200:203], v0 offset:39936
	s_waitcnt vmcnt(2)
	s_barrier
	s_waitcnt lgkmcnt(0)
	s_setprio 1
	s_waitcnt lgkmcnt(7)
	v_mfma_f32_16x16x32_bf16 v[34:37], v[2:5], v[18:21], v[126:129]
	s_waitcnt lgkmcnt(6)
	v_mfma_f32_16x16x32_bf16 v[118:121], v[6:9], v[22:25], v[34:37]
	v_mfma_f32_16x16x32_bf16 v[34:37], v[180:183], v[18:21], v[122:125]
	v_mfma_f32_16x16x32_bf16 v[110:113], v[184:187], v[22:25], v[34:37]
	s_waitcnt lgkmcnt(5)
	v_mfma_f32_16x16x32_bf16 v[34:37], v[2:5], v[38:41], v[130:133]
	s_waitcnt lgkmcnt(4)
	v_mfma_f32_16x16x32_bf16 v[102:105], v[6:9], v[46:49], v[34:37]
	v_mfma_f32_16x16x32_bf16 v[34:37], v[180:183], v[38:41], v[114:117]
	v_mfma_f32_16x16x32_bf16 v[94:97], v[184:187], v[46:49], v[34:37]
	s_waitcnt lgkmcnt(3)
	v_mfma_f32_16x16x32_bf16 v[34:37], v[2:5], v[58:61], v[160:163]
	s_waitcnt lgkmcnt(2)
	v_mfma_f32_16x16x32_bf16 v[74:77], v[6:9], v[66:69], v[34:37]
	v_mfma_f32_16x16x32_bf16 v[34:37], v[180:183], v[58:61], v[106:109]
	v_mfma_f32_16x16x32_bf16 v[62:65], v[184:187], v[66:69], v[34:37]
	s_waitcnt lgkmcnt(1)
	v_mfma_f32_16x16x32_bf16 v[34:37], v[2:5], v[188:191], v[196:199]
	s_waitcnt lgkmcnt(0)
	v_mfma_f32_16x16x32_bf16 v[42:45], v[6:9], v[200:203], v[34:37]
	v_mfma_f32_16x16x32_bf16 v[34:37], v[180:183], v[188:191], v[98:101]
	v_mfma_f32_16x16x32_bf16 v[34:37], v[184:187], v[200:203], v[34:37]
	s_setprio 0
	s_barrier
	ds_read_b128 v[130:133], v151 offset:49152
	ds_read_b128 v[160:163], v151 offset:50176
	ds_read_b128 v[196:199], v151 offset:51200
	ds_read_b128 v[148:151], v151 offset:52224
	s_waitcnt vmcnt(0)
	s_barrier
	s_waitcnt lgkmcnt(0)
	s_setprio 1
	s_waitcnt lgkmcnt(3)
	v_mfma_f32_16x16x32_bf16 v[98:101], v[130:133], v[18:21], v[222:225]
	s_waitcnt lgkmcnt(1)
	v_mfma_f32_16x16x32_bf16 v[18:21], v[196:199], v[18:21], v[90:93]
	s_waitcnt lgkmcnt(0)
	v_mfma_f32_16x16x32_bf16 v[122:125], v[148:151], v[22:25], v[18:21]
	v_mfma_f32_16x16x32_bf16 v[18:21], v[130:133], v[38:41], v[86:89]
	v_mfma_f32_16x16x32_bf16 v[114:117], v[160:163], v[46:49], v[18:21]
	v_mfma_f32_16x16x32_bf16 v[18:21], v[196:199], v[38:41], v[82:85]
	v_mfma_f32_16x16x32_bf16 v[106:109], v[148:151], v[46:49], v[18:21]
	v_mfma_f32_16x16x32_bf16 v[18:21], v[130:133], v[58:61], v[78:81]
	v_mfma_f32_16x16x32_bf16 v[126:129], v[160:163], v[22:25], v[98:101]
	v_mfma_f32_16x16x32_bf16 v[98:101], v[160:163], v[66:69], v[18:21]
	v_mfma_f32_16x16x32_bf16 v[18:21], v[196:199], v[58:61], v[164:167]
	v_mfma_f32_16x16x32_bf16 v[90:93], v[148:151], v[66:69], v[18:21]
	v_mfma_f32_16x16x32_bf16 v[18:21], v[130:133], v[188:191], v[70:73]
	v_mfma_f32_16x16x32_bf16 v[66:69], v[160:163], v[200:203], v[18:21]
	v_mfma_f32_16x16x32_bf16 v[18:21], v[196:199], v[188:191], v[168:171]
	v_mfma_f32_16x16x32_bf16 v[58:61], v[148:151], v[200:203], v[18:21]
	s_setprio 0
	s_barrier
	ds_read_b128 v[82:85], v0 offset:49152
	ds_read_b128 v[164:167], v0 offset:50176
	ds_read_b128 v[168:171], v0 offset:51200
	ds_read_b128 v[188:191], v0 offset:52224
	ds_read_b128 v[200:203], v0 offset:53248
	ds_read_b128 v[222:225], v0 offset:54272
	ds_read_b128 v[244:247], v0 offset:55296
	ds_read_b128 v[248:251], v0 offset:56320
	s_barrier
	s_waitcnt lgkmcnt(0)
	s_setprio 1
	s_waitcnt lgkmcnt(7)
	v_mfma_f32_16x16x32_bf16 v[18:21], v[2:5], v[82:85], v[192:195]
	s_waitcnt lgkmcnt(6)
	v_mfma_f32_16x16x32_bf16 v[78:81], v[6:9], v[164:167], v[18:21]
	v_mfma_f32_16x16x32_bf16 v[18:21], v[180:183], v[82:85], v[232:235]
	v_mfma_f32_16x16x32_bf16 v[70:73], v[184:187], v[164:167], v[18:21]
	s_waitcnt lgkmcnt(5)
	v_mfma_f32_16x16x32_bf16 v[18:21], v[2:5], v[168:171], v[54:57]
	s_waitcnt lgkmcnt(4)
	v_mfma_f32_16x16x32_bf16 v[46:49], v[6:9], v[188:191], v[18:21]
	v_mfma_f32_16x16x32_bf16 v[18:21], v[180:183], v[168:171], v[50:53]
	v_mfma_f32_16x16x32_bf16 v[38:41], v[184:187], v[188:191], v[18:21]
	s_waitcnt lgkmcnt(3)
	v_mfma_f32_16x16x32_bf16 v[18:21], v[2:5], v[200:203], v[236:239]
	s_waitcnt lgkmcnt(1)
	v_mfma_f32_16x16x32_bf16 v[2:5], v[2:5], v[244:247], v[134:137]
	v_mfma_f32_16x16x32_bf16 v[22:25], v[6:9], v[222:225], v[18:21]
	v_mfma_f32_16x16x32_bf16 v[18:21], v[180:183], v[200:203], v[240:243]
	s_waitcnt lgkmcnt(0)
	v_mfma_f32_16x16x32_bf16 v[6:9], v[6:9], v[248:251], v[2:5]
	v_mfma_f32_16x16x32_bf16 v[2:5], v[180:183], v[244:247], v[138:141]
	v_mfma_f32_16x16x32_bf16 v[18:21], v[184:187], v[222:225], v[18:21]
	v_mfma_f32_16x16x32_bf16 v[2:5], v[184:187], v[248:251], v[2:5]
	s_setprio 0
	s_setprio 1
	v_mfma_f32_16x16x32_bf16 v[26:29], v[196:199], v[82:85], v[26:29]
	v_mfma_f32_16x16x32_bf16 v[30:33], v[130:133], v[82:85], v[30:33]
	v_mfma_f32_16x16x32_bf16 v[82:85], v[148:151], v[164:167], v[26:29]
	v_mfma_f32_16x16x32_bf16 v[26:29], v[130:133], v[168:171], v[152:155]
	v_mfma_f32_16x16x32_bf16 v[54:57], v[160:163], v[188:191], v[26:29]
	v_mfma_f32_16x16x32_bf16 v[26:29], v[196:199], v[168:171], v[156:159]
	v_mfma_f32_16x16x32_bf16 v[10:13], v[196:199], v[200:203], v[10:13]
	v_mfma_f32_16x16x32_bf16 v[50:53], v[148:151], v[188:191], v[26:29]
	v_mfma_f32_16x16x32_bf16 v[14:17], v[130:133], v[200:203], v[14:17]
	v_mfma_f32_16x16x32_bf16 v[26:29], v[148:151], v[222:225], v[10:13]
	v_mfma_f32_16x16x32_bf16 v[10:13], v[130:133], v[244:247], v[172:175]
	v_mfma_f32_16x16x32_bf16 v[86:89], v[160:163], v[164:167], v[30:33]
	v_mfma_f32_16x16x32_bf16 v[30:33], v[160:163], v[222:225], v[14:17]
	v_mfma_f32_16x16x32_bf16 v[14:17], v[160:163], v[248:251], v[10:13]
	v_mfma_f32_16x16x32_bf16 v[10:13], v[196:199], v[244:247], v[176:179]
	v_mfma_f32_16x16x32_bf16 v[10:13], v[148:151], v[248:251], v[10:13]
	s_setprio 0
	s_movk_i32 s0, 0x100
	v_cmp_gt_u32_e32 vcc, s0, v142
	s_barrier
	s_and_saveexec_b64 s[0:1], vcc
	s_cbranch_execz .LBB0_674
	s_barrier
	s_branch .LBB0_674

.LBB0_689:
	ds_read_b128 v[104:107], v95
	ds_read_b128 v[108:111], v95 offset:1024
	ds_read_b128 v[112:115], v95 offset:2048
	ds_read_b128 v[116:119], v95 offset:3072
	v_add_u32_e32 v101, 0xc000, v85
	v_lshl_add_u64 v[152:153], v[72:73], 0, s[10:11]
	v_readfirstlane_b32 s1, v101
	v_lshl_add_u64 v[102:103], v[152:153], 0, s[34:35]
	s_mov_b32 m0, s1
	ds_read_b128 v[120:123], v93
	ds_read_b128 v[124:127], v93 offset:1024
	ds_read_b128 v[128:131], v93 offset:2048
	ds_read_b128 v[132:135], v93 offset:3072
	ds_read_b128 v[136:139], v93 offset:4096
	ds_read_b128 v[140:143], v93 offset:5120
	ds_read_b128 v[144:147], v93 offset:6144
	ds_read_b128 v[148:151], v93 offset:7168
	global_load_lds_dwordx4 v[102:103], off
	v_add_u32_e32 v102, 0xe000, v85
	v_lshl_add_u64 v[154:155], v[74:75], 0, s[10:11]
	v_readfirstlane_b32 s1, v102
	v_lshl_add_u64 v[156:157], v[154:155], 0, s[34:35]
	s_mov_b32 m0, s1
	s_nop 0
	global_load_lds_dwordx4 v[156:157], off
	s_waitcnt lgkmcnt(8)
	s_barrier
	s_waitcnt lgkmcnt(0)
	s_setprio 1
	s_waitcnt lgkmcnt(0)
	v_mfma_f32_16x16x32_bf16 v[62:65], v[104:107], v[120:123], v[62:65]
	v_mfma_f32_16x16x32_bf16 v[58:61], v[112:115], v[120:123], v[58:61]
	v_mfma_f32_16x16x32_bf16 v[54:57], v[104:107], v[128:131], v[54:57]
	v_mfma_f32_16x16x32_bf16 v[50:53], v[112:115], v[128:131], v[50:53]
	v_mfma_f32_16x16x32_bf16 v[46:49], v[104:107], v[136:139], v[46:49]
	v_mfma_f32_16x16x32_bf16 v[42:45], v[112:115], v[136:139], v[42:45]
	v_mfma_f32_16x16x32_bf16 v[38:41], v[104:107], v[144:147], v[38:41]
	v_mfma_f32_16x16x32_bf16 v[34:37], v[112:115], v[144:147], v[34:37]
	v_mfma_f32_16x16x32_bf16 v[62:65], v[108:111], v[124:127], v[62:65]
	v_mfma_f32_16x16x32_bf16 v[58:61], v[116:119], v[124:127], v[58:61]
	v_mfma_f32_16x16x32_bf16 v[54:57], v[108:111], v[132:135], v[54:57]
	v_mfma_f32_16x16x32_bf16 v[50:53], v[116:119], v[132:135], v[50:53]
	v_mfma_f32_16x16x32_bf16 v[46:49], v[108:111], v[140:143], v[46:49]
	v_mfma_f32_16x16x32_bf16 v[42:45], v[116:119], v[140:143], v[42:45]
	v_mfma_f32_16x16x32_bf16 v[38:41], v[108:111], v[148:151], v[38:41]
	v_mfma_f32_16x16x32_bf16 v[34:37], v[116:119], v[148:151], v[34:37]
	s_setprio 0
	s_barrier
	v_lshl_add_u64 v[156:157], v[68:69], 0, s[10:11]
	v_readfirstlane_b32 s1, v87
	v_lshl_add_u64 v[120:121], v[156:157], 0, s[74:75]
	s_mov_b32 m0, s1
	v_lshl_add_u64 v[158:159], v[70:71], 0, s[10:11]
	v_readfirstlane_b32 s1, v88
	global_load_lds_dwordx4 v[120:121], off
	v_lshl_add_u64 v[120:121], v[158:159], 0, s[74:75]
	s_mov_b32 m0, s1
	v_readfirstlane_b32 s1, v85
	global_load_lds_dwordx4 v[120:121], off
	v_lshl_add_u64 v[160:161], v[152:153], 0, s[74:75]
	s_mov_b32 m0, s1
	v_readfirstlane_b32 s1, v86
	s_barrier
	s_waitcnt lgkmcnt(0)
	s_barrier
	ds_read_b128 v[120:123], v93 offset:16384
	ds_read_b128 v[124:127], v93 offset:17408
	ds_read_b128 v[128:131], v93 offset:18432
	ds_read_b128 v[132:135], v93 offset:19456
	ds_read_b128 v[136:139], v93 offset:20480
	ds_read_b128 v[140:143], v93 offset:21504
	ds_read_b128 v[144:147], v93 offset:22528
	ds_read_b128 v[148:151], v93 offset:23552
	global_load_lds_dwordx4 v[160:161], off
	v_lshl_add_u64 v[160:161], v[154:155], 0, s[74:75]
	s_mov_b32 m0, s1
	s_nop 0
	global_load_lds_dwordx4 v[160:161], off
	s_barrier
	s_waitcnt lgkmcnt(0)
	s_setprio 1
	s_waitcnt lgkmcnt(0)
	v_mfma_f32_16x16x32_bf16 v[2:5], v[104:107], v[120:123], v[2:5]
	v_mfma_f32_16x16x32_bf16 v[6:9], v[112:115], v[120:123], v[6:9]
	v_mfma_f32_16x16x32_bf16 v[10:13], v[104:107], v[128:131], v[10:13]
	v_mfma_f32_16x16x32_bf16 v[14:17], v[112:115], v[128:131], v[14:17]
	v_mfma_f32_16x16x32_bf16 v[18:21], v[104:107], v[136:139], v[18:21]
	v_mfma_f32_16x16x32_bf16 v[22:25], v[112:115], v[136:139], v[22:25]
	v_mfma_f32_16x16x32_bf16 v[26:29], v[104:107], v[144:147], v[26:29]
	v_mfma_f32_16x16x32_bf16 v[30:33], v[112:115], v[144:147], v[30:33]
	v_mfma_f32_16x16x32_bf16 v[2:5], v[108:111], v[124:127], v[2:5]
	v_mfma_f32_16x16x32_bf16 v[6:9], v[116:119], v[124:127], v[6:9]
	v_mfma_f32_16x16x32_bf16 v[10:13], v[108:111], v[132:135], v[10:13]
	v_mfma_f32_16x16x32_bf16 v[14:17], v[116:119], v[132:135], v[14:17]
	v_mfma_f32_16x16x32_bf16 v[18:21], v[108:111], v[140:143], v[18:21]
	v_mfma_f32_16x16x32_bf16 v[22:25], v[116:119], v[140:143], v[22:25]
	v_mfma_f32_16x16x32_bf16 v[26:29], v[108:111], v[148:151], v[26:29]
	v_mfma_f32_16x16x32_bf16 v[30:33], v[116:119], v[148:151], v[30:33]
	s_setprio 0
	s_barrier
	v_lshl_add_u64 v[160:161], v[76:77], 0, s[10:11]
	v_readfirstlane_b32 s1, v89
	v_lshl_add_u64 v[104:105], v[160:161], 0, s[74:75]
	s_mov_b32 m0, s1
	v_lshl_add_u64 v[162:163], v[78:79], 0, s[10:11]
	v_readfirstlane_b32 s1, v90
	global_load_lds_dwordx4 v[104:105], off
	v_lshl_add_u64 v[104:105], v[162:163], 0, s[74:75]
	s_mov_b32 m0, s1
	s_nop 0
	global_load_lds_dwordx4 v[104:105], off
	s_waitcnt vmcnt(6)
	s_barrier
	s_barrier
	ds_read_b128 v[104:107], v95 offset:32768
	ds_read_b128 v[108:111], v95 offset:33792
	ds_read_b128 v[112:115], v95 offset:34816
	ds_read_b128 v[116:119], v95 offset:35840
	v_readfirstlane_b32 s1, v91
	v_lshl_add_u64 v[164:165], v[152:153], 0, s[78:79]
	s_mov_b32 m0, s1
	v_readfirstlane_b32 s1, v92
	ds_read_b128 v[120:123], v93 offset:32768
	ds_read_b128 v[124:127], v93 offset:33792
	ds_read_b128 v[128:131], v93 offset:34816
	ds_read_b128 v[132:135], v93 offset:35840
	ds_read_b128 v[136:139], v93 offset:36864
	ds_read_b128 v[140:143], v93 offset:37888
	ds_read_b128 v[144:147], v93 offset:38912
	ds_read_b128 v[148:151], v93 offset:39936
	global_load_lds_dwordx4 v[164:165], off
	v_lshl_add_u64 v[164:165], v[154:155], 0, s[78:79]
	s_mov_b32 m0, s1
	s_nop 0
	global_load_lds_dwordx4 v[164:165], off
	s_waitcnt lgkmcnt(8)
	s_barrier
	s_waitcnt lgkmcnt(0)
	s_setprio 1
	s_waitcnt lgkmcnt(0)
	v_mfma_f32_16x16x32_bf16 v[62:65], v[104:107], v[120:123], v[62:65]
	v_mfma_f32_16x16x32_bf16 v[58:61], v[112:115], v[120:123], v[58:61]
	v_mfma_f32_16x16x32_bf16 v[54:57], v[104:107], v[128:131], v[54:57]
	v_mfma_f32_16x16x32_bf16 v[50:53], v[112:115], v[128:131], v[50:53]
	v_mfma_f32_16x16x32_bf16 v[46:49], v[104:107], v[136:139], v[46:49]
	v_mfma_f32_16x16x32_bf16 v[42:45], v[112:115], v[136:139], v[42:45]
	v_mfma_f32_16x16x32_bf16 v[38:41], v[104:107], v[144:147], v[38:41]
	v_mfma_f32_16x16x32_bf16 v[34:37], v[112:115], v[144:147], v[34:37]
	v_mfma_f32_16x16x32_bf16 v[62:65], v[108:111], v[124:127], v[62:65]
	v_mfma_f32_16x16x32_bf16 v[58:61], v[116:119], v[124:127], v[58:61]
	v_mfma_f32_16x16x32_bf16 v[54:57], v[108:111], v[132:135], v[54:57]
	v_mfma_f32_16x16x32_bf16 v[50:53], v[116:119], v[132:135], v[50:53]
	v_mfma_f32_16x16x32_bf16 v[46:49], v[108:111], v[140:143], v[46:49]
	v_mfma_f32_16x16x32_bf16 v[42:45], v[116:119], v[140:143], v[42:45]
	v_mfma_f32_16x16x32_bf16 v[38:41], v[108:111], v[148:151], v[38:41]
	v_mfma_f32_16x16x32_bf16 v[34:37], v[116:119], v[148:151], v[34:37]
	s_setprio 0
	s_barrier
	v_readfirstlane_b32 s1, v94
	v_lshl_add_u64 v[120:121], v[156:157], 0, s[28:29]
	s_mov_b32 m0, s1
	v_readfirstlane_b32 s1, v96
	global_load_lds_dwordx4 v[120:121], off
	v_lshl_add_u64 v[120:121], v[158:159], 0, s[28:29]
	s_mov_b32 m0, s1
	v_readfirstlane_b32 s1, v97
	global_load_lds_dwordx4 v[120:121], off
	v_lshl_add_u64 v[152:153], v[152:153], 0, s[28:29]
	s_mov_b32 m0, s1
	v_readfirstlane_b32 s1, v98
	s_barrier
	s_waitcnt lgkmcnt(0)
	s_barrier
	ds_read_b128 v[120:123], v93 offset:49152
	ds_read_b128 v[124:127], v93 offset:50176
	ds_read_b128 v[128:131], v93 offset:51200
	ds_read_b128 v[132:135], v93 offset:52224
	ds_read_b128 v[136:139], v93 offset:53248
	ds_read_b128 v[140:143], v93 offset:54272
	ds_read_b128 v[144:147], v93 offset:55296
	ds_read_b128 v[148:151], v93 offset:56320
	global_load_lds_dwordx4 v[152:153], off
	v_lshl_add_u64 v[152:153], v[154:155], 0, s[28:29]
	s_mov_b32 m0, s1
	s_nop 0
	global_load_lds_dwordx4 v[152:153], off
	s_barrier
	s_waitcnt lgkmcnt(0)
	s_setprio 1
	s_waitcnt lgkmcnt(0)
	v_mfma_f32_16x16x32_bf16 v[2:5], v[104:107], v[120:123], v[2:5]
	v_mfma_f32_16x16x32_bf16 v[6:9], v[112:115], v[120:123], v[6:9]
	v_mfma_f32_16x16x32_bf16 v[10:13], v[104:107], v[128:131], v[10:13]
	v_mfma_f32_16x16x32_bf16 v[14:17], v[112:115], v[128:131], v[14:17]
	v_mfma_f32_16x16x32_bf16 v[18:21], v[104:107], v[136:139], v[18:21]
	v_mfma_f32_16x16x32_bf16 v[22:25], v[112:115], v[136:139], v[22:25]
	v_mfma_f32_16x16x32_bf16 v[26:29], v[104:107], v[144:147], v[26:29]
	v_mfma_f32_16x16x32_bf16 v[30:33], v[112:115], v[144:147], v[30:33]
	v_mfma_f32_16x16x32_bf16 v[2:5], v[108:111], v[124:127], v[2:5]
	v_mfma_f32_16x16x32_bf16 v[6:9], v[116:119], v[124:127], v[6:9]
	v_mfma_f32_16x16x32_bf16 v[10:13], v[108:111], v[132:135], v[10:13]
	v_mfma_f32_16x16x32_bf16 v[14:17], v[116:119], v[132:135], v[14:17]
	v_mfma_f32_16x16x32_bf16 v[18:21], v[108:111], v[140:143], v[18:21]
	v_mfma_f32_16x16x32_bf16 v[22:25], v[116:119], v[140:143], v[22:25]
	v_mfma_f32_16x16x32_bf16 v[26:29], v[108:111], v[148:151], v[26:29]
	v_mfma_f32_16x16x32_bf16 v[30:33], v[116:119], v[148:151], v[30:33]
	s_setprio 0
	s_barrier
	v_readfirstlane_b32 s1, v99
	v_lshl_add_u64 v[104:105], v[160:161], 0, s[28:29]
	s_mov_b32 m0, s1
	v_readfirstlane_b32 s1, v100
	global_load_lds_dwordx4 v[104:105], off
	v_lshl_add_u64 v[104:105], v[162:163], 0, s[28:29]
	s_mov_b32 m0, s1
	s_add_i32 s0, s0, 2
	global_load_lds_dwordx4 v[104:105], off
	s_waitcnt vmcnt(6)
	s_add_u32 s10, s10, 0x100
	s_addc_u32 s11, s11, 0
	s_cmpk_lt_u32 s0, 0x54
	s_barrier
	s_barrier
	s_cbranch_scc1 .LBB0_689
	s_add_u32 s0, s8, 0x2b80
	s_addc_u32 s1, s9, 0
	v_readfirstlane_b32 s8, v101
	v_lshl_add_u64 v[90:91], s[0:1], 0, v[0:1]
	s_mov_b32 m0, s8
	v_lshl_add_u64 v[66:67], s[0:1], 0, v[66:67]
	v_readfirstlane_b32 s0, v102
	ds_read_b128 v[68:71], v95
	ds_read_b128 v[72:75], v95 offset:1024
	ds_read_b128 v[76:79], v95 offset:2048
	ds_read_b128 v[86:89], v95 offset:3072
	ds_read_b128 v[96:99], v93
	ds_read_b128 v[104:107], v93 offset:1024
	ds_read_b128 v[108:111], v93 offset:2048
	ds_read_b128 v[112:115], v93 offset:3072
	ds_read_b128 v[116:119], v93 offset:4096
	ds_read_b128 v[120:123], v93 offset:5120
	ds_read_b128 v[124:127], v93 offset:6144
	ds_read_b128 v[128:131], v93 offset:7168
	global_load_lds_dwordx4 v[90:91], off
	s_mov_b32 m0, s0
	s_nop 0
	global_load_lds_dwordx4 v[66:67], off
	s_barrier
	s_waitcnt lgkmcnt(0)
	s_setprio 1
	s_waitcnt lgkmcnt(0)
	v_mfma_f32_16x16x32_bf16 v[62:65], v[68:71], v[96:99], v[62:65]
	v_mfma_f32_16x16x32_bf16 v[58:61], v[76:79], v[96:99], v[58:61]
	v_mfma_f32_16x16x32_bf16 v[54:57], v[68:71], v[108:111], v[54:57]
	v_mfma_f32_16x16x32_bf16 v[50:53], v[76:79], v[108:111], v[50:53]
	v_mfma_f32_16x16x32_bf16 v[46:49], v[68:71], v[116:119], v[46:49]
	v_mfma_f32_16x16x32_bf16 v[42:45], v[76:79], v[116:119], v[42:45]
	v_mfma_f32_16x16x32_bf16 v[38:41], v[68:71], v[124:127], v[38:41]
	v_mfma_f32_16x16x32_bf16 v[34:37], v[76:79], v[124:127], v[34:37]
	v_mfma_f32_16x16x32_bf16 v[62:65], v[72:75], v[104:107], v[62:65]
	v_mfma_f32_16x16x32_bf16 v[58:61], v[86:89], v[104:107], v[58:61]
	v_mfma_f32_16x16x32_bf16 v[54:57], v[72:75], v[112:115], v[54:57]
	v_mfma_f32_16x16x32_bf16 v[50:53], v[86:89], v[112:115], v[50:53]
	v_mfma_f32_16x16x32_bf16 v[46:49], v[72:75], v[120:123], v[46:49]
	v_mfma_f32_16x16x32_bf16 v[42:45], v[86:89], v[120:123], v[42:45]
	v_mfma_f32_16x16x32_bf16 v[38:41], v[72:75], v[128:131], v[38:41]
	v_mfma_f32_16x16x32_bf16 v[34:37], v[86:89], v[128:131], v[34:37]
	s_setprio 0
	s_barrier
	s_barrier
	s_waitcnt lgkmcnt(0)
	s_barrier
	ds_read_b128 v[96:99], v93 offset:16384
	ds_read_b128 v[100:103], v93 offset:17408
	ds_read_b128 v[104:107], v93 offset:18432
	ds_read_b128 v[108:111], v93 offset:19456
	ds_read_b128 v[112:115], v93 offset:20480
	ds_read_b128 v[116:119], v93 offset:21504
	ds_read_b128 v[120:123], v93 offset:22528
	ds_read_b128 v[124:127], v93 offset:23552
	s_waitcnt vmcnt(4)
	s_barrier
	s_waitcnt lgkmcnt(0)
	s_setprio 1
	s_waitcnt lgkmcnt(3)
	v_mfma_f32_16x16x32_bf16 v[18:21], v[68:71], v[112:115], v[18:21]
	v_mfma_f32_16x16x32_bf16 v[2:5], v[68:71], v[96:99], v[2:5]
	v_mfma_f32_16x16x32_bf16 v[6:9], v[76:79], v[96:99], v[6:9]
	s_waitcnt lgkmcnt(2)
	v_mfma_f32_16x16x32_bf16 v[96:99], v[72:75], v[116:119], v[18:21]
	v_mfma_f32_16x16x32_bf16 v[18:21], v[76:79], v[112:115], v[22:25]
	v_mfma_f32_16x16x32_bf16 v[2:5], v[72:75], v[100:103], v[2:5]
	v_mfma_f32_16x16x32_bf16 v[6:9], v[86:89], v[100:103], v[6:9]
	v_mfma_f32_16x16x32_bf16 v[10:13], v[68:71], v[104:107], v[10:13]
	v_mfma_f32_16x16x32_bf16 v[14:17], v[76:79], v[104:107], v[14:17]
	v_mfma_f32_16x16x32_bf16 v[100:103], v[86:89], v[116:119], v[18:21]
	s_waitcnt lgkmcnt(1)
	v_mfma_f32_16x16x32_bf16 v[18:21], v[68:71], v[120:123], v[26:29]
	v_mfma_f32_16x16x32_bf16 v[10:13], v[72:75], v[108:111], v[10:13]
	v_mfma_f32_16x16x32_bf16 v[14:17], v[86:89], v[108:111], v[14:17]
	s_waitcnt lgkmcnt(0)
	v_mfma_f32_16x16x32_bf16 v[66:69], v[72:75], v[124:127], v[18:21]
	v_mfma_f32_16x16x32_bf16 v[18:21], v[76:79], v[120:123], v[30:33]
	v_mfma_f32_16x16x32_bf16 v[70:73], v[86:89], v[124:127], v[18:21]
	s_setprio 0
	s_barrier
	ds_read_b128 v[74:77], v95 offset:32768
	ds_read_b128 v[86:89], v95 offset:33792
	ds_read_b128 v[104:107], v95 offset:34816
	ds_read_b128 v[108:111], v95 offset:35840
	s_nop 0
	ds_read_b128 v[18:21], v93 offset:32768
	ds_read_b128 v[22:25], v93 offset:33792
	ds_read_b128 v[26:29], v93 offset:34816
	ds_read_b128 v[30:33], v93 offset:35840
	ds_read_b128 v[112:115], v93 offset:36864
	ds_read_b128 v[116:119], v93 offset:37888
	ds_read_b128 v[120:123], v93 offset:38912
	ds_read_b128 v[124:127], v93 offset:39936
	s_waitcnt vmcnt(2)
	s_barrier
	s_waitcnt lgkmcnt(0)
	s_setprio 1
	s_waitcnt lgkmcnt(7)
	v_mfma_f32_16x16x32_bf16 v[62:65], v[74:77], v[18:21], v[62:65]
	v_mfma_f32_16x16x32_bf16 v[18:21], v[104:107], v[18:21], v[58:61]
	s_waitcnt lgkmcnt(6)
	v_mfma_f32_16x16x32_bf16 v[58:61], v[108:111], v[22:25], v[18:21]
	s_waitcnt lgkmcnt(5)
	v_mfma_f32_16x16x32_bf16 v[18:21], v[74:77], v[26:29], v[54:57]
	s_waitcnt lgkmcnt(4)
	v_mfma_f32_16x16x32_bf16 v[54:57], v[86:89], v[30:33], v[18:21]
	v_mfma_f32_16x16x32_bf16 v[18:21], v[104:107], v[26:29], v[50:53]
	v_mfma_f32_16x16x32_bf16 v[50:53], v[108:111], v[30:33], v[18:21]
	s_waitcnt lgkmcnt(3)
	v_mfma_f32_16x16x32_bf16 v[18:21], v[74:77], v[112:115], v[46:49]
	s_waitcnt lgkmcnt(2)
	v_mfma_f32_16x16x32_bf16 v[46:49], v[86:89], v[116:119], v[18:21]
	v_mfma_f32_16x16x32_bf16 v[18:21], v[104:107], v[112:115], v[42:45]
	v_mfma_f32_16x16x32_bf16 v[42:45], v[108:111], v[116:119], v[18:21]
	s_waitcnt lgkmcnt(1)
	v_mfma_f32_16x16x32_bf16 v[18:21], v[74:77], v[120:123], v[38:41]
	s_waitcnt lgkmcnt(0)
	v_mfma_f32_16x16x32_bf16 v[38:41], v[86:89], v[124:127], v[18:21]
	v_mfma_f32_16x16x32_bf16 v[18:21], v[104:107], v[120:123], v[34:37]
	v_mfma_f32_16x16x32_bf16 v[62:65], v[86:89], v[22:25], v[62:65]
	v_mfma_f32_16x16x32_bf16 v[34:37], v[108:111], v[124:127], v[18:21]
	s_setprio 0
	s_barrier
	s_waitcnt vmcnt(0)
	s_barrier
	s_waitcnt lgkmcnt(0)
	s_barrier
	s_nop 1
	ds_read_b128 v[18:21], v93 offset:49152
	ds_read_b128 v[22:25], v93 offset:50176
	ds_read_b128 v[112:115], v93 offset:51200
	ds_read_b128 v[116:119], v93 offset:52224
	ds_read_b128 v[120:123], v93 offset:53248
	ds_read_b128 v[124:127], v93 offset:54272
	ds_read_b128 v[128:131], v93 offset:55296
	ds_read_b128 v[90:93], v93 offset:56320
	s_barrier
	s_waitcnt lgkmcnt(0)
	s_setprio 1
	s_waitcnt lgkmcnt(7)
	v_mfma_f32_16x16x32_bf16 v[2:5], v[74:77], v[18:21], v[2:5]
	s_waitcnt lgkmcnt(6)
	v_mfma_f32_16x16x32_bf16 v[30:33], v[86:89], v[22:25], v[2:5]
	v_mfma_f32_16x16x32_bf16 v[2:5], v[104:107], v[18:21], v[6:9]
	v_mfma_f32_16x16x32_bf16 v[26:29], v[108:111], v[22:25], v[2:5]
	s_waitcnt lgkmcnt(5)
	v_mfma_f32_16x16x32_bf16 v[2:5], v[74:77], v[112:115], v[10:13]
	s_waitcnt lgkmcnt(4)
	v_mfma_f32_16x16x32_bf16 v[22:25], v[86:89], v[116:119], v[2:5]
	v_mfma_f32_16x16x32_bf16 v[2:5], v[104:107], v[112:115], v[14:17]
	v_mfma_f32_16x16x32_bf16 v[18:21], v[108:111], v[116:119], v[2:5]
	s_waitcnt lgkmcnt(3)
	v_mfma_f32_16x16x32_bf16 v[2:5], v[74:77], v[120:123], v[96:99]
	s_waitcnt lgkmcnt(2)
	v_mfma_f32_16x16x32_bf16 v[14:17], v[86:89], v[124:127], v[2:5]
	v_mfma_f32_16x16x32_bf16 v[2:5], v[104:107], v[120:123], v[100:103]
	v_mfma_f32_16x16x32_bf16 v[10:13], v[108:111], v[124:127], v[2:5]
	s_waitcnt lgkmcnt(1)
	v_mfma_f32_16x16x32_bf16 v[2:5], v[74:77], v[128:131], v[66:69]
	s_waitcnt lgkmcnt(0)
	v_mfma_f32_16x16x32_bf16 v[6:9], v[86:89], v[90:93], v[2:5]
	v_mfma_f32_16x16x32_bf16 v[2:5], v[104:107], v[128:131], v[70:73]
	v_mfma_f32_16x16x32_bf16 v[2:5], v[108:111], v[90:93], v[2:5]
	s_setprio 0
	s_movk_i32 s0, 0x100
	v_cmp_gt_u32_e32 vcc, s0, v80
	s_barrier
	s_and_saveexec_b64 s[0:1], vcc
	s_cbranch_execz .LBB0_692
	s_barrier

.LBB0_761:
	ds_read_b128 v[164:167], v148
	ds_read_b128 v[168:171], v148 offset:1024
	ds_read_b128 v[172:175], v148 offset:2048
	ds_read_b128 v[176:179], v148 offset:3072
	v_add_u32_e32 v161, 0xc000, v145
	v_lshl_add_u64 v[204:205], v[136:137], 0, s[10:11]
	v_readfirstlane_b32 s1, v161
	v_lshl_add_u64 v[162:163], v[204:205], 0, s[34:35]
	s_mov_b32 m0, s1
	ds_read_b128 v[180:183], v147
	ds_read_b128 v[184:187], v147 offset:1024
	ds_read_b128 v[188:191], v147 offset:2048
	ds_read_b128 v[192:195], v147 offset:3072
	ds_read_b128 v[196:199], v147 offset:4096
	ds_read_b128 v[200:203], v147 offset:5120
	ds_read_b128 v[222:225], v147 offset:6144
	ds_read_b128 v[232:235], v147 offset:7168
	global_load_lds_dwordx4 v[162:163], off
	v_add_u32_e32 v162, 0xe000, v145
	v_lshl_add_u64 v[210:211], v[138:139], 0, s[10:11]
	v_readfirstlane_b32 s1, v162
	v_lshl_add_u64 v[216:217], v[210:211], 0, s[34:35]
	s_mov_b32 m0, s1
	s_nop 0
	global_load_lds_dwordx4 v[216:217], off
	s_waitcnt lgkmcnt(8)
	s_barrier
	s_waitcnt lgkmcnt(0)
	s_setprio 1
	s_waitcnt lgkmcnt(0)
	v_mfma_f32_16x16x32_bf16 v[126:129], v[164:167], v[180:183], v[126:129]
	v_mfma_f32_16x16x32_bf16 v[122:125], v[172:175], v[180:183], v[122:125]
	v_mfma_f32_16x16x32_bf16 v[118:121], v[164:167], v[188:191], v[118:121]
	v_mfma_f32_16x16x32_bf16 v[114:117], v[172:175], v[188:191], v[114:117]
	v_mfma_f32_16x16x32_bf16 v[110:113], v[164:167], v[196:199], v[110:113]
	v_mfma_f32_16x16x32_bf16 v[106:109], v[172:175], v[196:199], v[106:109]
	v_mfma_f32_16x16x32_bf16 v[102:105], v[164:167], v[222:225], v[102:105]
	v_mfma_f32_16x16x32_bf16 v[98:101], v[172:175], v[222:225], v[98:101]
	v_mfma_f32_16x16x32_bf16 v[126:129], v[168:171], v[184:187], v[126:129]
	v_mfma_f32_16x16x32_bf16 v[122:125], v[176:179], v[184:187], v[122:125]
	v_mfma_f32_16x16x32_bf16 v[118:121], v[168:171], v[192:195], v[118:121]
	v_mfma_f32_16x16x32_bf16 v[114:117], v[176:179], v[192:195], v[114:117]
	v_mfma_f32_16x16x32_bf16 v[110:113], v[168:171], v[200:203], v[110:113]
	v_mfma_f32_16x16x32_bf16 v[106:109], v[176:179], v[200:203], v[106:109]
	v_mfma_f32_16x16x32_bf16 v[102:105], v[168:171], v[232:235], v[102:105]
	v_mfma_f32_16x16x32_bf16 v[98:101], v[176:179], v[232:235], v[98:101]
	s_setprio 0
	s_barrier
	v_lshl_add_u64 v[216:217], v[132:133], 0, s[10:11]
	v_readfirstlane_b32 s1, v149
	v_lshl_add_u64 v[218:219], v[216:217], 0, s[74:75]
	s_mov_b32 m0, s1
	ds_read_b128 v[236:239], v148 offset:16384
	ds_read_b128 v[240:243], v148 offset:17408
	ds_read_b128 v[244:247], v148 offset:18432
	ds_read_b128 v[248:251], v148 offset:19456
	global_load_lds_dwordx4 v[218:219], off
	v_lshl_add_u64 v[218:219], v[134:135], 0, s[10:11]
	v_readfirstlane_b32 s1, v150
	v_lshl_add_u64 v[228:229], v[218:219], 0, s[74:75]
	s_mov_b32 m0, s1
	s_nop 0
	global_load_lds_dwordx4 v[228:229], off
	s_barrier
	s_waitcnt lgkmcnt(0)
	s_setprio 1
	s_waitcnt lgkmcnt(0)
	v_mfma_f32_16x16x32_bf16 v[94:97], v[236:239], v[180:183], v[94:97]
	v_mfma_f32_16x16x32_bf16 v[90:93], v[244:247], v[180:183], v[90:93]
	v_mfma_f32_16x16x32_bf16 v[86:89], v[236:239], v[188:191], v[86:89]
	v_mfma_f32_16x16x32_bf16 v[82:85], v[244:247], v[188:191], v[82:85]
	v_mfma_f32_16x16x32_bf16 v[78:81], v[236:239], v[196:199], v[78:81]
	v_mfma_f32_16x16x32_bf16 v[74:77], v[244:247], v[196:199], v[74:77]
	v_mfma_f32_16x16x32_bf16 v[70:73], v[236:239], v[222:225], v[70:73]
	v_mfma_f32_16x16x32_bf16 v[66:69], v[244:247], v[222:225], v[66:69]
	v_mfma_f32_16x16x32_bf16 v[94:97], v[240:243], v[184:187], v[94:97]
	v_mfma_f32_16x16x32_bf16 v[90:93], v[248:251], v[184:187], v[90:93]
	v_mfma_f32_16x16x32_bf16 v[86:89], v[240:243], v[192:195], v[86:89]
	v_mfma_f32_16x16x32_bf16 v[82:85], v[248:251], v[192:195], v[82:85]
	v_mfma_f32_16x16x32_bf16 v[78:81], v[240:243], v[200:203], v[78:81]
	v_mfma_f32_16x16x32_bf16 v[74:77], v[248:251], v[200:203], v[74:77]
	v_mfma_f32_16x16x32_bf16 v[70:73], v[240:243], v[232:235], v[70:73]
	v_mfma_f32_16x16x32_bf16 v[66:69], v[248:251], v[232:235], v[66:69]
	s_setprio 0
	v_readfirstlane_b32 s1, v145
	v_lshl_add_u64 v[228:229], v[204:205], 0, s[74:75]
	s_mov_b32 m0, s1
	v_readfirstlane_b32 s1, v146
	s_barrier
	ds_read_b128 v[180:183], v147 offset:16384
	ds_read_b128 v[184:187], v147 offset:17408
	ds_read_b128 v[188:191], v147 offset:18432
	ds_read_b128 v[192:195], v147 offset:19456
	ds_read_b128 v[196:199], v147 offset:20480
	ds_read_b128 v[200:203], v147 offset:21504
	ds_read_b128 v[222:225], v147 offset:22528
	ds_read_b128 v[232:235], v147 offset:23552
	global_load_lds_dwordx4 v[228:229], off
	v_lshl_add_u64 v[228:229], v[210:211], 0, s[74:75]
	s_mov_b32 m0, s1
	s_nop 0
	global_load_lds_dwordx4 v[228:229], off
	s_barrier
	s_waitcnt lgkmcnt(0)
	s_setprio 1
	s_waitcnt lgkmcnt(0)
	v_mfma_f32_16x16x32_bf16 v[62:65], v[164:167], v[180:183], v[62:65]
	v_mfma_f32_16x16x32_bf16 v[58:61], v[172:175], v[180:183], v[58:61]
	v_mfma_f32_16x16x32_bf16 v[54:57], v[164:167], v[188:191], v[54:57]
	v_mfma_f32_16x16x32_bf16 v[50:53], v[172:175], v[188:191], v[50:53]
	v_mfma_f32_16x16x32_bf16 v[46:49], v[164:167], v[196:199], v[46:49]
	v_mfma_f32_16x16x32_bf16 v[42:45], v[172:175], v[196:199], v[42:45]
	v_mfma_f32_16x16x32_bf16 v[38:41], v[164:167], v[222:225], v[38:41]
	v_mfma_f32_16x16x32_bf16 v[34:37], v[172:175], v[222:225], v[34:37]
	v_mfma_f32_16x16x32_bf16 v[62:65], v[168:171], v[184:187], v[62:65]
	v_mfma_f32_16x16x32_bf16 v[58:61], v[176:179], v[184:187], v[58:61]
	v_mfma_f32_16x16x32_bf16 v[54:57], v[168:171], v[192:195], v[54:57]
	v_mfma_f32_16x16x32_bf16 v[50:53], v[176:179], v[192:195], v[50:53]
	v_mfma_f32_16x16x32_bf16 v[46:49], v[168:171], v[200:203], v[46:49]
	v_mfma_f32_16x16x32_bf16 v[42:45], v[176:179], v[200:203], v[42:45]
	v_mfma_f32_16x16x32_bf16 v[38:41], v[168:171], v[232:235], v[38:41]
	v_mfma_f32_16x16x32_bf16 v[34:37], v[176:179], v[232:235], v[34:37]
	s_setprio 0
	s_barrier
	v_readfirstlane_b32 s1, v151
	v_lshl_add_u64 v[164:165], v[216:217], 0, s[78:79]
	s_mov_b32 m0, s1
	v_readfirstlane_b32 s1, v152
	global_load_lds_dwordx4 v[164:165], off
	v_lshl_add_u64 v[164:165], v[218:219], 0, s[78:79]
	s_mov_b32 m0, s1
	s_nop 0
	global_load_lds_dwordx4 v[164:165], off
	s_waitcnt vmcnt(6)
	s_barrier
	s_setprio 1
	v_mfma_f32_16x16x32_bf16 v[30:33], v[236:239], v[180:183], v[30:33]
	v_mfma_f32_16x16x32_bf16 v[26:29], v[244:247], v[180:183], v[26:29]
	v_mfma_f32_16x16x32_bf16 v[22:25], v[236:239], v[188:191], v[22:25]
	v_mfma_f32_16x16x32_bf16 v[18:21], v[244:247], v[188:191], v[18:21]
	v_mfma_f32_16x16x32_bf16 v[14:17], v[236:239], v[196:199], v[14:17]
	v_mfma_f32_16x16x32_bf16 v[10:13], v[244:247], v[196:199], v[10:13]
	v_mfma_f32_16x16x32_bf16 v[6:9], v[236:239], v[222:225], v[6:9]
	v_mfma_f32_16x16x32_bf16 v[2:5], v[244:247], v[222:225], v[2:5]
	v_mfma_f32_16x16x32_bf16 v[30:33], v[240:243], v[184:187], v[30:33]
	v_mfma_f32_16x16x32_bf16 v[26:29], v[248:251], v[184:187], v[26:29]
	v_mfma_f32_16x16x32_bf16 v[22:25], v[240:243], v[192:195], v[22:25]
	v_mfma_f32_16x16x32_bf16 v[18:21], v[248:251], v[192:195], v[18:21]
	v_mfma_f32_16x16x32_bf16 v[14:17], v[240:243], v[200:203], v[14:17]
	v_mfma_f32_16x16x32_bf16 v[10:13], v[248:251], v[200:203], v[10:13]
	v_mfma_f32_16x16x32_bf16 v[6:9], v[240:243], v[232:235], v[6:9]
	v_mfma_f32_16x16x32_bf16 v[2:5], v[248:251], v[232:235], v[2:5]
	s_setprio 0
	s_barrier
	ds_read_b128 v[164:167], v148 offset:32768
	ds_read_b128 v[168:171], v148 offset:33792
	ds_read_b128 v[172:175], v148 offset:34816
	ds_read_b128 v[176:179], v148 offset:35840
	v_readfirstlane_b32 s1, v153
	v_lshl_add_u64 v[228:229], v[204:205], 0, s[78:79]
	s_mov_b32 m0, s1
	v_readfirstlane_b32 s1, v154
	ds_read_b128 v[180:183], v147 offset:32768
	ds_read_b128 v[184:187], v147 offset:33792
	ds_read_b128 v[188:191], v147 offset:34816
	ds_read_b128 v[192:195], v147 offset:35840
	ds_read_b128 v[196:199], v147 offset:36864
	ds_read_b128 v[200:203], v147 offset:37888
	ds_read_b128 v[222:225], v147 offset:38912
	ds_read_b128 v[232:235], v147 offset:39936
	global_load_lds_dwordx4 v[228:229], off
	v_lshl_add_u64 v[228:229], v[210:211], 0, s[78:79]
	s_mov_b32 m0, s1
	s_nop 0
	global_load_lds_dwordx4 v[228:229], off
	s_waitcnt lgkmcnt(8)
	s_barrier
	s_waitcnt lgkmcnt(0)
	s_setprio 1
	s_waitcnt lgkmcnt(0)
	v_mfma_f32_16x16x32_bf16 v[126:129], v[164:167], v[180:183], v[126:129]
	v_mfma_f32_16x16x32_bf16 v[122:125], v[172:175], v[180:183], v[122:125]
	v_mfma_f32_16x16x32_bf16 v[118:121], v[164:167], v[188:191], v[118:121]
	v_mfma_f32_16x16x32_bf16 v[114:117], v[172:175], v[188:191], v[114:117]
	v_mfma_f32_16x16x32_bf16 v[110:113], v[164:167], v[196:199], v[110:113]
	v_mfma_f32_16x16x32_bf16 v[106:109], v[172:175], v[196:199], v[106:109]
	v_mfma_f32_16x16x32_bf16 v[102:105], v[164:167], v[222:225], v[102:105]
	v_mfma_f32_16x16x32_bf16 v[98:101], v[172:175], v[222:225], v[98:101]
	v_mfma_f32_16x16x32_bf16 v[126:129], v[168:171], v[184:187], v[126:129]
	v_mfma_f32_16x16x32_bf16 v[122:125], v[176:179], v[184:187], v[122:125]
	v_mfma_f32_16x16x32_bf16 v[118:121], v[168:171], v[192:195], v[118:121]
	v_mfma_f32_16x16x32_bf16 v[114:117], v[176:179], v[192:195], v[114:117]
	v_mfma_f32_16x16x32_bf16 v[110:113], v[168:171], v[200:203], v[110:113]
	v_mfma_f32_16x16x32_bf16 v[106:109], v[176:179], v[200:203], v[106:109]
	v_mfma_f32_16x16x32_bf16 v[102:105], v[168:171], v[232:235], v[102:105]
	v_mfma_f32_16x16x32_bf16 v[98:101], v[176:179], v[232:235], v[98:101]
	s_setprio 0
	s_barrier
	v_readfirstlane_b32 s1, v155
	v_lshl_add_u64 v[228:229], v[216:217], 0, s[28:29]
	s_mov_b32 m0, s1
	v_readfirstlane_b32 s1, v156
	ds_read_b128 v[236:239], v148 offset:49152
	ds_read_b128 v[240:243], v148 offset:50176
	ds_read_b128 v[244:247], v148 offset:51200
	ds_read_b128 v[248:251], v148 offset:52224
	global_load_lds_dwordx4 v[228:229], off
	v_lshl_add_u64 v[228:229], v[218:219], 0, s[28:29]
	s_mov_b32 m0, s1
	s_nop 0
	global_load_lds_dwordx4 v[228:229], off
	s_barrier
	s_waitcnt lgkmcnt(0)
	s_setprio 1
	s_waitcnt lgkmcnt(0)
	v_mfma_f32_16x16x32_bf16 v[94:97], v[236:239], v[180:183], v[94:97]
	v_mfma_f32_16x16x32_bf16 v[90:93], v[244:247], v[180:183], v[90:93]
	v_mfma_f32_16x16x32_bf16 v[86:89], v[236:239], v[188:191], v[86:89]
	v_mfma_f32_16x16x32_bf16 v[82:85], v[244:247], v[188:191], v[82:85]
	v_mfma_f32_16x16x32_bf16 v[78:81], v[236:239], v[196:199], v[78:81]
	v_mfma_f32_16x16x32_bf16 v[74:77], v[244:247], v[196:199], v[74:77]
	v_mfma_f32_16x16x32_bf16 v[70:73], v[236:239], v[222:225], v[70:73]
	v_mfma_f32_16x16x32_bf16 v[66:69], v[244:247], v[222:225], v[66:69]
	v_mfma_f32_16x16x32_bf16 v[94:97], v[240:243], v[184:187], v[94:97]
	v_mfma_f32_16x16x32_bf16 v[90:93], v[248:251], v[184:187], v[90:93]
	v_mfma_f32_16x16x32_bf16 v[86:89], v[240:243], v[192:195], v[86:89]
	v_mfma_f32_16x16x32_bf16 v[82:85], v[248:251], v[192:195], v[82:85]
	v_mfma_f32_16x16x32_bf16 v[78:81], v[240:243], v[200:203], v[78:81]
	v_mfma_f32_16x16x32_bf16 v[74:77], v[248:251], v[200:203], v[74:77]
	v_mfma_f32_16x16x32_bf16 v[70:73], v[240:243], v[232:235], v[70:73]
	v_mfma_f32_16x16x32_bf16 v[66:69], v[248:251], v[232:235], v[66:69]
	s_setprio 0
	v_readfirstlane_b32 s1, v157
	v_lshl_add_u64 v[204:205], v[204:205], 0, s[28:29]
	s_mov_b32 m0, s1
	v_readfirstlane_b32 s1, v158
	s_barrier
	ds_read_b128 v[180:183], v147 offset:49152
	ds_read_b128 v[184:187], v147 offset:50176
	ds_read_b128 v[188:191], v147 offset:51200
	ds_read_b128 v[192:195], v147 offset:52224
	ds_read_b128 v[196:199], v147 offset:53248
	ds_read_b128 v[200:203], v147 offset:54272
	ds_read_b128 v[222:225], v147 offset:55296
	ds_read_b128 v[232:235], v147 offset:56320
	global_load_lds_dwordx4 v[204:205], off
	v_lshl_add_u64 v[204:205], v[210:211], 0, s[28:29]
	s_mov_b32 m0, s1
	s_nop 0
	global_load_lds_dwordx4 v[204:205], off
	s_barrier
	s_waitcnt lgkmcnt(0)
	s_setprio 1
	s_waitcnt lgkmcnt(0)
	v_mfma_f32_16x16x32_bf16 v[62:65], v[164:167], v[180:183], v[62:65]
	v_mfma_f32_16x16x32_bf16 v[58:61], v[172:175], v[180:183], v[58:61]
	v_mfma_f32_16x16x32_bf16 v[54:57], v[164:167], v[188:191], v[54:57]
	v_mfma_f32_16x16x32_bf16 v[50:53], v[172:175], v[188:191], v[50:53]
	v_mfma_f32_16x16x32_bf16 v[46:49], v[164:167], v[196:199], v[46:49]
	v_mfma_f32_16x16x32_bf16 v[42:45], v[172:175], v[196:199], v[42:45]
	v_mfma_f32_16x16x32_bf16 v[38:41], v[164:167], v[222:225], v[38:41]
	v_mfma_f32_16x16x32_bf16 v[34:37], v[172:175], v[222:225], v[34:37]
	v_mfma_f32_16x16x32_bf16 v[62:65], v[168:171], v[184:187], v[62:65]
	v_mfma_f32_16x16x32_bf16 v[58:61], v[176:179], v[184:187], v[58:61]
	v_mfma_f32_16x16x32_bf16 v[54:57], v[168:171], v[192:195], v[54:57]
	v_mfma_f32_16x16x32_bf16 v[50:53], v[176:179], v[192:195], v[50:53]
	v_mfma_f32_16x16x32_bf16 v[46:49], v[168:171], v[200:203], v[46:49]
	v_mfma_f32_16x16x32_bf16 v[42:45], v[176:179], v[200:203], v[42:45]
	v_mfma_f32_16x16x32_bf16 v[38:41], v[168:171], v[232:235], v[38:41]
	v_mfma_f32_16x16x32_bf16 v[34:37], v[176:179], v[232:235], v[34:37]
	s_setprio 0
	s_barrier
	v_readfirstlane_b32 s1, v159
	v_lshl_add_u64 v[164:165], v[216:217], 0, s[68:69]
	s_mov_b32 m0, s1
	v_readfirstlane_b32 s1, v160
	global_load_lds_dwordx4 v[164:165], off
	v_lshl_add_u64 v[164:165], v[218:219], 0, s[68:69]
	s_mov_b32 m0, s1
	s_nop 0
	global_load_lds_dwordx4 v[164:165], off
	s_waitcnt vmcnt(6)
	s_barrier
	s_setprio 1
	v_mfma_f32_16x16x32_bf16 v[30:33], v[236:239], v[180:183], v[30:33]
	v_mfma_f32_16x16x32_bf16 v[26:29], v[244:247], v[180:183], v[26:29]
	v_mfma_f32_16x16x32_bf16 v[22:25], v[236:239], v[188:191], v[22:25]
	v_mfma_f32_16x16x32_bf16 v[18:21], v[244:247], v[188:191], v[18:21]
	v_mfma_f32_16x16x32_bf16 v[14:17], v[236:239], v[196:199], v[14:17]
	v_mfma_f32_16x16x32_bf16 v[10:13], v[244:247], v[196:199], v[10:13]
	v_mfma_f32_16x16x32_bf16 v[6:9], v[236:239], v[222:225], v[6:9]
	v_mfma_f32_16x16x32_bf16 v[2:5], v[244:247], v[222:225], v[2:5]
	v_mfma_f32_16x16x32_bf16 v[30:33], v[240:243], v[184:187], v[30:33]
	v_mfma_f32_16x16x32_bf16 v[26:29], v[248:251], v[184:187], v[26:29]
	v_mfma_f32_16x16x32_bf16 v[22:25], v[240:243], v[192:195], v[22:25]
	v_mfma_f32_16x16x32_bf16 v[18:21], v[248:251], v[192:195], v[18:21]
	v_mfma_f32_16x16x32_bf16 v[14:17], v[240:243], v[200:203], v[14:17]
	v_mfma_f32_16x16x32_bf16 v[10:13], v[248:251], v[200:203], v[10:13]
	v_mfma_f32_16x16x32_bf16 v[6:9], v[240:243], v[232:235], v[6:9]
	v_mfma_f32_16x16x32_bf16 v[2:5], v[248:251], v[232:235], v[2:5]
	s_setprio 0
	s_add_i32 s0, s0, 2
	s_add_u32 s10, s10, 0x100
	s_addc_u32 s11, s11, 0
	s_cmpk_lt_u32 s0, 0x54
	s_barrier
	s_cbranch_scc1 .LBB0_761
	s_add_u32 s0, s8, 0x162b80
	s_addc_u32 s1, s9, 0
	v_readfirstlane_b32 s8, v161
	v_lshl_add_u64 v[158:159], s[0:1], 0, v[0:1]
	s_mov_b32 m0, s8
	v_lshl_add_u64 v[130:131], s[0:1], 0, v[130:131]
	v_readfirstlane_b32 s0, v162
	ds_read_b128 v[132:135], v148
	ds_read_b128 v[136:139], v148 offset:1024
	ds_read_b128 v[150:153], v148 offset:2048
	ds_read_b128 v[154:157], v148 offset:3072
	ds_read_b128 v[164:167], v147
	ds_read_b128 v[168:171], v147 offset:1024
	ds_read_b128 v[172:175], v147 offset:2048
	ds_read_b128 v[176:179], v147 offset:3072
	ds_read_b128 v[180:183], v147 offset:4096
	ds_read_b128 v[184:187], v147 offset:5120
	ds_read_b128 v[188:191], v147 offset:6144
	ds_read_b128 v[192:195], v147 offset:7168
	global_load_lds_dwordx4 v[158:159], off
	s_mov_b32 m0, s0
	s_nop 0
	global_load_lds_dwordx4 v[130:131], off
	s_barrier
	s_waitcnt lgkmcnt(0)
	s_setprio 1
	s_waitcnt lgkmcnt(0)
	v_mfma_f32_16x16x32_bf16 v[122:125], v[150:153], v[164:167], v[122:125]
	v_mfma_f32_16x16x32_bf16 v[118:121], v[132:135], v[172:175], v[118:121]
	v_mfma_f32_16x16x32_bf16 v[114:117], v[150:153], v[172:175], v[114:117]
	v_mfma_f32_16x16x32_bf16 v[102:105], v[132:135], v[188:191], v[102:105]
	v_mfma_f32_16x16x32_bf16 v[98:101], v[150:153], v[188:191], v[98:101]
	v_mfma_f32_16x16x32_bf16 v[126:129], v[132:135], v[164:167], v[126:129]
	v_mfma_f32_16x16x32_bf16 v[122:125], v[154:157], v[168:171], v[122:125]
	v_mfma_f32_16x16x32_bf16 v[118:121], v[136:139], v[176:179], v[118:121]
	v_mfma_f32_16x16x32_bf16 v[114:117], v[154:157], v[176:179], v[114:117]
	v_mfma_f32_16x16x32_bf16 v[110:113], v[132:135], v[180:183], v[110:113]
	v_mfma_f32_16x16x32_bf16 v[106:109], v[150:153], v[180:183], v[106:109]
	v_mfma_f32_16x16x32_bf16 v[102:105], v[136:139], v[192:195], v[102:105]
	v_mfma_f32_16x16x32_bf16 v[98:101], v[154:157], v[192:195], v[98:101]
	v_mfma_f32_16x16x32_bf16 v[126:129], v[136:139], v[168:171], v[126:129]
	v_mfma_f32_16x16x32_bf16 v[158:161], v[136:139], v[184:187], v[110:113]
	v_mfma_f32_16x16x32_bf16 v[196:199], v[154:157], v[184:187], v[106:109]
	s_setprio 0
	s_barrier
	ds_read_b128 v[106:109], v148 offset:16384
	ds_read_b128 v[110:113], v148 offset:17408
	ds_read_b128 v[200:203], v148 offset:18432
	ds_read_b128 v[222:225], v148 offset:19456
	s_barrier
	s_waitcnt lgkmcnt(0)
	s_setprio 1
	s_waitcnt lgkmcnt(3)
	v_mfma_f32_16x16x32_bf16 v[86:89], v[106:109], v[172:175], v[86:89]
	s_waitcnt lgkmcnt(1)
	v_mfma_f32_16x16x32_bf16 v[82:85], v[200:203], v[172:175], v[82:85]
	v_mfma_f32_16x16x32_bf16 v[70:73], v[106:109], v[188:191], v[70:73]
	v_mfma_f32_16x16x32_bf16 v[66:69], v[200:203], v[188:191], v[66:69]
	v_mfma_f32_16x16x32_bf16 v[94:97], v[106:109], v[164:167], v[94:97]
	v_mfma_f32_16x16x32_bf16 v[90:93], v[200:203], v[164:167], v[90:93]
	v_mfma_f32_16x16x32_bf16 v[86:89], v[110:113], v[176:179], v[86:89]
	s_waitcnt lgkmcnt(0)
	v_mfma_f32_16x16x32_bf16 v[82:85], v[222:225], v[176:179], v[82:85]
	v_mfma_f32_16x16x32_bf16 v[78:81], v[106:109], v[180:183], v[78:81]
	v_mfma_f32_16x16x32_bf16 v[74:77], v[200:203], v[180:183], v[74:77]
	v_mfma_f32_16x16x32_bf16 v[70:73], v[110:113], v[192:195], v[70:73]
	v_mfma_f32_16x16x32_bf16 v[66:69], v[222:225], v[192:195], v[66:69]
	v_mfma_f32_16x16x32_bf16 v[232:235], v[110:113], v[168:171], v[94:97]
	v_mfma_f32_16x16x32_bf16 v[162:165], v[222:225], v[168:171], v[90:93]
	v_mfma_f32_16x16x32_bf16 v[166:169], v[110:113], v[184:187], v[78:81]
	v_mfma_f32_16x16x32_bf16 v[170:173], v[222:225], v[184:187], v[74:77]
	s_setprio 0
	s_barrier
	s_nop 0
	ds_read_b128 v[74:77], v147 offset:16384
	ds_read_b128 v[78:81], v147 offset:17408
	ds_read_b128 v[90:93], v147 offset:18432
	ds_read_b128 v[94:97], v147 offset:19456
	ds_read_b128 v[174:177], v147 offset:20480
	ds_read_b128 v[178:181], v147 offset:21504
	ds_read_b128 v[182:185], v147 offset:22528
	ds_read_b128 v[186:189], v147 offset:23552
	s_waitcnt vmcnt(4)
	s_barrier
	s_waitcnt lgkmcnt(0)
	s_setprio 1
	s_waitcnt lgkmcnt(7)
	v_mfma_f32_16x16x32_bf16 v[62:65], v[132:135], v[74:77], v[62:65]
	v_mfma_f32_16x16x32_bf16 v[58:61], v[150:153], v[74:77], v[58:61]
	s_waitcnt lgkmcnt(5)
	v_mfma_f32_16x16x32_bf16 v[54:57], v[132:135], v[90:93], v[54:57]
	v_mfma_f32_16x16x32_bf16 v[50:53], v[150:153], v[90:93], v[50:53]
	s_waitcnt lgkmcnt(1)
	v_mfma_f32_16x16x32_bf16 v[38:41], v[132:135], v[182:185], v[38:41]
	v_mfma_f32_16x16x32_bf16 v[34:37], v[150:153], v[182:185], v[34:37]
	v_mfma_f32_16x16x32_bf16 v[62:65], v[136:139], v[78:81], v[62:65]
	v_mfma_f32_16x16x32_bf16 v[58:61], v[154:157], v[78:81], v[58:61]
	v_mfma_f32_16x16x32_bf16 v[54:57], v[136:139], v[94:97], v[54:57]
	v_mfma_f32_16x16x32_bf16 v[50:53], v[154:157], v[94:97], v[50:53]
	v_mfma_f32_16x16x32_bf16 v[46:49], v[132:135], v[174:177], v[46:49]
	v_mfma_f32_16x16x32_bf16 v[42:45], v[150:153], v[174:177], v[42:45]
	s_waitcnt lgkmcnt(0)
	v_mfma_f32_16x16x32_bf16 v[38:41], v[136:139], v[186:189], v[38:41]
	v_mfma_f32_16x16x32_bf16 v[34:37], v[154:157], v[186:189], v[34:37]
	v_mfma_f32_16x16x32_bf16 v[190:193], v[136:139], v[178:181], v[46:49]
	v_mfma_f32_16x16x32_bf16 v[236:239], v[154:157], v[178:181], v[42:45]
	s_setprio 0
	s_setprio 1
	v_mfma_f32_16x16x32_bf16 v[22:25], v[106:109], v[90:93], v[22:25]
	v_mfma_f32_16x16x32_bf16 v[18:21], v[200:203], v[90:93], v[18:21]
	v_mfma_f32_16x16x32_bf16 v[6:9], v[106:109], v[182:185], v[6:9]
	v_mfma_f32_16x16x32_bf16 v[2:5], v[200:203], v[182:185], v[2:5]
	v_mfma_f32_16x16x32_bf16 v[30:33], v[106:109], v[74:77], v[30:33]
	v_mfma_f32_16x16x32_bf16 v[26:29], v[200:203], v[74:77], v[26:29]
	v_mfma_f32_16x16x32_bf16 v[22:25], v[110:113], v[94:97], v[22:25]
	v_mfma_f32_16x16x32_bf16 v[18:21], v[222:225], v[94:97], v[18:21]
	v_mfma_f32_16x16x32_bf16 v[14:17], v[106:109], v[174:177], v[14:17]
	v_mfma_f32_16x16x32_bf16 v[10:13], v[200:203], v[174:177], v[10:13]
	v_mfma_f32_16x16x32_bf16 v[6:9], v[110:113], v[186:189], v[6:9]
	v_mfma_f32_16x16x32_bf16 v[2:5], v[222:225], v[186:189], v[2:5]
	v_mfma_f32_16x16x32_bf16 v[134:137], v[110:113], v[78:81], v[30:33]
	v_mfma_f32_16x16x32_bf16 v[150:153], v[222:225], v[78:81], v[26:29]
	v_mfma_f32_16x16x32_bf16 v[154:157], v[110:113], v[178:181], v[14:17]
	v_mfma_f32_16x16x32_bf16 v[174:177], v[222:225], v[178:181], v[10:13]
	s_setprio 0
	s_barrier
	s_nop 0
	ds_read_b128 v[10:13], v148 offset:32768
	ds_read_b128 v[14:17], v148 offset:33792
	ds_read_b128 v[178:181], v148 offset:34816
	ds_read_b128 v[182:185], v148 offset:35840
	ds_read_b128 v[26:29], v147 offset:32768
	ds_read_b128 v[30:33], v147 offset:33792
	ds_read_b128 v[42:45], v147 offset:34816
	ds_read_b128 v[46:49], v147 offset:35840
	ds_read_b128 v[186:189], v147 offset:36864
	ds_read_b128 v[200:203], v147 offset:37888
	ds_read_b128 v[222:225], v147 offset:38912
	ds_read_b128 v[240:243], v147 offset:39936
	s_waitcnt vmcnt(2)
	s_barrier
	s_waitcnt lgkmcnt(0)
	s_setprio 1
	s_waitcnt lgkmcnt(7)
	v_mfma_f32_16x16x32_bf16 v[74:77], v[10:13], v[26:29], v[126:129]
	s_waitcnt lgkmcnt(6)
	v_mfma_f32_16x16x32_bf16 v[130:133], v[14:17], v[30:33], v[74:77]
	v_mfma_f32_16x16x32_bf16 v[74:77], v[178:181], v[26:29], v[122:125]
	v_mfma_f32_16x16x32_bf16 v[122:125], v[182:185], v[30:33], v[74:77]
	s_waitcnt lgkmcnt(5)
	v_mfma_f32_16x16x32_bf16 v[74:77], v[10:13], v[42:45], v[118:121]
	s_waitcnt lgkmcnt(4)
	v_mfma_f32_16x16x32_bf16 v[110:113], v[14:17], v[46:49], v[74:77]
	v_mfma_f32_16x16x32_bf16 v[74:77], v[178:181], v[42:45], v[114:117]
	v_mfma_f32_16x16x32_bf16 v[106:109], v[182:185], v[46:49], v[74:77]
	s_waitcnt lgkmcnt(3)
	v_mfma_f32_16x16x32_bf16 v[74:77], v[10:13], v[186:189], v[158:161]
	s_waitcnt lgkmcnt(2)
	v_mfma_f32_16x16x32_bf16 v[94:97], v[14:17], v[200:203], v[74:77]
	v_mfma_f32_16x16x32_bf16 v[74:77], v[178:181], v[186:189], v[196:199]
	v_mfma_f32_16x16x32_bf16 v[90:93], v[182:185], v[200:203], v[74:77]
	s_waitcnt lgkmcnt(1)
	v_mfma_f32_16x16x32_bf16 v[74:77], v[10:13], v[222:225], v[102:105]
	s_waitcnt lgkmcnt(0)
	v_mfma_f32_16x16x32_bf16 v[78:81], v[14:17], v[240:243], v[74:77]
	v_mfma_f32_16x16x32_bf16 v[74:77], v[178:181], v[222:225], v[98:101]
	v_mfma_f32_16x16x32_bf16 v[74:77], v[182:185], v[240:243], v[74:77]
	s_setprio 0
	s_barrier
	ds_read_b128 v[126:129], v148 offset:49152
	ds_read_b128 v[158:161], v148 offset:50176
	ds_read_b128 v[194:197], v148 offset:51200
	ds_read_b128 v[244:247], v148 offset:52224
	s_waitcnt vmcnt(0)
	s_barrier
	s_waitcnt lgkmcnt(0)
	s_setprio 1
	s_waitcnt lgkmcnt(3)
	v_mfma_f32_16x16x32_bf16 v[98:101], v[126:129], v[26:29], v[232:235]
	s_waitcnt lgkmcnt(1)
	v_mfma_f32_16x16x32_bf16 v[26:29], v[194:197], v[26:29], v[162:165]
	s_waitcnt lgkmcnt(0)
	v_mfma_f32_16x16x32_bf16 v[114:117], v[244:247], v[30:33], v[26:29]
	v_mfma_f32_16x16x32_bf16 v[26:29], v[126:129], v[42:45], v[86:89]
	v_mfma_f32_16x16x32_bf16 v[102:105], v[158:161], v[46:49], v[26:29]
	v_mfma_f32_16x16x32_bf16 v[26:29], v[194:197], v[42:45], v[82:85]
	v_mfma_f32_16x16x32_bf16 v[118:121], v[158:161], v[30:33], v[98:101]
	v_mfma_f32_16x16x32_bf16 v[98:101], v[244:247], v[46:49], v[26:29]
	v_mfma_f32_16x16x32_bf16 v[26:29], v[126:129], v[186:189], v[166:169]
	v_mfma_f32_16x16x32_bf16 v[86:89], v[158:161], v[200:203], v[26:29]
	v_mfma_f32_16x16x32_bf16 v[26:29], v[194:197], v[186:189], v[170:173]
	v_mfma_f32_16x16x32_bf16 v[82:85], v[244:247], v[200:203], v[26:29]
	v_mfma_f32_16x16x32_bf16 v[26:29], v[126:129], v[222:225], v[70:73]
	v_mfma_f32_16x16x32_bf16 v[70:73], v[158:161], v[240:243], v[26:29]
	v_mfma_f32_16x16x32_bf16 v[26:29], v[194:197], v[222:225], v[66:69]
	v_mfma_f32_16x16x32_bf16 v[66:69], v[244:247], v[240:243], v[26:29]
	s_setprio 0
	s_barrier
	ds_read_b128 v[162:165], v147 offset:49152
	ds_read_b128 v[166:169], v147 offset:50176
	ds_read_b128 v[170:173], v147 offset:51200
	ds_read_b128 v[186:189], v147 offset:52224
	ds_read_b128 v[198:201], v147 offset:53248
	ds_read_b128 v[202:205], v147 offset:54272
	ds_read_b128 v[222:225], v147 offset:55296
	ds_read_b128 v[146:149], v147 offset:56320
	s_barrier
	s_waitcnt lgkmcnt(0)
	s_setprio 1
	s_waitcnt lgkmcnt(7)
	v_mfma_f32_16x16x32_bf16 v[26:29], v[10:13], v[162:165], v[62:65]
	s_waitcnt lgkmcnt(6)
	v_mfma_f32_16x16x32_bf16 v[62:65], v[14:17], v[166:169], v[26:29]
	v_mfma_f32_16x16x32_bf16 v[26:29], v[178:181], v[162:165], v[58:61]
	v_mfma_f32_16x16x32_bf16 v[58:61], v[182:185], v[166:169], v[26:29]
	s_waitcnt lgkmcnt(5)
	v_mfma_f32_16x16x32_bf16 v[26:29], v[10:13], v[170:173], v[54:57]
	s_waitcnt lgkmcnt(4)
	v_mfma_f32_16x16x32_bf16 v[46:49], v[14:17], v[186:189], v[26:29]
	v_mfma_f32_16x16x32_bf16 v[26:29], v[178:181], v[170:173], v[50:53]
	v_mfma_f32_16x16x32_bf16 v[42:45], v[182:185], v[186:189], v[26:29]
	s_waitcnt lgkmcnt(3)
	v_mfma_f32_16x16x32_bf16 v[26:29], v[10:13], v[198:201], v[190:193]
	s_waitcnt lgkmcnt(1)
	v_mfma_f32_16x16x32_bf16 v[10:13], v[10:13], v[222:225], v[38:41]
	v_mfma_f32_16x16x32_bf16 v[30:33], v[14:17], v[202:205], v[26:29]
	v_mfma_f32_16x16x32_bf16 v[26:29], v[178:181], v[198:201], v[236:239]
	s_waitcnt lgkmcnt(0)
	v_mfma_f32_16x16x32_bf16 v[14:17], v[14:17], v[146:149], v[10:13]
	v_mfma_f32_16x16x32_bf16 v[10:13], v[178:181], v[222:225], v[34:37]
	v_mfma_f32_16x16x32_bf16 v[26:29], v[182:185], v[202:205], v[26:29]
	v_mfma_f32_16x16x32_bf16 v[10:13], v[182:185], v[146:149], v[10:13]
	s_setprio 0
	s_setprio 1
	v_mfma_f32_16x16x32_bf16 v[34:37], v[126:129], v[162:165], v[134:137]
	v_mfma_f32_16x16x32_bf16 v[54:57], v[158:161], v[166:169], v[34:37]
	v_mfma_f32_16x16x32_bf16 v[34:37], v[194:197], v[162:165], v[150:153]
	v_mfma_f32_16x16x32_bf16 v[18:21], v[194:197], v[170:173], v[18:21]
	v_mfma_f32_16x16x32_bf16 v[50:53], v[244:247], v[166:169], v[34:37]
	v_mfma_f32_16x16x32_bf16 v[22:25], v[126:129], v[170:173], v[22:25]
	v_mfma_f32_16x16x32_bf16 v[34:37], v[244:247], v[186:189], v[18:21]
	v_mfma_f32_16x16x32_bf16 v[18:21], v[126:129], v[198:201], v[154:157]
	v_mfma_f32_16x16x32_bf16 v[38:41], v[158:161], v[186:189], v[22:25]
	v_mfma_f32_16x16x32_bf16 v[22:25], v[158:161], v[202:205], v[18:21]
	v_mfma_f32_16x16x32_bf16 v[18:21], v[194:197], v[198:201], v[174:177]
	v_mfma_f32_16x16x32_bf16 v[6:9], v[126:129], v[222:225], v[6:9]
	v_mfma_f32_16x16x32_bf16 v[2:5], v[194:197], v[222:225], v[2:5]
	v_mfma_f32_16x16x32_bf16 v[18:21], v[244:247], v[202:205], v[18:21]
	v_mfma_f32_16x16x32_bf16 v[6:9], v[158:161], v[146:149], v[6:9]
	v_mfma_f32_16x16x32_bf16 v[2:5], v[244:247], v[146:149], v[2:5]
	s_setprio 0
	s_movk_i32 s0, 0x100
	v_cmp_gt_u32_e32 vcc, s0, v140
	s_barrier
	s_and_saveexec_b64 s[0:1], vcc
	s_cbranch_execz .LBB0_764
	s_barrier

	.amdhsa_kernel _Z11mega_kernel6Params
		.amdhsa_group_segment_fixed_size 134400
		.amdhsa_private_segment_fixed_size 0
		.amdhsa_kernarg_size 824
		.amdhsa_user_sgpr_count 2
		.amdhsa_user_sgpr_dispatch_ptr 0
		.amdhsa_user_sgpr_queue_ptr 0
		.amdhsa_user_sgpr_kernarg_segment_ptr 1
		.amdhsa_user_sgpr_dispatch_id 0
		.amdhsa_user_sgpr_kernarg_preload_length 0
		.amdhsa_user_sgpr_kernarg_preload_offset 0
		.amdhsa_user_sgpr_private_segment_size 0
		.amdhsa_uses_dynamic_stack 0
		.amdhsa_enable_private_segment 0
		.amdhsa_system_sgpr_workgroup_id_x 1
		.amdhsa_system_sgpr_workgroup_id_y 0
		.amdhsa_system_sgpr_workgroup_id_z 0
		.amdhsa_system_sgpr_workgroup_info 0
		.amdhsa_system_vgpr_workitem_id 2
		.amdhsa_next_free_vgpr 256
		.amdhsa_next_free_sgpr 100
		.amdhsa_accum_offset 256
		.amdhsa_reserve_vcc 1
		.amdhsa_float_round_mode_32 0
		.amdhsa_float_round_mode_16_64 0
		.amdhsa_float_denorm_mode_32 3
		.amdhsa_float_denorm_mode_16_64 3
		.amdhsa_dx10_clamp 1
		.amdhsa_ieee_mode 1
		.amdhsa_fp16_overflow 0
		.amdhsa_tg_split 0
		.amdhsa_exception_fp_ieee_invalid_op 0
		.amdhsa_exception_fp_denorm_src 0
		.amdhsa_exception_fp_ieee_div_zero 0
		.amdhsa_exception_fp_ieee_overflow 0
		.amdhsa_exception_fp_ieee_underflow 0
		.amdhsa_exception_fp_ieee_inexact 0
		.amdhsa_exception_int_div_zero 0
	.end_amdhsa_kernel

amdhsa.kernels:
  - .agpr_count:     0
    .args:
      - .offset:         0
        .size:           568
        .value_kind:     by_value
      - .offset:         568
        .size:           4
        .value_kind:     hidden_block_count_x
      - .offset:         572
        .size:           4
        .value_kind:     hidden_block_count_y
      - .offset:         576
        .size:           4
        .value_kind:     hidden_block_count_z
      - .offset:         580
        .size:           2
        .value_kind:     hidden_group_size_x
      - .offset:         582
        .size:           2
        .value_kind:     hidden_group_size_y
      - .offset:         584
        .size:           2
        .value_kind:     hidden_group_size_z
      - .offset:         586
        .size:           2
        .value_kind:     hidden_remainder_x
      - .offset:         588
        .size:           2
        .value_kind:     hidden_remainder_y
      - .offset:         590
        .size:           2
        .value_kind:     hidden_remainder_z
      - .offset:         608
        .size:           8
        .value_kind:     hidden_global_offset_x
      - .offset:         616
        .size:           8
        .value_kind:     hidden_global_offset_y
      - .offset:         624
        .size:           8
        .value_kind:     hidden_global_offset_z
      - .offset:         632
        .size:           2
        .value_kind:     hidden_grid_dims
      - .offset:         656
        .size:           8
        .value_kind:     hidden_multigrid_sync_arg
    .group_segment_fixed_size: 134400
    .kernarg_segment_align: 8
    .kernarg_segment_size: 824
    .language:       OpenCL C
    .language_version:
      - 2
      - 0
    .max_flat_workgroup_size: 512
    .name:           _Z11mega_kernel6Params
    .private_segment_fixed_size: 0
    .sgpr_count:     106
    .sgpr_spill_count: 240
    .symbol:         _Z11mega_kernel6Params.kd
    .uniform_work_group_size: 1
    .uses_dynamic_stack: false
    .vgpr_count:     256
    .vgpr_spill_count: 0
    .wavefront_size: 64
